# GEMM K-loops: inner s_setprio 0/1 pair in the middle of each 32-MFMA block removed (block-level raise kept)
# speedup vs baseline: 1.0003x; 1.0003x over previous
; #define PG8_STAGE(bufoff, gbase, voff) do { _Pragma("unroll") for (int _i = 0; _i < 2; ++_i) \
;         __builtin_amdgcn_global_load_lds((const unsigned*)((const char*)(gbase) + (voff)[_i]), (PG8_LAS unsigned*)(lds + (bufoff) + ldsw + _i * 8192), 16, 0, 0); } while (0)
; #define PG8_LDA(dst, b, h) do { _Pragma("unroll") for (int m = 0; m < 4; ++m) _Pragma("unroll") for (int k = 0; k < 2; ++k) dst[m][k] = *(const PG8_LAS bf16x8*)(lds + PG8_SA(b, h) + aoff + m * 2048 + k * 1024); } while (0)
; #define PG8_LDB(dst, b, h) do { _Pragma("unroll") for (int n = 0; n < 2; ++n) _Pragma("unroll") for (int k = 0; k < 2; ++k) dst[n][k] = *(const PG8_LAS bf16x8*)(lds + PG8_SB(b, h) + boff + n * 2048 + k * 1024); } while (0)
; #define PG8_MMA(ai, bj, At, Bt) do { __builtin_amdgcn_s_setprio(1); _Pragma("unroll") for (int m = 0; m < 4; ++m) _Pragma("unroll") for (int n = 0; n < 2; ++n) _Pragma("unroll") for (int k = 0; k < 2; ++k) \
;         acc[ai][bj][m][n] = __builtin_amdgcn_mfma_f32_16x16x32_bf16(Bt[n][k], At[m][k], acc[ai][bj][m][n], 0, 0, 0); __builtin_amdgcn_s_setprio(0); } while (0)
; #define PG8_WAIT_V(n) asm volatile("s_waitcnt vmcnt(" #n ")" ::: "memory")
; #define PG8_WAIT_L(n) asm volatile("s_waitcnt lgkmcnt(" #n ")" ::: "memory")
; #define PG8_BAR __builtin_amdgcn_s_barrier()
; #define PG8_SCHED __builtin_amdgcn_sched_barrier(0)
; template <class Epi, class Sched, bool ALIGN_EPI = false, bool SP2 = false, bool HALFM = false>
; __device__ __forceinline__ void gemm_phase(PG8_LAS unsigned char* lds, const Gemm g, const Sched& S, const Epi& E) {
;     ...
;             PG8_LDB(B0, 0, 0); PG8_LDB(B1, 0, 1); PG8_SCHED; PG8_LDA(At, 0, 0); PG8_STAGE(PG8_SA(1, 1), a1 + hstep, voffA);
;             PG8_WAIT_V(8); PG8_WAIT_L(0); PG8_BAR; PG8_MMA(0, 0, At, B0); PG8_MMA(0, 1, At, B1); PG8_BAR; PG8_SCHED;
;             PG8_LDA(At, 0, 1); PG8_STAGE(PG8_SB(0, 0), b2, voffB); PG8_STAGE(PG8_SB(0, 1), b2 + hstep, voffB); PG8_STAGE(PG8_SA(0, 0), a2, voffA);
;             PG8_WAIT_V(8); PG8_WAIT_L(0); PG8_BAR; if constexpr (!HALFM) { PG8_MMA(1, 0, At, B0); PG8_MMA(1, 1, At, B1); } PG8_BAR; PG8_SCHED;
.LBB0_496:
	ds_read_b128 v[154:157], v150
	ds_read_b128 v[158:161], v150 offset:1024
	ds_read_b128 v[162:165], v150 offset:2048
	ds_read_b128 v[166:169], v150 offset:3072
	ds_read_b128 v[170:173], v151
	ds_read_b128 v[174:177], v151 offset:1024
	ds_read_b128 v[178:181], v151 offset:2048
	ds_read_b128 v[182:185], v151 offset:3072
	s_add_u32 s24, s22, 0xfffc0080
	s_addc_u32 s25, s23, -1
	s_cmp_eq_u32 s45, 12
	s_cselect_b32 s27, s15, s25
	s_cselect_b32 s26, s41, s24
	s_cselect_b32 s25, s13, s44
	s_cselect_b32 s24, s42, s43
	v_lshl_add_u64 v[146:147], s[22:23], 0, v[138:139]
	s_add_i32 m0, s2, 0xc000
	ds_read_b128 v[186:189], v152
	ds_read_b128 v[190:193], v152 offset:1024
	ds_read_b128 v[194:197], v152 offset:2048
	ds_read_b128 v[198:201], v152 offset:3072
	ds_read_b128 v[202:205], v152 offset:4096
	ds_read_b128 v[206:209], v152 offset:5120
	ds_read_b128 v[210:213], v152 offset:6144
	ds_read_b128 v[214:217], v152 offset:7168
	global_load_lds_dwordx4 v[146:147], off
	v_lshl_add_u64 v[146:147], s[22:23], 0, v[140:141]
	s_add_i32 m0, s2, 0xe000
	s_nop 0
	global_load_lds_dwordx4 v[146:147], off
	s_mov_b32 m0, s30
	v_lshl_add_u64 v[146:147], v[220:221], 0, s[8:9]
	global_load_lds_dwordx4 v[146:147], off
	s_mov_b32 m0, s31
	v_lshl_add_u64 v[146:147], v[222:223], 0, s[8:9]
	global_load_lds_dwordx4 v[146:147], off
	s_waitcnt vmcnt(10)
	s_waitcnt lgkmcnt(0)
	s_barrier
	s_setprio 1
	s_waitcnt lgkmcnt(0)
	v_mfma_f32_16x16x32_bf16 v[126:129], v[154:157], v[186:189], v[126:129]
	v_mfma_f32_16x16x32_bf16 v[122:125], v[162:165], v[186:189], v[122:125]
	v_mfma_f32_16x16x32_bf16 v[110:113], v[154:157], v[194:197], v[110:113]
	v_mfma_f32_16x16x32_bf16 v[106:109], v[162:165], v[194:197], v[106:109]
	v_mfma_f32_16x16x32_bf16 v[94:97], v[154:157], v[202:205], v[94:97]
	v_mfma_f32_16x16x32_bf16 v[90:93], v[162:165], v[202:205], v[90:93]
	v_mfma_f32_16x16x32_bf16 v[78:81], v[154:157], v[210:213], v[78:81]
	v_mfma_f32_16x16x32_bf16 v[74:77], v[162:165], v[210:213], v[74:77]
	v_mfma_f32_16x16x32_bf16 v[126:129], v[158:161], v[190:193], v[126:129]
	v_mfma_f32_16x16x32_bf16 v[122:125], v[166:169], v[190:193], v[122:125]
	v_mfma_f32_16x16x32_bf16 v[110:113], v[158:161], v[198:201], v[110:113]
	v_mfma_f32_16x16x32_bf16 v[106:109], v[166:169], v[198:201], v[106:109]
	v_mfma_f32_16x16x32_bf16 v[94:97], v[158:161], v[206:209], v[94:97]
	v_mfma_f32_16x16x32_bf16 v[90:93], v[166:169], v[206:209], v[90:93]
	v_mfma_f32_16x16x32_bf16 v[78:81], v[158:161], v[214:217], v[78:81]
	v_mfma_f32_16x16x32_bf16 v[74:77], v[166:169], v[214:217], v[74:77]
	v_mfma_f32_16x16x32_bf16 v[118:121], v[170:173], v[186:189], v[118:121]
	v_mfma_f32_16x16x32_bf16 v[114:117], v[178:181], v[186:189], v[114:117]
	v_mfma_f32_16x16x32_bf16 v[102:105], v[170:173], v[194:197], v[102:105]
	v_mfma_f32_16x16x32_bf16 v[98:101], v[178:181], v[194:197], v[98:101]
	v_mfma_f32_16x16x32_bf16 v[86:89], v[170:173], v[202:205], v[86:89]
	v_mfma_f32_16x16x32_bf16 v[82:85], v[178:181], v[202:205], v[82:85]
	v_mfma_f32_16x16x32_bf16 v[70:73], v[170:173], v[210:213], v[70:73]
	v_mfma_f32_16x16x32_bf16 v[66:69], v[178:181], v[210:213], v[66:69]
	v_mfma_f32_16x16x32_bf16 v[118:121], v[174:177], v[190:193], v[118:121]
	v_mfma_f32_16x16x32_bf16 v[114:117], v[182:185], v[190:193], v[114:117]
	v_mfma_f32_16x16x32_bf16 v[102:105], v[174:177], v[198:201], v[102:105]
	v_mfma_f32_16x16x32_bf16 v[98:101], v[182:185], v[198:201], v[98:101]
	v_mfma_f32_16x16x32_bf16 v[86:89], v[174:177], v[206:209], v[86:89]
	v_mfma_f32_16x16x32_bf16 v[82:85], v[182:185], v[206:209], v[82:85]
	v_mfma_f32_16x16x32_bf16 v[70:73], v[174:177], v[214:217], v[70:73]
	v_mfma_f32_16x16x32_bf16 v[66:69], v[182:185], v[214:217], v[66:69]
	s_setprio 0
	s_barrier
	s_add_i32 s46, s37, s0
	v_lshl_add_u64 v[146:147], s[24:25], 0, v[134:135]
	s_mov_b32 m0, s46
	ds_read_b128 v[186:189], v152 offset:16384
	ds_read_b128 v[190:193], v152 offset:17408
	ds_read_b128 v[194:197], v152 offset:18432
	ds_read_b128 v[198:201], v152 offset:19456
	ds_read_b128 v[202:205], v152 offset:20480
	ds_read_b128 v[206:209], v152 offset:21504
	ds_read_b128 v[210:213], v152 offset:22528
	ds_read_b128 v[214:217], v152 offset:23552
	global_load_lds_dwordx4 v[146:147], off
	s_add_i32 m0, s46, 0x2000
	s_add_u32 s46, s24, 0x40000
	v_lshl_add_u64 v[218:219], s[24:25], 0, v[130:131]
	s_addc_u32 s47, s25, 0
	s_add_i32 s48, s38, s0
	global_load_lds_dwordx4 v[218:219], off
	v_lshl_add_u64 v[220:221], s[46:47], 0, v[134:135]
	s_mov_b32 m0, s48
	v_lshl_add_u64 v[222:223], s[26:27], 0, v[132:133]
	global_load_lds_dwordx4 v[220:221], off
	v_lshl_add_u64 v[220:221], s[46:47], 0, v[130:131]
	s_add_i32 m0, s48, 0x2000
	s_nop 0
	global_load_lds_dwordx4 v[220:221], off
	v_lshl_add_u64 v[220:221], s[26:27], 0, v[136:137]
	s_waitcnt vmcnt(4)
	s_waitcnt lgkmcnt(0)
	s_barrier
; #define PG8_STAGE(bufoff, gbase, voff) do { _Pragma("unroll") for (int _i = 0; _i < 2; ++_i) \
;         __builtin_amdgcn_global_load_lds((const unsigned*)((const char*)(gbase) + (voff)[_i]), (PG8_LAS unsigned*)(lds + (bufoff) + ldsw + _i * 8192), 16, 0, 0); } while (0)
; #define PG8_LDA(dst, b, h) do { _Pragma("unroll") for (int m = 0; m < 4; ++m) _Pragma("unroll") for (int k = 0; k < 2; ++k) dst[m][k] = *(const PG8_LAS bf16x8*)(lds + PG8_SA(b, h) + aoff + m * 2048 + k * 1024); } while (0)
; #define PG8_LDB(dst, b, h) do { _Pragma("unroll") for (int n = 0; n < 2; ++n) _Pragma("unroll") for (int k = 0; k < 2; ++k) dst[n][k] = *(const PG8_LAS bf16x8*)(lds + PG8_SB(b, h) + boff + n * 2048 + k * 1024); } while (0)
; #define PG8_MMA(ai, bj, At, Bt) do { __builtin_amdgcn_s_setprio(1); _Pragma("unroll") for (int m = 0; m < 4; ++m) _Pragma("unroll") for (int n = 0; n < 2; ++n) _Pragma("unroll") for (int k = 0; k < 2; ++k) \
;         acc[ai][bj][m][n] = __builtin_amdgcn_mfma_f32_16x16x32_bf16(Bt[n][k], At[m][k], acc[ai][bj][m][n], 0, 0, 0); __builtin_amdgcn_s_setprio(0); } while (0)
; #define PG8_WAIT_V(n) asm volatile("s_waitcnt vmcnt(" #n ")" ::: "memory")
; #define PG8_WAIT_L(n) asm volatile("s_waitcnt lgkmcnt(" #n ")" ::: "memory")
; #define PG8_BAR __builtin_amdgcn_s_barrier()
; #define PG8_SCHED __builtin_amdgcn_sched_barrier(0)
; template <class Epi, class Sched, bool ALIGN_EPI = false, bool SP2 = false, bool HALFM = false>
; __device__ __forceinline__ void gemm_phase(PG8_LAS unsigned char* lds, const Gemm g, const Sched& S, const Epi& E) {
;     ...
;             PG8_WAIT_V(8); PG8_WAIT_L(0); PG8_BAR; if constexpr (!HALFM) { PG8_MMA(1, 0, At, B0); PG8_MMA(1, 1, At, B1); } PG8_BAR; PG8_SCHED;
;             PG8_LDB(B0, 1, 0); PG8_LDB(B1, 1, 1); PG8_SCHED; PG8_LDA(At, 1, 0); PG8_STAGE(PG8_SA(0, 1), a2 + hstep, voffA);
;             PG8_WAIT_V(8); PG8_WAIT_L(0); PG8_BAR; PG8_MMA(0, 0, At, B0); PG8_MMA(0, 1, At, B1); PG8_BAR; PG8_SCHED;
	s_setprio 1
	s_waitcnt lgkmcnt(0)
	v_mfma_f32_16x16x32_bf16 v[62:65], v[154:157], v[186:189], v[62:65]
	v_mfma_f32_16x16x32_bf16 v[58:61], v[162:165], v[186:189], v[58:61]
	v_mfma_f32_16x16x32_bf16 v[46:49], v[154:157], v[194:197], v[46:49]
	v_mfma_f32_16x16x32_bf16 v[42:45], v[162:165], v[194:197], v[42:45]
	v_mfma_f32_16x16x32_bf16 v[30:33], v[154:157], v[202:205], v[30:33]
	v_mfma_f32_16x16x32_bf16 v[26:29], v[162:165], v[202:205], v[26:29]
	v_mfma_f32_16x16x32_bf16 v[14:17], v[154:157], v[210:213], v[14:17]
	v_mfma_f32_16x16x32_bf16 v[10:13], v[162:165], v[210:213], v[10:13]
	v_mfma_f32_16x16x32_bf16 v[62:65], v[158:161], v[190:193], v[62:65]
	v_mfma_f32_16x16x32_bf16 v[58:61], v[166:169], v[190:193], v[58:61]
	v_mfma_f32_16x16x32_bf16 v[46:49], v[158:161], v[198:201], v[46:49]
	v_mfma_f32_16x16x32_bf16 v[42:45], v[166:169], v[198:201], v[42:45]
	v_mfma_f32_16x16x32_bf16 v[30:33], v[158:161], v[206:209], v[30:33]
	v_mfma_f32_16x16x32_bf16 v[26:29], v[166:169], v[206:209], v[26:29]
	v_mfma_f32_16x16x32_bf16 v[14:17], v[158:161], v[214:217], v[14:17]
	v_mfma_f32_16x16x32_bf16 v[10:13], v[166:169], v[214:217], v[10:13]
	v_mfma_f32_16x16x32_bf16 v[54:57], v[170:173], v[186:189], v[54:57]
	v_mfma_f32_16x16x32_bf16 v[50:53], v[178:181], v[186:189], v[50:53]
	v_mfma_f32_16x16x32_bf16 v[38:41], v[170:173], v[194:197], v[38:41]
	v_mfma_f32_16x16x32_bf16 v[34:37], v[178:181], v[194:197], v[34:37]
	v_mfma_f32_16x16x32_bf16 v[22:25], v[170:173], v[202:205], v[22:25]
	v_mfma_f32_16x16x32_bf16 v[18:21], v[178:181], v[202:205], v[18:21]
	v_mfma_f32_16x16x32_bf16 v[6:9], v[170:173], v[210:213], v[6:9]
	v_mfma_f32_16x16x32_bf16 v[2:5], v[178:181], v[210:213], v[2:5]
	v_mfma_f32_16x16x32_bf16 v[54:57], v[174:177], v[190:193], v[54:57]
	v_mfma_f32_16x16x32_bf16 v[50:53], v[182:185], v[190:193], v[50:53]
	v_mfma_f32_16x16x32_bf16 v[38:41], v[174:177], v[198:201], v[38:41]
	v_mfma_f32_16x16x32_bf16 v[34:37], v[182:185], v[198:201], v[34:37]
	v_mfma_f32_16x16x32_bf16 v[22:25], v[174:177], v[206:209], v[22:25]
	v_mfma_f32_16x16x32_bf16 v[18:21], v[182:185], v[206:209], v[18:21]
	v_mfma_f32_16x16x32_bf16 v[6:9], v[174:177], v[214:217], v[6:9]
	v_mfma_f32_16x16x32_bf16 v[2:5], v[182:185], v[214:217], v[2:5]
	s_setprio 0
	s_barrier
	s_add_i32 s46, 0, 0x18000
	v_add_u32_e32 v153, s46, v148
	s_add_i32 s47, 0, 0x1c000
	ds_read_b128 v[154:157], v153
	ds_read_b128 v[158:161], v153 offset:1024
	ds_read_b128 v[162:165], v153 offset:2048
	ds_read_b128 v[166:169], v153 offset:3072
	v_add_u32_e32 v153, s47, v148
	ds_read_b128 v[170:173], v153
	ds_read_b128 v[174:177], v153 offset:1024
	ds_read_b128 v[178:181], v153 offset:2048
	ds_read_b128 v[182:185], v153 offset:3072
	s_add_u32 s26, s26, 0x40000
	s_addc_u32 s27, s27, 0
	s_mov_b32 m0, s21
	v_lshl_add_u64 v[224:225], s[26:27], 0, v[136:137]
	ds_read_b128 v[186:189], v152 offset:32768
	ds_read_b128 v[190:193], v152 offset:33792
	ds_read_b128 v[194:197], v152 offset:34816
	ds_read_b128 v[198:201], v152 offset:35840
	ds_read_b128 v[202:205], v152 offset:36864
	ds_read_b128 v[206:209], v152 offset:37888
	ds_read_b128 v[210:213], v152 offset:38912
	ds_read_b128 v[214:217], v152 offset:39936
	global_load_lds_dwordx4 v[224:225], off
	v_lshl_add_u64 v[224:225], s[26:27], 0, v[132:133]
	s_mov_b32 m0, s28
	s_nop 0
	global_load_lds_dwordx4 v[224:225], off
	s_mov_b32 m0, s2
	s_nop 0
	global_load_lds_dwordx4 v[220:221], off
	s_mov_b32 m0, s3
	s_nop 0
	global_load_lds_dwordx4 v[222:223], off
	s_waitcnt vmcnt(10)
	s_waitcnt lgkmcnt(0)
	s_barrier
; #define PG8_STAGE(bufoff, gbase, voff) do { _Pragma("unroll") for (int _i = 0; _i < 2; ++_i) \
;         __builtin_amdgcn_global_load_lds((const unsigned*)((const char*)(gbase) + (voff)[_i]), (PG8_LAS unsigned*)(lds + (bufoff) + ldsw + _i * 8192), 16, 0, 0); } while (0)
; #define PG8_LDA(dst, b, h) do { _Pragma("unroll") for (int m = 0; m < 4; ++m) _Pragma("unroll") for (int k = 0; k < 2; ++k) dst[m][k] = *(const PG8_LAS bf16x8*)(lds + PG8_SA(b, h) + aoff + m * 2048 + k * 1024); } while (0)
; #define PG8_MMA(ai, bj, At, Bt) do { __builtin_amdgcn_s_setprio(1); _Pragma("unroll") for (int m = 0; m < 4; ++m) _Pragma("unroll") for (int n = 0; n < 2; ++n) _Pragma("unroll") for (int k = 0; k < 2; ++k) \
;         acc[ai][bj][m][n] = __builtin_amdgcn_mfma_f32_16x16x32_bf16(Bt[n][k], At[m][k], acc[ai][bj][m][n], 0, 0, 0); __builtin_amdgcn_s_setprio(0); } while (0)
; #define PG8_WAIT_V(n) asm volatile("s_waitcnt vmcnt(" #n ")" ::: "memory")
; #define PG8_WAIT_L(n) asm volatile("s_waitcnt lgkmcnt(" #n ")" ::: "memory")
; #define PG8_BAR __builtin_amdgcn_s_barrier()
; #define PG8_SCHED __builtin_amdgcn_sched_barrier(0)
; template <class Epi, class Sched, bool ALIGN_EPI = false, bool SP2 = false, bool HALFM = false>
; __device__ __forceinline__ void gemm_phase(PG8_LAS unsigned char* lds, const Gemm g, const Sched& S, const Epi& E) {
;     ...
;             PG8_WAIT_V(8); PG8_WAIT_L(0); PG8_BAR; PG8_MMA(0, 0, At, B0); PG8_MMA(0, 1, At, B1); PG8_BAR; PG8_SCHED;
;             PG8_LDA(At, 1, 1); PG8_STAGE(PG8_SB(1, 0), b3, voffB); PG8_STAGE(PG8_SB(1, 1), b3 + hstep, voffB); PG8_STAGE(PG8_SA(1, 0), a3, voffA);
;             PG8_WAIT_V(8); PG8_WAIT_L(0); PG8_BAR; if constexpr (!HALFM) { PG8_MMA(1, 0, At, B0); PG8_MMA(1, 1, At, B1); } PG8_BAR; PG8_SCHED;
	s_setprio 1
	s_waitcnt lgkmcnt(0)
	v_mfma_f32_16x16x32_bf16 v[126:129], v[154:157], v[186:189], v[126:129]
	v_mfma_f32_16x16x32_bf16 v[122:125], v[162:165], v[186:189], v[122:125]
	v_mfma_f32_16x16x32_bf16 v[110:113], v[154:157], v[194:197], v[110:113]
	v_mfma_f32_16x16x32_bf16 v[106:109], v[162:165], v[194:197], v[106:109]
	v_mfma_f32_16x16x32_bf16 v[94:97], v[154:157], v[202:205], v[94:97]
	v_mfma_f32_16x16x32_bf16 v[90:93], v[162:165], v[202:205], v[90:93]
	v_mfma_f32_16x16x32_bf16 v[78:81], v[154:157], v[210:213], v[78:81]
	v_mfma_f32_16x16x32_bf16 v[74:77], v[162:165], v[210:213], v[74:77]
	v_mfma_f32_16x16x32_bf16 v[126:129], v[158:161], v[190:193], v[126:129]
	v_mfma_f32_16x16x32_bf16 v[122:125], v[166:169], v[190:193], v[122:125]
	v_mfma_f32_16x16x32_bf16 v[110:113], v[158:161], v[198:201], v[110:113]
	v_mfma_f32_16x16x32_bf16 v[106:109], v[166:169], v[198:201], v[106:109]
	v_mfma_f32_16x16x32_bf16 v[94:97], v[158:161], v[206:209], v[94:97]
	v_mfma_f32_16x16x32_bf16 v[90:93], v[166:169], v[206:209], v[90:93]
	v_mfma_f32_16x16x32_bf16 v[78:81], v[158:161], v[214:217], v[78:81]
	v_mfma_f32_16x16x32_bf16 v[74:77], v[166:169], v[214:217], v[74:77]
	v_mfma_f32_16x16x32_bf16 v[118:121], v[170:173], v[186:189], v[118:121]
	v_mfma_f32_16x16x32_bf16 v[114:117], v[178:181], v[186:189], v[114:117]
	v_mfma_f32_16x16x32_bf16 v[102:105], v[170:173], v[194:197], v[102:105]
	v_mfma_f32_16x16x32_bf16 v[98:101], v[178:181], v[194:197], v[98:101]
	v_mfma_f32_16x16x32_bf16 v[86:89], v[170:173], v[202:205], v[86:89]
	v_mfma_f32_16x16x32_bf16 v[82:85], v[178:181], v[202:205], v[82:85]
	v_mfma_f32_16x16x32_bf16 v[70:73], v[170:173], v[210:213], v[70:73]
	v_mfma_f32_16x16x32_bf16 v[66:69], v[178:181], v[210:213], v[66:69]
	v_mfma_f32_16x16x32_bf16 v[118:121], v[174:177], v[190:193], v[118:121]
	v_mfma_f32_16x16x32_bf16 v[114:117], v[182:185], v[190:193], v[114:117]
	v_mfma_f32_16x16x32_bf16 v[102:105], v[174:177], v[198:201], v[102:105]
	v_mfma_f32_16x16x32_bf16 v[98:101], v[182:185], v[198:201], v[98:101]
	v_mfma_f32_16x16x32_bf16 v[86:89], v[174:177], v[206:209], v[86:89]
	v_mfma_f32_16x16x32_bf16 v[82:85], v[182:185], v[206:209], v[82:85]
	v_mfma_f32_16x16x32_bf16 v[70:73], v[174:177], v[214:217], v[70:73]
	v_mfma_f32_16x16x32_bf16 v[66:69], v[182:185], v[214:217], v[66:69]
	s_setprio 0
	s_barrier
	s_add_i32 s26, s46, s0
	v_lshl_add_u64 v[146:147], v[146:147], 0, s[8:9]
	s_mov_b32 m0, s26
	ds_read_b128 v[186:189], v152 offset:49152
	ds_read_b128 v[190:193], v152 offset:50176
	ds_read_b128 v[194:197], v152 offset:51200
	ds_read_b128 v[198:201], v152 offset:52224
	ds_read_b128 v[202:205], v152 offset:53248
	ds_read_b128 v[206:209], v152 offset:54272
	ds_read_b128 v[210:213], v152 offset:55296
	ds_read_b128 v[214:217], v152 offset:56320
	global_load_lds_dwordx4 v[146:147], off
	s_add_i32 m0, s26, 0x2000
	s_add_u32 s24, s24, 0x40080
	v_lshl_add_u64 v[146:147], v[218:219], 0, s[8:9]
	s_addc_u32 s25, s25, 0
	s_add_i32 s26, s47, s0
	global_load_lds_dwordx4 v[146:147], off
	v_lshl_add_u64 v[146:147], s[24:25], 0, v[134:135]
	s_mov_b32 m0, s26
	s_nop 0
	global_load_lds_dwordx4 v[146:147], off
	v_lshl_add_u64 v[146:147], s[24:25], 0, v[130:131]
	s_add_i32 m0, s26, 0x2000
	s_nop 0
	global_load_lds_dwordx4 v[146:147], off
	s_waitcnt vmcnt(4)
	s_waitcnt lgkmcnt(0)
	s_barrier
	s_setprio 1
	s_waitcnt lgkmcnt(0)
	v_mfma_f32_16x16x32_bf16 v[62:65], v[154:157], v[186:189], v[62:65]
	v_mfma_f32_16x16x32_bf16 v[58:61], v[162:165], v[186:189], v[58:61]
	v_mfma_f32_16x16x32_bf16 v[46:49], v[154:157], v[194:197], v[46:49]
	v_mfma_f32_16x16x32_bf16 v[42:45], v[162:165], v[194:197], v[42:45]
	v_mfma_f32_16x16x32_bf16 v[30:33], v[154:157], v[202:205], v[30:33]
	v_mfma_f32_16x16x32_bf16 v[26:29], v[162:165], v[202:205], v[26:29]
	v_mfma_f32_16x16x32_bf16 v[14:17], v[154:157], v[210:213], v[14:17]
	v_mfma_f32_16x16x32_bf16 v[10:13], v[162:165], v[210:213], v[10:13]
	v_mfma_f32_16x16x32_bf16 v[62:65], v[158:161], v[190:193], v[62:65]
	v_mfma_f32_16x16x32_bf16 v[58:61], v[166:169], v[190:193], v[58:61]
	v_mfma_f32_16x16x32_bf16 v[46:49], v[158:161], v[198:201], v[46:49]
	v_mfma_f32_16x16x32_bf16 v[42:45], v[166:169], v[198:201], v[42:45]
	v_mfma_f32_16x16x32_bf16 v[30:33], v[158:161], v[206:209], v[30:33]
	v_mfma_f32_16x16x32_bf16 v[26:29], v[166:169], v[206:209], v[26:29]
	v_mfma_f32_16x16x32_bf16 v[14:17], v[158:161], v[214:217], v[14:17]
	v_mfma_f32_16x16x32_bf16 v[10:13], v[166:169], v[214:217], v[10:13]
	v_mfma_f32_16x16x32_bf16 v[54:57], v[170:173], v[186:189], v[54:57]
	v_mfma_f32_16x16x32_bf16 v[50:53], v[178:181], v[186:189], v[50:53]
	v_mfma_f32_16x16x32_bf16 v[38:41], v[170:173], v[194:197], v[38:41]
	v_mfma_f32_16x16x32_bf16 v[34:37], v[178:181], v[194:197], v[34:37]
	v_mfma_f32_16x16x32_bf16 v[22:25], v[170:173], v[202:205], v[22:25]
	v_mfma_f32_16x16x32_bf16 v[18:21], v[178:181], v[202:205], v[18:21]
	v_mfma_f32_16x16x32_bf16 v[6:9], v[170:173], v[210:213], v[6:9]
	v_mfma_f32_16x16x32_bf16 v[2:5], v[178:181], v[210:213], v[2:5]
	v_mfma_f32_16x16x32_bf16 v[54:57], v[174:177], v[190:193], v[54:57]
	v_mfma_f32_16x16x32_bf16 v[50:53], v[182:185], v[190:193], v[50:53]
	v_mfma_f32_16x16x32_bf16 v[38:41], v[174:177], v[198:201], v[38:41]
	v_mfma_f32_16x16x32_bf16 v[34:37], v[182:185], v[198:201], v[34:37]
	v_mfma_f32_16x16x32_bf16 v[22:25], v[174:177], v[206:209], v[22:25]
	v_mfma_f32_16x16x32_bf16 v[18:21], v[182:185], v[206:209], v[18:21]
	v_mfma_f32_16x16x32_bf16 v[6:9], v[174:177], v[214:217], v[6:9]
	v_mfma_f32_16x16x32_bf16 v[2:5], v[182:185], v[214:217], v[2:5]
	s_setprio 0
	s_barrier
	s_add_i32 s45, s45, 2
	s_add_u32 s22, s22, 0x100
	s_addc_u32 s23, s23, 0
	s_add_u32 s43, s43, 0x100
	s_addc_u32 s44, s44, 0
	s_cmp_gt_u32 s45, 13
	s_cbranch_scc0 .LBB0_496
	s_and_b64 vcc, exec, s[10:11]
	s_cbranch_vccz .LBB0_499
	s_barrier

; #define PG8_STAGE(bufoff, gbase, voff) do { _Pragma("unroll") for (int _i = 0; _i < 2; ++_i) \
;         __builtin_amdgcn_global_load_lds((const unsigned*)((const char*)(gbase) + (voff)[_i]), (PG8_LAS unsigned*)(lds + (bufoff) + ldsw + _i * 8192), 16, 0, 0); } while (0)
; #define PG8_LDA(dst, b, h) do { _Pragma("unroll") for (int m = 0; m < 4; ++m) _Pragma("unroll") for (int k = 0; k < 2; ++k) dst[m][k] = *(const PG8_LAS bf16x8*)(lds + PG8_SA(b, h) + aoff + m * 2048 + k * 1024); } while (0)
; #define PG8_LDB(dst, b, h) do { _Pragma("unroll") for (int n = 0; n < 2; ++n) _Pragma("unroll") for (int k = 0; k < 2; ++k) dst[n][k] = *(const PG8_LAS bf16x8*)(lds + PG8_SB(b, h) + boff + n * 2048 + k * 1024); } while (0)
; #define PG8_MMA(ai, bj, At, Bt) do { __builtin_amdgcn_s_setprio(1); _Pragma("unroll") for (int m = 0; m < 4; ++m) _Pragma("unroll") for (int n = 0; n < 2; ++n) _Pragma("unroll") for (int k = 0; k < 2; ++k) \
;         acc[ai][bj][m][n] = __builtin_amdgcn_mfma_f32_16x16x32_bf16(Bt[n][k], At[m][k], acc[ai][bj][m][n], 0, 0, 0); __builtin_amdgcn_s_setprio(0); } while (0)
; #define PG8_WAIT_V(n) asm volatile("s_waitcnt vmcnt(" #n ")" ::: "memory")
; #define PG8_WAIT_L(n) asm volatile("s_waitcnt lgkmcnt(" #n ")" ::: "memory")
; #define PG8_BAR __builtin_amdgcn_s_barrier()
; #define PG8_SCHED __builtin_amdgcn_sched_barrier(0)
; template <class Epi, class Sched, bool ALIGN_EPI = false, bool SP2 = false, bool HALFM = false>
; __device__ __forceinline__ void gemm_phase(PG8_LAS unsigned char* lds, const Gemm g, const Sched& S, const Epi& E) {
;     ...
;             PG8_LDB(B0, 0, 0); PG8_LDB(B1, 0, 1); PG8_SCHED; PG8_LDA(At, 0, 0); PG8_STAGE(PG8_SA(1, 1), a1 + hstep, voffA);
;             PG8_WAIT_V(8); PG8_WAIT_L(0); PG8_BAR; PG8_MMA(0, 0, At, B0); PG8_MMA(0, 1, At, B1); PG8_BAR; PG8_SCHED;
;             PG8_LDA(At, 0, 1); PG8_STAGE(PG8_SB(0, 0), b2, voffB); PG8_STAGE(PG8_SB(0, 1), b2 + hstep, voffB); PG8_STAGE(PG8_SA(0, 0), a2, voffA);
;             PG8_WAIT_V(8); PG8_WAIT_L(0); PG8_BAR; if constexpr (!HALFM) { PG8_MMA(1, 0, At, B0); PG8_MMA(1, 1, At, B1); } PG8_BAR; PG8_SCHED;
.LBB0_637:
	ds_read_b128 v[130:133], v208
	ds_read_b128 v[134:137], v208 offset:1024
	ds_read_b128 v[138:141], v208 offset:2048
	ds_read_b128 v[142:145], v208 offset:3072
	ds_read_b128 v[146:149], v209
	ds_read_b128 v[150:153], v209 offset:1024
	ds_read_b128 v[154:157], v209 offset:2048
	ds_read_b128 v[158:161], v209 offset:3072
	s_add_u32 s26, s24, 0x100
	s_addc_u32 s27, s25, 0
	s_cmp_eq_u32 s49, 40
	s_cselect_b32 s31, s11, s27
	s_cselect_b32 s30, s10, s26
	s_cselect_b32 s29, s23, s48
	s_cselect_b32 s28, s22, s47
	v_lshl_add_u64 v[216:217], s[24:25], 0, v[186:187]
	s_add_i32 m0, s1, 0xc000
	ds_read_b128 v[162:165], v210
	ds_read_b128 v[166:169], v210 offset:1024
	ds_read_b128 v[170:173], v210 offset:2048
	ds_read_b128 v[174:177], v210 offset:3072
	ds_read_b128 v[194:197], v210 offset:4096
	ds_read_b128 v[198:201], v210 offset:5120
	ds_read_b128 v[202:205], v210 offset:6144
	ds_read_b128 v[212:215], v210 offset:7168
	global_load_lds_dwordx4 v[216:217], off
	v_lshl_add_u64 v[216:217], s[24:25], 0, v[188:189]
	s_add_i32 m0, s1, 0xe000
	s_nop 0
	global_load_lds_dwordx4 v[216:217], off
	s_mov_b32 m0, s38
	v_lshl_add_u64 v[216:217], v[220:221], 0, s[18:19]
	global_load_lds_dwordx4 v[216:217], off
	s_mov_b32 m0, s39
	v_lshl_add_u64 v[216:217], v[222:223], 0, s[18:19]
	global_load_lds_dwordx4 v[216:217], off
	s_waitcnt vmcnt(10)
	s_waitcnt lgkmcnt(0)
	s_barrier
	s_setprio 1
	s_waitcnt lgkmcnt(0)
	v_mfma_f32_16x16x32_bf16 v[126:129], v[130:133], v[162:165], v[126:129]
	v_mfma_f32_16x16x32_bf16 v[122:125], v[138:141], v[162:165], v[122:125]
	v_mfma_f32_16x16x32_bf16 v[110:113], v[130:133], v[170:173], v[110:113]
	v_mfma_f32_16x16x32_bf16 v[106:109], v[138:141], v[170:173], v[106:109]
	v_mfma_f32_16x16x32_bf16 v[94:97], v[130:133], v[194:197], v[94:97]
	v_mfma_f32_16x16x32_bf16 v[90:93], v[138:141], v[194:197], v[90:93]
	v_mfma_f32_16x16x32_bf16 v[78:81], v[130:133], v[202:205], v[78:81]
	v_mfma_f32_16x16x32_bf16 v[74:77], v[138:141], v[202:205], v[74:77]
	v_mfma_f32_16x16x32_bf16 v[126:129], v[134:137], v[166:169], v[126:129]
	v_mfma_f32_16x16x32_bf16 v[122:125], v[142:145], v[166:169], v[122:125]
	v_mfma_f32_16x16x32_bf16 v[110:113], v[134:137], v[174:177], v[110:113]
	v_mfma_f32_16x16x32_bf16 v[106:109], v[142:145], v[174:177], v[106:109]
	v_mfma_f32_16x16x32_bf16 v[94:97], v[134:137], v[198:201], v[94:97]
	v_mfma_f32_16x16x32_bf16 v[90:93], v[142:145], v[198:201], v[90:93]
	v_mfma_f32_16x16x32_bf16 v[78:81], v[134:137], v[212:215], v[78:81]
	v_mfma_f32_16x16x32_bf16 v[74:77], v[142:145], v[212:215], v[74:77]
	v_mfma_f32_16x16x32_bf16 v[118:121], v[146:149], v[162:165], v[118:121]
	v_mfma_f32_16x16x32_bf16 v[114:117], v[154:157], v[162:165], v[114:117]
	v_mfma_f32_16x16x32_bf16 v[102:105], v[146:149], v[170:173], v[102:105]
	v_mfma_f32_16x16x32_bf16 v[98:101], v[154:157], v[170:173], v[98:101]
	v_mfma_f32_16x16x32_bf16 v[86:89], v[146:149], v[194:197], v[86:89]
	v_mfma_f32_16x16x32_bf16 v[82:85], v[154:157], v[194:197], v[82:85]
	v_mfma_f32_16x16x32_bf16 v[70:73], v[146:149], v[202:205], v[70:73]
	v_mfma_f32_16x16x32_bf16 v[66:69], v[154:157], v[202:205], v[66:69]
	v_mfma_f32_16x16x32_bf16 v[118:121], v[150:153], v[166:169], v[118:121]
	v_mfma_f32_16x16x32_bf16 v[114:117], v[158:161], v[166:169], v[114:117]
	v_mfma_f32_16x16x32_bf16 v[102:105], v[150:153], v[174:177], v[102:105]
	v_mfma_f32_16x16x32_bf16 v[98:101], v[158:161], v[174:177], v[98:101]
	v_mfma_f32_16x16x32_bf16 v[86:89], v[150:153], v[198:201], v[86:89]
	v_mfma_f32_16x16x32_bf16 v[82:85], v[158:161], v[198:201], v[82:85]
	v_mfma_f32_16x16x32_bf16 v[70:73], v[150:153], v[212:215], v[70:73]
	v_mfma_f32_16x16x32_bf16 v[66:69], v[158:161], v[212:215], v[66:69]
	s_setprio 0
	s_barrier
	s_add_i32 s24, s41, s0
	v_lshl_add_u64 v[216:217], s[28:29], 0, v[180:181]
	s_mov_b32 m0, s24
	ds_read_b128 v[162:165], v210 offset:16384
	ds_read_b128 v[166:169], v210 offset:17408
	ds_read_b128 v[170:173], v210 offset:18432
	ds_read_b128 v[174:177], v210 offset:19456
	ds_read_b128 v[194:197], v210 offset:20480
	ds_read_b128 v[198:201], v210 offset:21504
	ds_read_b128 v[202:205], v210 offset:22528
	ds_read_b128 v[212:215], v210 offset:23552
	global_load_lds_dwordx4 v[216:217], off
	s_add_i32 m0, s24, 0x2000
	s_add_u32 s24, s28, 0xb0000
	v_lshl_add_u64 v[218:219], s[28:29], 0, v[184:185]
	s_addc_u32 s25, s29, 0
	s_add_i32 s50, s42, s0
	global_load_lds_dwordx4 v[218:219], off
	v_lshl_add_u64 v[220:221], s[24:25], 0, v[180:181]
	s_mov_b32 m0, s50
	v_lshl_add_u64 v[222:223], s[30:31], 0, v[182:183]
	global_load_lds_dwordx4 v[220:221], off
	v_lshl_add_u64 v[220:221], s[24:25], 0, v[184:185]
	s_add_i32 m0, s50, 0x2000
	s_nop 0
	global_load_lds_dwordx4 v[220:221], off
	v_lshl_add_u64 v[220:221], s[30:31], 0, v[178:179]
	s_waitcnt vmcnt(4)
	s_waitcnt lgkmcnt(0)
	s_barrier
; #define PG8_STAGE(bufoff, gbase, voff) do { _Pragma("unroll") for (int _i = 0; _i < 2; ++_i) \
;         __builtin_amdgcn_global_load_lds((const unsigned*)((const char*)(gbase) + (voff)[_i]), (PG8_LAS unsigned*)(lds + (bufoff) + ldsw + _i * 8192), 16, 0, 0); } while (0)
; #define PG8_LDA(dst, b, h) do { _Pragma("unroll") for (int m = 0; m < 4; ++m) _Pragma("unroll") for (int k = 0; k < 2; ++k) dst[m][k] = *(const PG8_LAS bf16x8*)(lds + PG8_SA(b, h) + aoff + m * 2048 + k * 1024); } while (0)
; #define PG8_LDB(dst, b, h) do { _Pragma("unroll") for (int n = 0; n < 2; ++n) _Pragma("unroll") for (int k = 0; k < 2; ++k) dst[n][k] = *(const PG8_LAS bf16x8*)(lds + PG8_SB(b, h) + boff + n * 2048 + k * 1024); } while (0)
; #define PG8_MMA(ai, bj, At, Bt) do { __builtin_amdgcn_s_setprio(1); _Pragma("unroll") for (int m = 0; m < 4; ++m) _Pragma("unroll") for (int n = 0; n < 2; ++n) _Pragma("unroll") for (int k = 0; k < 2; ++k) \
;         acc[ai][bj][m][n] = __builtin_amdgcn_mfma_f32_16x16x32_bf16(Bt[n][k], At[m][k], acc[ai][bj][m][n], 0, 0, 0); __builtin_amdgcn_s_setprio(0); } while (0)
; #define PG8_WAIT_V(n) asm volatile("s_waitcnt vmcnt(" #n ")" ::: "memory")
; #define PG8_WAIT_L(n) asm volatile("s_waitcnt lgkmcnt(" #n ")" ::: "memory")
; #define PG8_BAR __builtin_amdgcn_s_barrier()
; #define PG8_SCHED __builtin_amdgcn_sched_barrier(0)
; template <class Epi, class Sched, bool ALIGN_EPI = false, bool SP2 = false, bool HALFM = false>
; __device__ __forceinline__ void gemm_phase(PG8_LAS unsigned char* lds, const Gemm g, const Sched& S, const Epi& E) {
;     ...
;             PG8_WAIT_V(8); PG8_WAIT_L(0); PG8_BAR; if constexpr (!HALFM) { PG8_MMA(1, 0, At, B0); PG8_MMA(1, 1, At, B1); } PG8_BAR; PG8_SCHED;
;             PG8_LDB(B0, 1, 0); PG8_LDB(B1, 1, 1); PG8_SCHED; PG8_LDA(At, 1, 0); PG8_STAGE(PG8_SA(0, 1), a2 + hstep, voffA);
;             PG8_WAIT_V(8); PG8_WAIT_L(0); PG8_BAR; PG8_MMA(0, 0, At, B0); PG8_MMA(0, 1, At, B1); PG8_BAR; PG8_SCHED;
	s_setprio 1
	s_waitcnt lgkmcnt(0)
	v_mfma_f32_16x16x32_bf16 v[62:65], v[130:133], v[162:165], v[62:65]
	v_mfma_f32_16x16x32_bf16 v[58:61], v[138:141], v[162:165], v[58:61]
	v_mfma_f32_16x16x32_bf16 v[46:49], v[130:133], v[170:173], v[46:49]
	v_mfma_f32_16x16x32_bf16 v[42:45], v[138:141], v[170:173], v[42:45]
	v_mfma_f32_16x16x32_bf16 v[30:33], v[130:133], v[194:197], v[30:33]
	v_mfma_f32_16x16x32_bf16 v[26:29], v[138:141], v[194:197], v[26:29]
	v_mfma_f32_16x16x32_bf16 v[14:17], v[130:133], v[202:205], v[14:17]
	v_mfma_f32_16x16x32_bf16 v[10:13], v[138:141], v[202:205], v[10:13]
	v_mfma_f32_16x16x32_bf16 v[62:65], v[134:137], v[166:169], v[62:65]
	v_mfma_f32_16x16x32_bf16 v[58:61], v[142:145], v[166:169], v[58:61]
	v_mfma_f32_16x16x32_bf16 v[46:49], v[134:137], v[174:177], v[46:49]
	v_mfma_f32_16x16x32_bf16 v[42:45], v[142:145], v[174:177], v[42:45]
	v_mfma_f32_16x16x32_bf16 v[30:33], v[134:137], v[198:201], v[30:33]
	v_mfma_f32_16x16x32_bf16 v[26:29], v[142:145], v[198:201], v[26:29]
	v_mfma_f32_16x16x32_bf16 v[14:17], v[134:137], v[212:215], v[14:17]
	v_mfma_f32_16x16x32_bf16 v[10:13], v[142:145], v[212:215], v[10:13]
	v_mfma_f32_16x16x32_bf16 v[54:57], v[146:149], v[162:165], v[54:57]
	v_mfma_f32_16x16x32_bf16 v[50:53], v[154:157], v[162:165], v[50:53]
	v_mfma_f32_16x16x32_bf16 v[38:41], v[146:149], v[170:173], v[38:41]
	v_mfma_f32_16x16x32_bf16 v[34:37], v[154:157], v[170:173], v[34:37]
	v_mfma_f32_16x16x32_bf16 v[22:25], v[146:149], v[194:197], v[22:25]
	v_mfma_f32_16x16x32_bf16 v[18:21], v[154:157], v[194:197], v[18:21]
	v_mfma_f32_16x16x32_bf16 v[6:9], v[146:149], v[202:205], v[6:9]
	v_mfma_f32_16x16x32_bf16 v[2:5], v[154:157], v[202:205], v[2:5]
	v_mfma_f32_16x16x32_bf16 v[54:57], v[150:153], v[166:169], v[54:57]
	v_mfma_f32_16x16x32_bf16 v[50:53], v[158:161], v[166:169], v[50:53]
	v_mfma_f32_16x16x32_bf16 v[38:41], v[150:153], v[174:177], v[38:41]
	v_mfma_f32_16x16x32_bf16 v[34:37], v[158:161], v[174:177], v[34:37]
	v_mfma_f32_16x16x32_bf16 v[22:25], v[150:153], v[198:201], v[22:25]
	v_mfma_f32_16x16x32_bf16 v[18:21], v[158:161], v[198:201], v[18:21]
	v_mfma_f32_16x16x32_bf16 v[6:9], v[150:153], v[212:215], v[6:9]
	v_mfma_f32_16x16x32_bf16 v[2:5], v[158:161], v[212:215], v[2:5]
	s_setprio 0
	s_barrier
	s_add_i32 s50, 0, 0x18000
	s_add_i32 s51, 0, 0x1c000
	v_add_u32_e32 v142, s50, v206
	v_add_u32_e32 v158, s51, v206
	ds_read_b128 v[130:133], v142
	ds_read_b128 v[134:137], v142 offset:1024
	ds_read_b128 v[138:141], v142 offset:2048
	ds_read_b128 v[142:145], v142 offset:3072
	ds_read_b128 v[146:149], v158
	ds_read_b128 v[150:153], v158 offset:1024
	ds_read_b128 v[154:157], v158 offset:2048
	ds_read_b128 v[158:161], v158 offset:3072
	s_add_u32 s24, s30, 0xb0000
	s_addc_u32 s25, s31, 0
	s_mov_b32 m0, s3
	v_lshl_add_u64 v[224:225], s[24:25], 0, v[178:179]
	ds_read_b128 v[162:165], v210 offset:32768
	ds_read_b128 v[166:169], v210 offset:33792
	ds_read_b128 v[170:173], v210 offset:34816
	ds_read_b128 v[174:177], v210 offset:35840
	ds_read_b128 v[194:197], v210 offset:36864
	ds_read_b128 v[198:201], v210 offset:37888
	ds_read_b128 v[202:205], v210 offset:38912
	ds_read_b128 v[212:215], v210 offset:39936
	global_load_lds_dwordx4 v[224:225], off
	v_lshl_add_u64 v[224:225], s[24:25], 0, v[182:183]
	s_mov_b32 m0, s36
	s_nop 0
	global_load_lds_dwordx4 v[224:225], off
	s_mov_b32 m0, s1
	s_nop 0
	global_load_lds_dwordx4 v[220:221], off
	s_mov_b32 m0, s2
	s_nop 0
	global_load_lds_dwordx4 v[222:223], off
	s_waitcnt vmcnt(10)
	s_waitcnt lgkmcnt(0)
	s_barrier
; #define PG8_STAGE(bufoff, gbase, voff) do { _Pragma("unroll") for (int _i = 0; _i < 2; ++_i) \
;         __builtin_amdgcn_global_load_lds((const unsigned*)((const char*)(gbase) + (voff)[_i]), (PG8_LAS unsigned*)(lds + (bufoff) + ldsw + _i * 8192), 16, 0, 0); } while (0)
; #define PG8_LDA(dst, b, h) do { _Pragma("unroll") for (int m = 0; m < 4; ++m) _Pragma("unroll") for (int k = 0; k < 2; ++k) dst[m][k] = *(const PG8_LAS bf16x8*)(lds + PG8_SA(b, h) + aoff + m * 2048 + k * 1024); } while (0)
; #define PG8_MMA(ai, bj, At, Bt) do { __builtin_amdgcn_s_setprio(1); _Pragma("unroll") for (int m = 0; m < 4; ++m) _Pragma("unroll") for (int n = 0; n < 2; ++n) _Pragma("unroll") for (int k = 0; k < 2; ++k) \
;         acc[ai][bj][m][n] = __builtin_amdgcn_mfma_f32_16x16x32_bf16(Bt[n][k], At[m][k], acc[ai][bj][m][n], 0, 0, 0); __builtin_amdgcn_s_setprio(0); } while (0)
; #define PG8_WAIT_V(n) asm volatile("s_waitcnt vmcnt(" #n ")" ::: "memory")
; #define PG8_WAIT_L(n) asm volatile("s_waitcnt lgkmcnt(" #n ")" ::: "memory")
; #define PG8_BAR __builtin_amdgcn_s_barrier()
; #define PG8_SCHED __builtin_amdgcn_sched_barrier(0)
; template <class Epi, class Sched, bool ALIGN_EPI = false, bool SP2 = false, bool HALFM = false>
; __device__ __forceinline__ void gemm_phase(PG8_LAS unsigned char* lds, const Gemm g, const Sched& S, const Epi& E) {
;     ...
;             PG8_WAIT_V(8); PG8_WAIT_L(0); PG8_BAR; PG8_MMA(0, 0, At, B0); PG8_MMA(0, 1, At, B1); PG8_BAR; PG8_SCHED;
;             PG8_LDA(At, 1, 1); PG8_STAGE(PG8_SB(1, 0), b3, voffB); PG8_STAGE(PG8_SB(1, 1), b3 + hstep, voffB); PG8_STAGE(PG8_SA(1, 0), a3, voffA);
;             PG8_WAIT_V(8); PG8_WAIT_L(0); PG8_BAR; if constexpr (!HALFM) { PG8_MMA(1, 0, At, B0); PG8_MMA(1, 1, At, B1); } PG8_BAR; PG8_SCHED;
	s_setprio 1
	s_waitcnt lgkmcnt(0)
	v_mfma_f32_16x16x32_bf16 v[126:129], v[130:133], v[162:165], v[126:129]
	v_mfma_f32_16x16x32_bf16 v[122:125], v[138:141], v[162:165], v[122:125]
	v_mfma_f32_16x16x32_bf16 v[110:113], v[130:133], v[170:173], v[110:113]
	v_mfma_f32_16x16x32_bf16 v[106:109], v[138:141], v[170:173], v[106:109]
	v_mfma_f32_16x16x32_bf16 v[94:97], v[130:133], v[194:197], v[94:97]
	v_mfma_f32_16x16x32_bf16 v[90:93], v[138:141], v[194:197], v[90:93]
	v_mfma_f32_16x16x32_bf16 v[78:81], v[130:133], v[202:205], v[78:81]
	v_mfma_f32_16x16x32_bf16 v[74:77], v[138:141], v[202:205], v[74:77]
	v_mfma_f32_16x16x32_bf16 v[126:129], v[134:137], v[166:169], v[126:129]
	v_mfma_f32_16x16x32_bf16 v[122:125], v[142:145], v[166:169], v[122:125]
	v_mfma_f32_16x16x32_bf16 v[110:113], v[134:137], v[174:177], v[110:113]
	v_mfma_f32_16x16x32_bf16 v[106:109], v[142:145], v[174:177], v[106:109]
	v_mfma_f32_16x16x32_bf16 v[94:97], v[134:137], v[198:201], v[94:97]
	v_mfma_f32_16x16x32_bf16 v[90:93], v[142:145], v[198:201], v[90:93]
	v_mfma_f32_16x16x32_bf16 v[78:81], v[134:137], v[212:215], v[78:81]
	v_mfma_f32_16x16x32_bf16 v[74:77], v[142:145], v[212:215], v[74:77]
	v_mfma_f32_16x16x32_bf16 v[118:121], v[146:149], v[162:165], v[118:121]
	v_mfma_f32_16x16x32_bf16 v[114:117], v[154:157], v[162:165], v[114:117]
	v_mfma_f32_16x16x32_bf16 v[102:105], v[146:149], v[170:173], v[102:105]
	v_mfma_f32_16x16x32_bf16 v[98:101], v[154:157], v[170:173], v[98:101]
	v_mfma_f32_16x16x32_bf16 v[86:89], v[146:149], v[194:197], v[86:89]
	v_mfma_f32_16x16x32_bf16 v[82:85], v[154:157], v[194:197], v[82:85]
	v_mfma_f32_16x16x32_bf16 v[70:73], v[146:149], v[202:205], v[70:73]
	v_mfma_f32_16x16x32_bf16 v[66:69], v[154:157], v[202:205], v[66:69]
	v_mfma_f32_16x16x32_bf16 v[118:121], v[150:153], v[166:169], v[118:121]
	v_mfma_f32_16x16x32_bf16 v[114:117], v[158:161], v[166:169], v[114:117]
	v_mfma_f32_16x16x32_bf16 v[102:105], v[150:153], v[174:177], v[102:105]
	v_mfma_f32_16x16x32_bf16 v[98:101], v[158:161], v[174:177], v[98:101]
	v_mfma_f32_16x16x32_bf16 v[86:89], v[150:153], v[198:201], v[86:89]
	v_mfma_f32_16x16x32_bf16 v[82:85], v[158:161], v[198:201], v[82:85]
	v_mfma_f32_16x16x32_bf16 v[70:73], v[150:153], v[212:215], v[70:73]
	v_mfma_f32_16x16x32_bf16 v[66:69], v[158:161], v[212:215], v[66:69]
	s_setprio 0
	s_barrier
	s_add_i32 s24, s50, s0
	v_lshl_add_u64 v[216:217], v[216:217], 0, s[18:19]
	s_mov_b32 m0, s24
	ds_read_b128 v[162:165], v210 offset:49152
	ds_read_b128 v[166:169], v210 offset:50176
	ds_read_b128 v[170:173], v210 offset:51200
	ds_read_b128 v[174:177], v210 offset:52224
	ds_read_b128 v[194:197], v210 offset:53248
	ds_read_b128 v[198:201], v210 offset:54272
	ds_read_b128 v[202:205], v210 offset:55296
	ds_read_b128 v[212:215], v210 offset:56320
	global_load_lds_dwordx4 v[216:217], off
	s_add_i32 m0, s24, 0x2000
	s_add_u32 s24, s28, 0xb0080
	v_lshl_add_u64 v[216:217], v[218:219], 0, s[18:19]
	s_addc_u32 s25, s29, 0
	s_add_i32 s28, s51, s0
	global_load_lds_dwordx4 v[216:217], off
	v_lshl_add_u64 v[216:217], s[24:25], 0, v[180:181]
	s_mov_b32 m0, s28
	s_nop 0
	global_load_lds_dwordx4 v[216:217], off
	v_lshl_add_u64 v[216:217], s[24:25], 0, v[184:185]
	s_add_i32 m0, s28, 0x2000
	s_nop 0
	global_load_lds_dwordx4 v[216:217], off
	s_waitcnt vmcnt(4)
	s_waitcnt lgkmcnt(0)
	s_barrier
	s_setprio 1
	s_waitcnt lgkmcnt(0)
	v_mfma_f32_16x16x32_bf16 v[62:65], v[130:133], v[162:165], v[62:65]
	v_mfma_f32_16x16x32_bf16 v[58:61], v[138:141], v[162:165], v[58:61]
	v_mfma_f32_16x16x32_bf16 v[46:49], v[130:133], v[170:173], v[46:49]
	v_mfma_f32_16x16x32_bf16 v[42:45], v[138:141], v[170:173], v[42:45]
	v_mfma_f32_16x16x32_bf16 v[30:33], v[130:133], v[194:197], v[30:33]
	v_mfma_f32_16x16x32_bf16 v[26:29], v[138:141], v[194:197], v[26:29]
	v_mfma_f32_16x16x32_bf16 v[14:17], v[130:133], v[202:205], v[14:17]
	v_mfma_f32_16x16x32_bf16 v[10:13], v[138:141], v[202:205], v[10:13]
	v_mfma_f32_16x16x32_bf16 v[62:65], v[134:137], v[166:169], v[62:65]
	v_mfma_f32_16x16x32_bf16 v[58:61], v[142:145], v[166:169], v[58:61]
	v_mfma_f32_16x16x32_bf16 v[46:49], v[134:137], v[174:177], v[46:49]
	v_mfma_f32_16x16x32_bf16 v[42:45], v[142:145], v[174:177], v[42:45]
	v_mfma_f32_16x16x32_bf16 v[30:33], v[134:137], v[198:201], v[30:33]
	v_mfma_f32_16x16x32_bf16 v[26:29], v[142:145], v[198:201], v[26:29]
	v_mfma_f32_16x16x32_bf16 v[14:17], v[134:137], v[212:215], v[14:17]
	v_mfma_f32_16x16x32_bf16 v[10:13], v[142:145], v[212:215], v[10:13]
	v_mfma_f32_16x16x32_bf16 v[54:57], v[146:149], v[162:165], v[54:57]
	v_mfma_f32_16x16x32_bf16 v[50:53], v[154:157], v[162:165], v[50:53]
	v_mfma_f32_16x16x32_bf16 v[38:41], v[146:149], v[170:173], v[38:41]
	v_mfma_f32_16x16x32_bf16 v[34:37], v[154:157], v[170:173], v[34:37]
	v_mfma_f32_16x16x32_bf16 v[22:25], v[146:149], v[194:197], v[22:25]
	v_mfma_f32_16x16x32_bf16 v[18:21], v[154:157], v[194:197], v[18:21]
	v_mfma_f32_16x16x32_bf16 v[6:9], v[146:149], v[202:205], v[6:9]
	v_mfma_f32_16x16x32_bf16 v[2:5], v[154:157], v[202:205], v[2:5]
	v_mfma_f32_16x16x32_bf16 v[54:57], v[150:153], v[166:169], v[54:57]
	v_mfma_f32_16x16x32_bf16 v[50:53], v[158:161], v[166:169], v[50:53]
	v_mfma_f32_16x16x32_bf16 v[38:41], v[150:153], v[174:177], v[38:41]
	v_mfma_f32_16x16x32_bf16 v[34:37], v[158:161], v[174:177], v[34:37]
	v_mfma_f32_16x16x32_bf16 v[22:25], v[150:153], v[198:201], v[22:25]
	v_mfma_f32_16x16x32_bf16 v[18:21], v[158:161], v[198:201], v[18:21]
	v_mfma_f32_16x16x32_bf16 v[6:9], v[150:153], v[212:215], v[6:9]
	v_mfma_f32_16x16x32_bf16 v[2:5], v[158:161], v[212:215], v[2:5]
	s_setprio 0
	s_barrier
	s_add_i32 s49, s49, 2
	s_add_u32 s47, s47, 0x100
	s_addc_u32 s48, s48, 0
	s_cmp_gt_u32 s49, 41
	s_mov_b64 s[24:25], s[26:27]
	s_cbranch_scc0 .LBB0_637
	s_and_b64 vcc, exec, s[20:21]
	s_cbranch_vccz .LBB0_640
	s_barrier

; #define PG8_STAGE(bufoff, gbase, voff) do { _Pragma("unroll") for (int _i = 0; _i < 2; ++_i) \
;         __builtin_amdgcn_global_load_lds((const unsigned*)((const char*)(gbase) + (voff)[_i]), (PG8_LAS unsigned*)(lds + (bufoff) + ldsw + _i * 8192), 16, 0, 0); } while (0)
; #define PG8_LDA(dst, b, h) do { _Pragma("unroll") for (int m = 0; m < 4; ++m) _Pragma("unroll") for (int k = 0; k < 2; ++k) dst[m][k] = *(const PG8_LAS bf16x8*)(lds + PG8_SA(b, h) + aoff + m * 2048 + k * 1024); } while (0)
; #define PG8_LDB(dst, b, h) do { _Pragma("unroll") for (int n = 0; n < 2; ++n) _Pragma("unroll") for (int k = 0; k < 2; ++k) dst[n][k] = *(const PG8_LAS bf16x8*)(lds + PG8_SB(b, h) + boff + n * 2048 + k * 1024); } while (0)
; #define PG8_MMA(ai, bj, At, Bt) do { __builtin_amdgcn_s_setprio(1); _Pragma("unroll") for (int m = 0; m < 4; ++m) _Pragma("unroll") for (int n = 0; n < 2; ++n) _Pragma("unroll") for (int k = 0; k < 2; ++k) \
;         acc[ai][bj][m][n] = __builtin_amdgcn_mfma_f32_16x16x32_bf16(Bt[n][k], At[m][k], acc[ai][bj][m][n], 0, 0, 0); __builtin_amdgcn_s_setprio(0); } while (0)
; #define PG8_WAIT_V(n) asm volatile("s_waitcnt vmcnt(" #n ")" ::: "memory")
; #define PG8_WAIT_L(n) asm volatile("s_waitcnt lgkmcnt(" #n ")" ::: "memory")
; #define PG8_BAR __builtin_amdgcn_s_barrier()
; #define PG8_SCHED __builtin_amdgcn_sched_barrier(0)
; template <class Epi, class Sched, bool ALIGN_EPI = false, bool SP2 = false, bool HALFM = false>
; __device__ __forceinline__ void gemm_phase(PG8_LAS unsigned char* lds, const Gemm g, const Sched& S, const Epi& E) {
;     ...
;             PG8_LDB(B0, 0, 0); PG8_LDB(B1, 0, 1); PG8_SCHED; PG8_LDA(At, 0, 0); PG8_STAGE(PG8_SA(1, 1), a1 + hstep, voffA);
;             PG8_WAIT_V(8); PG8_WAIT_L(0); PG8_BAR; PG8_MMA(0, 0, At, B0); PG8_MMA(0, 1, At, B1); PG8_BAR; PG8_SCHED;
;             PG8_LDA(At, 0, 1); PG8_STAGE(PG8_SB(0, 0), b2, voffB); PG8_STAGE(PG8_SB(0, 1), b2 + hstep, voffB); PG8_STAGE(PG8_SA(0, 0), a2, voffA);
;             PG8_WAIT_V(8); PG8_WAIT_L(0); PG8_BAR; if constexpr (!HALFM) { PG8_MMA(1, 0, At, B0); PG8_MMA(1, 1, At, B1); } PG8_BAR; PG8_SCHED;
.LBB0_752:
	s_waitcnt lgkmcnt(0)
	ds_read_b128 v[82:85], v190
	ds_read_b128 v[134:137], v190 offset:1024
	ds_read_b128 v[160:163], v190 offset:2048
	ds_read_b128 v[164:167], v190 offset:3072
	ds_read_b128 v[168:171], v191
	ds_read_b128 v[172:175], v191 offset:1024
	ds_read_b128 v[176:179], v191 offset:2048
	ds_read_b128 v[180:183], v191 offset:3072
	s_add_u32 s31, s8, 0xfffc0080
	s_addc_u32 s38, s9, -1
	s_cmp_eq_u32 s29, 12
	s_cselect_b32 s41, s0, s38
	s_cselect_b32 s40, s1, s31
	s_cselect_b32 s39, s2, s11
	s_cselect_b32 s38, s3, s5
	v_lshl_add_u64 v[224:225], s[8:9], 0, v[152:153]
	s_add_i32 m0, s44, 0xc000
	ds_read_b128 v[184:187], v192
	ds_read_b128 v[196:199], v192 offset:1024
	ds_read_b128 v[200:203], v192 offset:2048
	ds_read_b128 v[204:207], v192 offset:3072
	ds_read_b128 v[208:211], v192 offset:4096
	ds_read_b128 v[212:215], v192 offset:5120
	ds_read_b128 v[216:219], v192 offset:6144
	ds_read_b128 v[220:223], v192 offset:7168
	global_load_lds_dwordx4 v[224:225], off
	v_lshl_add_u64 v[224:225], s[8:9], 0, v[154:155]
	s_add_i32 m0, s44, 0xe000
	s_nop 0
	global_load_lds_dwordx4 v[224:225], off
	s_mov_b32 m0, s52
	v_lshl_add_u64 v[224:225], v[228:229], 0, s[20:21]
	global_load_lds_dwordx4 v[224:225], off
	s_mov_b32 m0, s53
	v_lshl_add_u64 v[224:225], v[230:231], 0, s[20:21]
	global_load_lds_dwordx4 v[224:225], off
	s_waitcnt vmcnt(10)
	s_waitcnt lgkmcnt(0)
	s_barrier
	s_setprio 1
	s_waitcnt lgkmcnt(0)
	v_mfma_f32_16x16x32_bf16 v[130:133], v[82:85], v[184:187], v[130:133]
	v_mfma_f32_16x16x32_bf16 v[126:129], v[160:163], v[184:187], v[126:129]
	v_mfma_f32_16x16x32_bf16 v[114:117], v[82:85], v[200:203], v[114:117]
	v_mfma_f32_16x16x32_bf16 v[110:113], v[160:163], v[200:203], v[110:113]
	v_mfma_f32_16x16x32_bf16 v[98:101], v[82:85], v[208:211], v[98:101]
	v_mfma_f32_16x16x32_bf16 v[94:97], v[160:163], v[208:211], v[94:97]
	v_mfma_f32_16x16x32_bf16 v[78:81], v[82:85], v[216:219], v[78:81]
	v_mfma_f32_16x16x32_bf16 v[74:77], v[160:163], v[216:219], v[74:77]
	v_mfma_f32_16x16x32_bf16 v[130:133], v[134:137], v[196:199], v[130:133]
	v_mfma_f32_16x16x32_bf16 v[126:129], v[164:167], v[196:199], v[126:129]
	v_mfma_f32_16x16x32_bf16 v[114:117], v[134:137], v[204:207], v[114:117]
	v_mfma_f32_16x16x32_bf16 v[110:113], v[164:167], v[204:207], v[110:113]
	v_mfma_f32_16x16x32_bf16 v[98:101], v[134:137], v[212:215], v[98:101]
	v_mfma_f32_16x16x32_bf16 v[94:97], v[164:167], v[212:215], v[94:97]
	v_mfma_f32_16x16x32_bf16 v[78:81], v[134:137], v[220:223], v[78:81]
	v_mfma_f32_16x16x32_bf16 v[74:77], v[164:167], v[220:223], v[74:77]
	v_mfma_f32_16x16x32_bf16 v[122:125], v[168:171], v[184:187], v[122:125]
	v_mfma_f32_16x16x32_bf16 v[118:121], v[176:179], v[184:187], v[118:121]
	v_mfma_f32_16x16x32_bf16 v[106:109], v[168:171], v[200:203], v[106:109]
	v_mfma_f32_16x16x32_bf16 v[102:105], v[176:179], v[200:203], v[102:105]
	v_mfma_f32_16x16x32_bf16 v[90:93], v[168:171], v[208:211], v[90:93]
	v_mfma_f32_16x16x32_bf16 v[86:89], v[176:179], v[208:211], v[86:89]
	v_mfma_f32_16x16x32_bf16 v[70:73], v[168:171], v[216:219], v[70:73]
	v_mfma_f32_16x16x32_bf16 v[66:69], v[176:179], v[216:219], v[66:69]
	v_mfma_f32_16x16x32_bf16 v[122:125], v[172:175], v[196:199], v[122:125]
	v_mfma_f32_16x16x32_bf16 v[118:121], v[180:183], v[196:199], v[118:121]
	v_mfma_f32_16x16x32_bf16 v[106:109], v[172:175], v[204:207], v[106:109]
	v_mfma_f32_16x16x32_bf16 v[102:105], v[180:183], v[204:207], v[102:105]
	v_mfma_f32_16x16x32_bf16 v[90:93], v[172:175], v[212:215], v[90:93]
	v_mfma_f32_16x16x32_bf16 v[86:89], v[180:183], v[212:215], v[86:89]
	v_mfma_f32_16x16x32_bf16 v[70:73], v[172:175], v[220:223], v[70:73]
	v_mfma_f32_16x16x32_bf16 v[66:69], v[180:183], v[220:223], v[66:69]
	s_setprio 0
	s_barrier
	s_add_i32 s31, s56, s27
	v_lshl_add_u64 v[224:225], s[38:39], 0, v[140:141]
	s_mov_b32 m0, s31
	ds_read_b128 v[184:187], v192 offset:16384
	ds_read_b128 v[196:199], v192 offset:17408
	ds_read_b128 v[200:203], v192 offset:18432
	ds_read_b128 v[204:207], v192 offset:19456
	ds_read_b128 v[208:211], v192 offset:20480
	ds_read_b128 v[212:215], v192 offset:21504
	ds_read_b128 v[216:219], v192 offset:22528
	ds_read_b128 v[220:223], v192 offset:23552
	global_load_lds_dwordx4 v[224:225], off
	s_add_i32 m0, s31, 0x2000
	s_add_u32 s42, s38, 0x40000
	v_lshl_add_u64 v[226:227], s[38:39], 0, v[144:145]
	s_addc_u32 s43, s39, 0
	s_add_i32 s31, s57, s27
	global_load_lds_dwordx4 v[226:227], off
	v_lshl_add_u64 v[228:229], s[42:43], 0, v[140:141]
	s_mov_b32 m0, s31
	v_lshl_add_u64 v[230:231], s[40:41], 0, v[142:143]
	global_load_lds_dwordx4 v[228:229], off
	v_lshl_add_u64 v[228:229], s[42:43], 0, v[144:145]
	s_add_i32 m0, s31, 0x2000
	s_nop 0
	global_load_lds_dwordx4 v[228:229], off
	v_lshl_add_u64 v[228:229], s[40:41], 0, v[138:139]
	s_waitcnt vmcnt(4)
	s_waitcnt lgkmcnt(0)
	s_barrier
; #define PG8_STAGE(bufoff, gbase, voff) do { _Pragma("unroll") for (int _i = 0; _i < 2; ++_i) \
;         __builtin_amdgcn_global_load_lds((const unsigned*)((const char*)(gbase) + (voff)[_i]), (PG8_LAS unsigned*)(lds + (bufoff) + ldsw + _i * 8192), 16, 0, 0); } while (0)
; #define PG8_LDA(dst, b, h) do { _Pragma("unroll") for (int m = 0; m < 4; ++m) _Pragma("unroll") for (int k = 0; k < 2; ++k) dst[m][k] = *(const PG8_LAS bf16x8*)(lds + PG8_SA(b, h) + aoff + m * 2048 + k * 1024); } while (0)
; #define PG8_LDB(dst, b, h) do { _Pragma("unroll") for (int n = 0; n < 2; ++n) _Pragma("unroll") for (int k = 0; k < 2; ++k) dst[n][k] = *(const PG8_LAS bf16x8*)(lds + PG8_SB(b, h) + boff + n * 2048 + k * 1024); } while (0)
; #define PG8_MMA(ai, bj, At, Bt) do { __builtin_amdgcn_s_setprio(1); _Pragma("unroll") for (int m = 0; m < 4; ++m) _Pragma("unroll") for (int n = 0; n < 2; ++n) _Pragma("unroll") for (int k = 0; k < 2; ++k) \
;         acc[ai][bj][m][n] = __builtin_amdgcn_mfma_f32_16x16x32_bf16(Bt[n][k], At[m][k], acc[ai][bj][m][n], 0, 0, 0); __builtin_amdgcn_s_setprio(0); } while (0)
; #define PG8_WAIT_V(n) asm volatile("s_waitcnt vmcnt(" #n ")" ::: "memory")
; #define PG8_WAIT_L(n) asm volatile("s_waitcnt lgkmcnt(" #n ")" ::: "memory")
; #define PG8_BAR __builtin_amdgcn_s_barrier()
; #define PG8_SCHED __builtin_amdgcn_sched_barrier(0)
; template <class Epi, class Sched, bool ALIGN_EPI = false, bool SP2 = false, bool HALFM = false>
; __device__ __forceinline__ void gemm_phase(PG8_LAS unsigned char* lds, const Gemm g, const Sched& S, const Epi& E) {
;     ...
;             PG8_WAIT_V(8); PG8_WAIT_L(0); PG8_BAR; if constexpr (!HALFM) { PG8_MMA(1, 0, At, B0); PG8_MMA(1, 1, At, B1); } PG8_BAR; PG8_SCHED;
;             PG8_LDB(B0, 1, 0); PG8_LDB(B1, 1, 1); PG8_SCHED; PG8_LDA(At, 1, 0); PG8_STAGE(PG8_SA(0, 1), a2 + hstep, voffA);
;             PG8_WAIT_V(8); PG8_WAIT_L(0); PG8_BAR; PG8_MMA(0, 0, At, B0); PG8_MMA(0, 1, At, B1); PG8_BAR; PG8_SCHED;
	s_setprio 1
	s_waitcnt lgkmcnt(0)
	v_mfma_f32_16x16x32_bf16 v[62:65], v[82:85], v[184:187], v[62:65]
	v_mfma_f32_16x16x32_bf16 v[58:61], v[160:163], v[184:187], v[58:61]
	v_mfma_f32_16x16x32_bf16 v[46:49], v[82:85], v[200:203], v[46:49]
	v_mfma_f32_16x16x32_bf16 v[42:45], v[160:163], v[200:203], v[42:45]
	v_mfma_f32_16x16x32_bf16 v[30:33], v[82:85], v[208:211], v[30:33]
	v_mfma_f32_16x16x32_bf16 v[26:29], v[160:163], v[208:211], v[26:29]
	v_mfma_f32_16x16x32_bf16 v[14:17], v[82:85], v[216:219], v[14:17]
	v_mfma_f32_16x16x32_bf16 v[10:13], v[160:163], v[216:219], v[10:13]
	v_mfma_f32_16x16x32_bf16 v[62:65], v[134:137], v[196:199], v[62:65]
	v_mfma_f32_16x16x32_bf16 v[58:61], v[164:167], v[196:199], v[58:61]
	v_mfma_f32_16x16x32_bf16 v[46:49], v[134:137], v[204:207], v[46:49]
	v_mfma_f32_16x16x32_bf16 v[42:45], v[164:167], v[204:207], v[42:45]
	v_mfma_f32_16x16x32_bf16 v[30:33], v[134:137], v[212:215], v[30:33]
	v_mfma_f32_16x16x32_bf16 v[26:29], v[164:167], v[212:215], v[26:29]
	v_mfma_f32_16x16x32_bf16 v[14:17], v[134:137], v[220:223], v[14:17]
	v_mfma_f32_16x16x32_bf16 v[10:13], v[164:167], v[220:223], v[10:13]
	v_mfma_f32_16x16x32_bf16 v[54:57], v[168:171], v[184:187], v[54:57]
	v_mfma_f32_16x16x32_bf16 v[50:53], v[176:179], v[184:187], v[50:53]
	v_mfma_f32_16x16x32_bf16 v[38:41], v[168:171], v[200:203], v[38:41]
	v_mfma_f32_16x16x32_bf16 v[34:37], v[176:179], v[200:203], v[34:37]
	v_mfma_f32_16x16x32_bf16 v[22:25], v[168:171], v[208:211], v[22:25]
	v_mfma_f32_16x16x32_bf16 v[18:21], v[176:179], v[208:211], v[18:21]
	v_mfma_f32_16x16x32_bf16 v[6:9], v[168:171], v[216:219], v[6:9]
	v_mfma_f32_16x16x32_bf16 v[2:5], v[176:179], v[216:219], v[2:5]
	v_mfma_f32_16x16x32_bf16 v[54:57], v[172:175], v[196:199], v[54:57]
	v_mfma_f32_16x16x32_bf16 v[50:53], v[180:183], v[196:199], v[50:53]
	v_mfma_f32_16x16x32_bf16 v[38:41], v[172:175], v[204:207], v[38:41]
	v_mfma_f32_16x16x32_bf16 v[34:37], v[180:183], v[204:207], v[34:37]
	v_mfma_f32_16x16x32_bf16 v[22:25], v[172:175], v[212:215], v[22:25]
	v_mfma_f32_16x16x32_bf16 v[18:21], v[180:183], v[212:215], v[18:21]
	v_mfma_f32_16x16x32_bf16 v[6:9], v[172:175], v[220:223], v[6:9]
	v_mfma_f32_16x16x32_bf16 v[2:5], v[180:183], v[220:223], v[2:5]
	s_setprio 0
	s_barrier
	s_add_i32 s31, 0, 0x18000
	s_add_i32 s42, 0, 0x1c000
	v_add_u32_e32 v164, s31, v188
	v_add_u32_e32 v180, s42, v188
	ds_read_b128 v[82:85], v164
	ds_read_b128 v[134:137], v164 offset:1024
	ds_read_b128 v[160:163], v164 offset:2048
	ds_read_b128 v[164:167], v164 offset:3072
	ds_read_b128 v[168:171], v180
	ds_read_b128 v[172:175], v180 offset:1024
	ds_read_b128 v[176:179], v180 offset:2048
	ds_read_b128 v[180:183], v180 offset:3072
	s_add_u32 s40, s40, 0x40000
	s_addc_u32 s41, s41, 0
	s_mov_b32 m0, s48
	v_lshl_add_u64 v[232:233], s[40:41], 0, v[138:139]
	ds_read_b128 v[184:187], v192 offset:32768
	ds_read_b128 v[196:199], v192 offset:33792
	ds_read_b128 v[200:203], v192 offset:34816
	ds_read_b128 v[204:207], v192 offset:35840
	ds_read_b128 v[208:211], v192 offset:36864
	ds_read_b128 v[212:215], v192 offset:37888
	ds_read_b128 v[216:219], v192 offset:38912
	ds_read_b128 v[220:223], v192 offset:39936
	global_load_lds_dwordx4 v[232:233], off
	v_lshl_add_u64 v[232:233], s[40:41], 0, v[142:143]
	s_mov_b32 m0, s49
	s_nop 0
	global_load_lds_dwordx4 v[232:233], off
	s_mov_b32 m0, s44
	s_nop 0
	global_load_lds_dwordx4 v[228:229], off
	s_mov_b32 m0, s45
	s_nop 0
	global_load_lds_dwordx4 v[230:231], off
	s_waitcnt vmcnt(10)
	s_waitcnt lgkmcnt(0)
	s_barrier
	s_setprio 1
	s_waitcnt lgkmcnt(0)
	v_mfma_f32_16x16x32_bf16 v[130:133], v[82:85], v[184:187], v[130:133]
	v_mfma_f32_16x16x32_bf16 v[126:129], v[160:163], v[184:187], v[126:129]
	v_mfma_f32_16x16x32_bf16 v[114:117], v[82:85], v[200:203], v[114:117]
	v_mfma_f32_16x16x32_bf16 v[110:113], v[160:163], v[200:203], v[110:113]
	v_mfma_f32_16x16x32_bf16 v[98:101], v[82:85], v[208:211], v[98:101]
	v_mfma_f32_16x16x32_bf16 v[94:97], v[160:163], v[208:211], v[94:97]
	v_mfma_f32_16x16x32_bf16 v[78:81], v[82:85], v[216:219], v[78:81]
	v_mfma_f32_16x16x32_bf16 v[74:77], v[160:163], v[216:219], v[74:77]
	v_mfma_f32_16x16x32_bf16 v[130:133], v[134:137], v[196:199], v[130:133]
	v_mfma_f32_16x16x32_bf16 v[126:129], v[164:167], v[196:199], v[126:129]
	v_mfma_f32_16x16x32_bf16 v[114:117], v[134:137], v[204:207], v[114:117]
	v_mfma_f32_16x16x32_bf16 v[110:113], v[164:167], v[204:207], v[110:113]
	v_mfma_f32_16x16x32_bf16 v[98:101], v[134:137], v[212:215], v[98:101]
	v_mfma_f32_16x16x32_bf16 v[94:97], v[164:167], v[212:215], v[94:97]
	v_mfma_f32_16x16x32_bf16 v[78:81], v[134:137], v[220:223], v[78:81]
	v_mfma_f32_16x16x32_bf16 v[74:77], v[164:167], v[220:223], v[74:77]
	v_mfma_f32_16x16x32_bf16 v[122:125], v[168:171], v[184:187], v[122:125]
	v_mfma_f32_16x16x32_bf16 v[118:121], v[176:179], v[184:187], v[118:121]
	v_mfma_f32_16x16x32_bf16 v[106:109], v[168:171], v[200:203], v[106:109]
	v_mfma_f32_16x16x32_bf16 v[102:105], v[176:179], v[200:203], v[102:105]
	v_mfma_f32_16x16x32_bf16 v[90:93], v[168:171], v[208:211], v[90:93]
	v_mfma_f32_16x16x32_bf16 v[86:89], v[176:179], v[208:211], v[86:89]
	v_mfma_f32_16x16x32_bf16 v[70:73], v[168:171], v[216:219], v[70:73]
	v_mfma_f32_16x16x32_bf16 v[66:69], v[176:179], v[216:219], v[66:69]
	v_mfma_f32_16x16x32_bf16 v[122:125], v[172:175], v[196:199], v[122:125]
	v_mfma_f32_16x16x32_bf16 v[118:121], v[180:183], v[196:199], v[118:121]
	v_mfma_f32_16x16x32_bf16 v[106:109], v[172:175], v[204:207], v[106:109]
	v_mfma_f32_16x16x32_bf16 v[102:105], v[180:183], v[204:207], v[102:105]
	v_mfma_f32_16x16x32_bf16 v[90:93], v[172:175], v[212:215], v[90:93]
	v_mfma_f32_16x16x32_bf16 v[86:89], v[180:183], v[212:215], v[86:89]
	v_mfma_f32_16x16x32_bf16 v[70:73], v[172:175], v[220:223], v[70:73]
	v_mfma_f32_16x16x32_bf16 v[66:69], v[180:183], v[220:223], v[66:69]
	s_setprio 0
	s_barrier
; #define PG8_STAGE(bufoff, gbase, voff) do { _Pragma("unroll") for (int _i = 0; _i < 2; ++_i) \
;         __builtin_amdgcn_global_load_lds((const unsigned*)((const char*)(gbase) + (voff)[_i]), (PG8_LAS unsigned*)(lds + (bufoff) + ldsw + _i * 8192), 16, 0, 0); } while (0)
; #define PG8_LDA(dst, b, h) do { _Pragma("unroll") for (int m = 0; m < 4; ++m) _Pragma("unroll") for (int k = 0; k < 2; ++k) dst[m][k] = *(const PG8_LAS bf16x8*)(lds + PG8_SA(b, h) + aoff + m * 2048 + k * 1024); } while (0)
; #define PG8_MMA(ai, bj, At, Bt) do { __builtin_amdgcn_s_setprio(1); _Pragma("unroll") for (int m = 0; m < 4; ++m) _Pragma("unroll") for (int n = 0; n < 2; ++n) _Pragma("unroll") for (int k = 0; k < 2; ++k) \
;         acc[ai][bj][m][n] = __builtin_amdgcn_mfma_f32_16x16x32_bf16(Bt[n][k], At[m][k], acc[ai][bj][m][n], 0, 0, 0); __builtin_amdgcn_s_setprio(0); } while (0)
; #define PG8_WAIT_V(n) asm volatile("s_waitcnt vmcnt(" #n ")" ::: "memory")
; #define PG8_WAIT_L(n) asm volatile("s_waitcnt lgkmcnt(" #n ")" ::: "memory")
; #define PG8_BAR __builtin_amdgcn_s_barrier()
; #define PG8_SCHED __builtin_amdgcn_sched_barrier(0)
; template <class Epi, class Sched, bool ALIGN_EPI = false, bool SP2 = false, bool HALFM = false>
; __device__ __forceinline__ void gemm_phase(PG8_LAS unsigned char* lds, const Gemm g, const Sched& S, const Epi& E) {
;     ...
;             PG8_LDA(At, 1, 1); PG8_STAGE(PG8_SB(1, 0), b3, voffB); PG8_STAGE(PG8_SB(1, 1), b3 + hstep, voffB); PG8_STAGE(PG8_SA(1, 0), a3, voffA);
;             PG8_WAIT_V(8); PG8_WAIT_L(0); PG8_BAR; if constexpr (!HALFM) { PG8_MMA(1, 0, At, B0); PG8_MMA(1, 1, At, B1); } PG8_BAR; PG8_SCHED;
	s_add_i32 s31, s31, s27
	v_lshl_add_u64 v[224:225], v[224:225], 0, s[20:21]
	s_mov_b32 m0, s31
	ds_read_b128 v[184:187], v192 offset:49152
	ds_read_b128 v[196:199], v192 offset:50176
	ds_read_b128 v[200:203], v192 offset:51200
	ds_read_b128 v[204:207], v192 offset:52224
	ds_read_b128 v[208:211], v192 offset:53248
	ds_read_b128 v[212:215], v192 offset:54272
	ds_read_b128 v[216:219], v192 offset:55296
	ds_read_b128 v[220:223], v192 offset:56320
	global_load_lds_dwordx4 v[224:225], off
	s_add_i32 m0, s31, 0x2000
	s_add_u32 s38, s38, 0x40080
	v_lshl_add_u64 v[224:225], v[226:227], 0, s[20:21]
	s_addc_u32 s39, s39, 0
	s_add_i32 s31, s42, s27
	global_load_lds_dwordx4 v[224:225], off
	v_lshl_add_u64 v[224:225], s[38:39], 0, v[140:141]
	s_mov_b32 m0, s31
	s_nop 0
	global_load_lds_dwordx4 v[224:225], off
	v_lshl_add_u64 v[224:225], s[38:39], 0, v[144:145]
	s_add_i32 m0, s31, 0x2000
	s_nop 0
	global_load_lds_dwordx4 v[224:225], off
	s_waitcnt vmcnt(4)
	s_waitcnt lgkmcnt(0)
	s_barrier
	s_setprio 1
	s_waitcnt lgkmcnt(0)
	v_mfma_f32_16x16x32_bf16 v[62:65], v[82:85], v[184:187], v[62:65]
	v_mfma_f32_16x16x32_bf16 v[58:61], v[160:163], v[184:187], v[58:61]
	v_mfma_f32_16x16x32_bf16 v[46:49], v[82:85], v[200:203], v[46:49]
	v_mfma_f32_16x16x32_bf16 v[42:45], v[160:163], v[200:203], v[42:45]
	v_mfma_f32_16x16x32_bf16 v[30:33], v[82:85], v[208:211], v[30:33]
	v_mfma_f32_16x16x32_bf16 v[26:29], v[160:163], v[208:211], v[26:29]
	v_mfma_f32_16x16x32_bf16 v[14:17], v[82:85], v[216:219], v[14:17]
	v_mfma_f32_16x16x32_bf16 v[10:13], v[160:163], v[216:219], v[10:13]
	v_mfma_f32_16x16x32_bf16 v[62:65], v[134:137], v[196:199], v[62:65]
	v_mfma_f32_16x16x32_bf16 v[58:61], v[164:167], v[196:199], v[58:61]
	v_mfma_f32_16x16x32_bf16 v[46:49], v[134:137], v[204:207], v[46:49]
	v_mfma_f32_16x16x32_bf16 v[42:45], v[164:167], v[204:207], v[42:45]
	v_mfma_f32_16x16x32_bf16 v[30:33], v[134:137], v[212:215], v[30:33]
	v_mfma_f32_16x16x32_bf16 v[26:29], v[164:167], v[212:215], v[26:29]
	v_mfma_f32_16x16x32_bf16 v[14:17], v[134:137], v[220:223], v[14:17]
	v_mfma_f32_16x16x32_bf16 v[10:13], v[164:167], v[220:223], v[10:13]
	v_mfma_f32_16x16x32_bf16 v[54:57], v[168:171], v[184:187], v[54:57]
	v_mfma_f32_16x16x32_bf16 v[50:53], v[176:179], v[184:187], v[50:53]
	v_mfma_f32_16x16x32_bf16 v[38:41], v[168:171], v[200:203], v[38:41]
	v_mfma_f32_16x16x32_bf16 v[34:37], v[176:179], v[200:203], v[34:37]
	v_mfma_f32_16x16x32_bf16 v[22:25], v[168:171], v[208:211], v[22:25]
	v_mfma_f32_16x16x32_bf16 v[18:21], v[176:179], v[208:211], v[18:21]
	v_mfma_f32_16x16x32_bf16 v[6:9], v[168:171], v[216:219], v[6:9]
	v_mfma_f32_16x16x32_bf16 v[2:5], v[176:179], v[216:219], v[2:5]
	v_mfma_f32_16x16x32_bf16 v[54:57], v[172:175], v[196:199], v[54:57]
	v_mfma_f32_16x16x32_bf16 v[50:53], v[180:183], v[196:199], v[50:53]
	v_mfma_f32_16x16x32_bf16 v[38:41], v[172:175], v[204:207], v[38:41]
	v_mfma_f32_16x16x32_bf16 v[34:37], v[180:183], v[204:207], v[34:37]
	v_mfma_f32_16x16x32_bf16 v[22:25], v[172:175], v[212:215], v[22:25]
	v_mfma_f32_16x16x32_bf16 v[18:21], v[180:183], v[212:215], v[18:21]
	v_mfma_f32_16x16x32_bf16 v[6:9], v[172:175], v[220:223], v[6:9]
	v_mfma_f32_16x16x32_bf16 v[2:5], v[180:183], v[220:223], v[2:5]
	s_setprio 0
	s_barrier
	s_add_i32 s29, s29, 2
	s_add_u32 s8, s8, 0x100
	s_addc_u32 s9, s9, 0
	s_add_u32 s5, s5, 0x100
	s_addc_u32 s11, s11, 0
	s_cmp_gt_u32 s29, 13
	s_cbranch_scc0 .LBB0_752
	s_and_b64 vcc, exec, s[22:23]
	s_cbranch_vccnz .LBB0_757
	s_cmp_gt_i32 s10, 45
	s_mov_b64 s[8:9], -1
	s_cbranch_scc1 .LBB0_758

; #define PG8_STAGE(bufoff, gbase, voff) do { _Pragma("unroll") for (int _i = 0; _i < 2; ++_i) \
;         __builtin_amdgcn_global_load_lds((const unsigned*)((const char*)(gbase) + (voff)[_i]), (PG8_LAS unsigned*)(lds + (bufoff) + ldsw + _i * 8192), 16, 0, 0); } while (0)
; #define PG8_LDA(dst, b, h) do { _Pragma("unroll") for (int m = 0; m < 4; ++m) _Pragma("unroll") for (int k = 0; k < 2; ++k) dst[m][k] = *(const PG8_LAS bf16x8*)(lds + PG8_SA(b, h) + aoff + m * 2048 + k * 1024); } while (0)
; #define PG8_LDB(dst, b, h) do { _Pragma("unroll") for (int n = 0; n < 2; ++n) _Pragma("unroll") for (int k = 0; k < 2; ++k) dst[n][k] = *(const PG8_LAS bf16x8*)(lds + PG8_SB(b, h) + boff + n * 2048 + k * 1024); } while (0)
; #define PG8_MMA(ai, bj, At, Bt) do { __builtin_amdgcn_s_setprio(1); _Pragma("unroll") for (int m = 0; m < 4; ++m) _Pragma("unroll") for (int n = 0; n < 2; ++n) _Pragma("unroll") for (int k = 0; k < 2; ++k) \
;         acc[ai][bj][m][n] = __builtin_amdgcn_mfma_f32_16x16x32_bf16(Bt[n][k], At[m][k], acc[ai][bj][m][n], 0, 0, 0); __builtin_amdgcn_s_setprio(0); } while (0)
; #define PG8_WAIT_V(n) asm volatile("s_waitcnt vmcnt(" #n ")" ::: "memory")
; #define PG8_BAR __builtin_amdgcn_s_barrier()
; template <class Epi, class Sched, bool ALIGN_EPI = false, bool SP2 = false, bool HALFM = false>
; __device__ __forceinline__ void gemm_phase(PG8_LAS unsigned char* lds, const Gemm g, const Sched& S, const Epi& E) {
;     ...
;             const bool last = (t == nt - 2);
;             const char* a1 = cA + (size_t)(t + 1) * kstep;
;             const char* a2 = last ? nA : cA + (size_t)(t + 2) * kstep; const char* b2 = last ? nB : cB + (size_t)(t + 2) * kstep;
;             const char* a3 = a2 + kstep; const char* b3 = b2 + kstep;
;             if (last && has_next) S.a_ready(nxt);
;             if constexpr (SP2) {
;             PG8_LDB(B0, 0, 0); PG8_LDB(B1, 0, 1); PG8_SCHED; PG8_LDA(At, 0, 0); PG8_STAGE(PG8_SA(1, 1), a1 + hstep, voffA);
;             PG8_WAIT_V(8); PG8_WAIT_L(0); PG8_BAR; PG8_MMA(0, 0, At, B0); PG8_MMA(0, 1, At, B1); PG8_BAR; PG8_SCHED;
;             PG8_LDA(At, 0, 1); PG8_STAGE(PG8_SB(0, 0), b2, voffB); PG8_STAGE(PG8_SB(0, 1), b2 + hstep, voffB); PG8_STAGE(PG8_SA(0, 0), a2, voffA);
;             PG8_WAIT_V(8); PG8_WAIT_L(0); PG8_BAR; if constexpr (!HALFM) { PG8_MMA(1, 0, At, B0); PG8_MMA(1, 1, At, B1); } PG8_BAR; PG8_SCHED;
.LBB0_1510:
	ds_read_b128 v[130:133], v196
	ds_read_b128 v[134:137], v196 offset:1024
	ds_read_b128 v[138:141], v196 offset:2048
	ds_read_b128 v[142:145], v196 offset:3072
	ds_read_b128 v[146:149], v197
	ds_read_b128 v[150:153], v197 offset:1024
	ds_read_b128 v[154:157], v197 offset:2048
	ds_read_b128 v[158:161], v197 offset:3072
	s_add_u32 s42, s40, 0xfff80080
	s_addc_u32 s43, s41, -1
	s_cmp_eq_u32 s61, 28
	s_cselect_b32 s45, s35, s43
	s_cselect_b32 s44, s57, s42
	s_cselect_b32 s43, s31, s60
	s_cselect_b32 s42, s58, s59
	v_lshl_add_u64 v[216:217], s[40:41], 0, v[174:175]
	s_add_i32 m0, s1, 0xc000
	ds_read_b128 v[162:165], v198
	ds_read_b128 v[182:185], v198 offset:1024
	ds_read_b128 v[186:189], v198 offset:2048
	ds_read_b128 v[190:193], v198 offset:3072
	ds_read_b128 v[200:203], v198 offset:4096
	ds_read_b128 v[204:207], v198 offset:5120
	ds_read_b128 v[208:211], v198 offset:6144
	ds_read_b128 v[212:215], v198 offset:7168
	global_load_lds_dwordx4 v[216:217], off
	v_lshl_add_u64 v[216:217], s[40:41], 0, v[176:177]
	s_add_i32 m0, s1, 0xe000
	s_nop 0
	global_load_lds_dwordx4 v[216:217], off
	s_mov_b32 m0, s47
	v_lshl_add_u64 v[216:217], v[220:221], 0, s[18:19]
	global_load_lds_dwordx4 v[216:217], off
	s_mov_b32 m0, s48
	v_lshl_add_u64 v[216:217], v[222:223], 0, s[18:19]
	global_load_lds_dwordx4 v[216:217], off
	s_waitcnt vmcnt(10)
	s_waitcnt lgkmcnt(0)
	s_barrier
	s_setprio 1
	s_waitcnt lgkmcnt(0)
	v_mfma_f32_16x16x32_bf16 v[126:129], v[130:133], v[162:165], v[126:129]
	v_mfma_f32_16x16x32_bf16 v[122:125], v[138:141], v[162:165], v[122:125]
	v_mfma_f32_16x16x32_bf16 v[114:117], v[130:133], v[186:189], v[114:117]
	v_mfma_f32_16x16x32_bf16 v[106:109], v[138:141], v[186:189], v[106:109]
	v_mfma_f32_16x16x32_bf16 v[98:101], v[130:133], v[200:203], v[98:101]
	v_mfma_f32_16x16x32_bf16 v[90:93], v[138:141], v[200:203], v[90:93]
	v_mfma_f32_16x16x32_bf16 v[82:85], v[130:133], v[208:211], v[82:85]
	v_mfma_f32_16x16x32_bf16 v[74:77], v[138:141], v[208:211], v[74:77]
	v_mfma_f32_16x16x32_bf16 v[126:129], v[134:137], v[182:185], v[126:129]
	v_mfma_f32_16x16x32_bf16 v[122:125], v[142:145], v[182:185], v[122:125]
	v_mfma_f32_16x16x32_bf16 v[114:117], v[134:137], v[190:193], v[114:117]
	v_mfma_f32_16x16x32_bf16 v[106:109], v[142:145], v[190:193], v[106:109]
	v_mfma_f32_16x16x32_bf16 v[98:101], v[134:137], v[204:207], v[98:101]
	v_mfma_f32_16x16x32_bf16 v[90:93], v[142:145], v[204:207], v[90:93]
	v_mfma_f32_16x16x32_bf16 v[82:85], v[134:137], v[212:215], v[82:85]
	v_mfma_f32_16x16x32_bf16 v[74:77], v[142:145], v[212:215], v[74:77]
	v_mfma_f32_16x16x32_bf16 v[118:121], v[146:149], v[162:165], v[118:121]
	v_mfma_f32_16x16x32_bf16 v[110:113], v[154:157], v[162:165], v[110:113]
	v_mfma_f32_16x16x32_bf16 v[102:105], v[146:149], v[186:189], v[102:105]
	v_mfma_f32_16x16x32_bf16 v[94:97], v[154:157], v[186:189], v[94:97]
	v_mfma_f32_16x16x32_bf16 v[86:89], v[146:149], v[200:203], v[86:89]
	v_mfma_f32_16x16x32_bf16 v[78:81], v[154:157], v[200:203], v[78:81]
	v_mfma_f32_16x16x32_bf16 v[70:73], v[146:149], v[208:211], v[70:73]
	v_mfma_f32_16x16x32_bf16 v[66:69], v[154:157], v[208:211], v[66:69]
	v_mfma_f32_16x16x32_bf16 v[118:121], v[150:153], v[182:185], v[118:121]
	v_mfma_f32_16x16x32_bf16 v[110:113], v[158:161], v[182:185], v[110:113]
	v_mfma_f32_16x16x32_bf16 v[102:105], v[150:153], v[190:193], v[102:105]
	v_mfma_f32_16x16x32_bf16 v[94:97], v[158:161], v[190:193], v[94:97]
	v_mfma_f32_16x16x32_bf16 v[86:89], v[150:153], v[204:207], v[86:89]
	v_mfma_f32_16x16x32_bf16 v[78:81], v[158:161], v[204:207], v[78:81]
	v_mfma_f32_16x16x32_bf16 v[70:73], v[150:153], v[212:215], v[70:73]
	v_mfma_f32_16x16x32_bf16 v[66:69], v[158:161], v[212:215], v[66:69]
	s_setprio 0
	s_barrier
	s_add_i32 s62, s50, s0
	v_lshl_add_u64 v[216:217], s[42:43], 0, v[168:169]
	s_mov_b32 m0, s62
	ds_read_b128 v[162:165], v198 offset:16384
	ds_read_b128 v[182:185], v198 offset:17408
	ds_read_b128 v[186:189], v198 offset:18432
	ds_read_b128 v[190:193], v198 offset:19456
	ds_read_b128 v[200:203], v198 offset:20480
	ds_read_b128 v[204:207], v198 offset:21504
	ds_read_b128 v[208:211], v198 offset:22528
	ds_read_b128 v[212:215], v198 offset:23552
	global_load_lds_dwordx4 v[216:217], off
	s_add_i32 m0, s62, 0x2000
	s_add_u32 s62, s42, 0x80000
	v_lshl_add_u64 v[218:219], s[42:43], 0, v[172:173]
	s_addc_u32 s63, s43, 0
	s_add_i32 s64, s51, s0
	global_load_lds_dwordx4 v[218:219], off
	v_lshl_add_u64 v[220:221], s[62:63], 0, v[168:169]
	s_mov_b32 m0, s64
	v_lshl_add_u64 v[222:223], s[44:45], 0, v[170:171]
	global_load_lds_dwordx4 v[220:221], off
	v_lshl_add_u64 v[220:221], s[62:63], 0, v[172:173]
	s_add_i32 m0, s64, 0x2000
	s_nop 0
	global_load_lds_dwordx4 v[220:221], off
	v_lshl_add_u64 v[220:221], s[44:45], 0, v[166:167]
	s_waitcnt vmcnt(4)
	s_waitcnt lgkmcnt(0)
	s_barrier
; #define PG8_STAGE(bufoff, gbase, voff) do { _Pragma("unroll") for (int _i = 0; _i < 2; ++_i) \
;         __builtin_amdgcn_global_load_lds((const unsigned*)((const char*)(gbase) + (voff)[_i]), (PG8_LAS unsigned*)(lds + (bufoff) + ldsw + _i * 8192), 16, 0, 0); } while (0)
; #define PG8_LDA(dst, b, h) do { _Pragma("unroll") for (int m = 0; m < 4; ++m) _Pragma("unroll") for (int k = 0; k < 2; ++k) dst[m][k] = *(const PG8_LAS bf16x8*)(lds + PG8_SA(b, h) + aoff + m * 2048 + k * 1024); } while (0)
; #define PG8_LDB(dst, b, h) do { _Pragma("unroll") for (int n = 0; n < 2; ++n) _Pragma("unroll") for (int k = 0; k < 2; ++k) dst[n][k] = *(const PG8_LAS bf16x8*)(lds + PG8_SB(b, h) + boff + n * 2048 + k * 1024); } while (0)
; #define PG8_MMA(ai, bj, At, Bt) do { __builtin_amdgcn_s_setprio(1); _Pragma("unroll") for (int m = 0; m < 4; ++m) _Pragma("unroll") for (int n = 0; n < 2; ++n) _Pragma("unroll") for (int k = 0; k < 2; ++k) \
;         acc[ai][bj][m][n] = __builtin_amdgcn_mfma_f32_16x16x32_bf16(Bt[n][k], At[m][k], acc[ai][bj][m][n], 0, 0, 0); __builtin_amdgcn_s_setprio(0); } while (0)
; #define PG8_WAIT_V(n) asm volatile("s_waitcnt vmcnt(" #n ")" ::: "memory")
; #define PG8_WAIT_L(n) asm volatile("s_waitcnt lgkmcnt(" #n ")" ::: "memory")
; #define PG8_BAR __builtin_amdgcn_s_barrier()
; #define PG8_SCHED __builtin_amdgcn_sched_barrier(0)
; template <class Epi, class Sched, bool ALIGN_EPI = false, bool SP2 = false, bool HALFM = false>
; __device__ __forceinline__ void gemm_phase(PG8_LAS unsigned char* lds, const Gemm g, const Sched& S, const Epi& E) {
;     ...
;             PG8_WAIT_V(8); PG8_WAIT_L(0); PG8_BAR; if constexpr (!HALFM) { PG8_MMA(1, 0, At, B0); PG8_MMA(1, 1, At, B1); } PG8_BAR; PG8_SCHED;
;             PG8_LDB(B0, 1, 0); PG8_LDB(B1, 1, 1); PG8_SCHED; PG8_LDA(At, 1, 0); PG8_STAGE(PG8_SA(0, 1), a2 + hstep, voffA);
;             PG8_WAIT_V(8); PG8_WAIT_L(0); PG8_BAR; PG8_MMA(0, 0, At, B0); PG8_MMA(0, 1, At, B1); PG8_BAR; PG8_SCHED;
	s_setprio 1
	s_waitcnt lgkmcnt(0)
	v_mfma_f32_16x16x32_bf16 v[62:65], v[130:133], v[162:165], v[62:65]
	v_mfma_f32_16x16x32_bf16 v[58:61], v[138:141], v[162:165], v[58:61]
	v_mfma_f32_16x16x32_bf16 v[50:53], v[130:133], v[186:189], v[50:53]
	v_mfma_f32_16x16x32_bf16 v[42:45], v[138:141], v[186:189], v[42:45]
	v_mfma_f32_16x16x32_bf16 v[34:37], v[130:133], v[200:203], v[34:37]
	v_mfma_f32_16x16x32_bf16 v[26:29], v[138:141], v[200:203], v[26:29]
	v_mfma_f32_16x16x32_bf16 v[18:21], v[130:133], v[208:211], v[18:21]
	v_mfma_f32_16x16x32_bf16 v[10:13], v[138:141], v[208:211], v[10:13]
	v_mfma_f32_16x16x32_bf16 v[62:65], v[134:137], v[182:185], v[62:65]
	v_mfma_f32_16x16x32_bf16 v[58:61], v[142:145], v[182:185], v[58:61]
	v_mfma_f32_16x16x32_bf16 v[50:53], v[134:137], v[190:193], v[50:53]
	v_mfma_f32_16x16x32_bf16 v[42:45], v[142:145], v[190:193], v[42:45]
	v_mfma_f32_16x16x32_bf16 v[34:37], v[134:137], v[204:207], v[34:37]
	v_mfma_f32_16x16x32_bf16 v[26:29], v[142:145], v[204:207], v[26:29]
	v_mfma_f32_16x16x32_bf16 v[18:21], v[134:137], v[212:215], v[18:21]
	v_mfma_f32_16x16x32_bf16 v[10:13], v[142:145], v[212:215], v[10:13]
	v_mfma_f32_16x16x32_bf16 v[54:57], v[146:149], v[162:165], v[54:57]
	v_mfma_f32_16x16x32_bf16 v[46:49], v[154:157], v[162:165], v[46:49]
	v_mfma_f32_16x16x32_bf16 v[38:41], v[146:149], v[186:189], v[38:41]
	v_mfma_f32_16x16x32_bf16 v[30:33], v[154:157], v[186:189], v[30:33]
	v_mfma_f32_16x16x32_bf16 v[22:25], v[146:149], v[200:203], v[22:25]
	v_mfma_f32_16x16x32_bf16 v[14:17], v[154:157], v[200:203], v[14:17]
	v_mfma_f32_16x16x32_bf16 v[6:9], v[146:149], v[208:211], v[6:9]
	v_mfma_f32_16x16x32_bf16 v[2:5], v[154:157], v[208:211], v[2:5]
	v_mfma_f32_16x16x32_bf16 v[54:57], v[150:153], v[182:185], v[54:57]
	v_mfma_f32_16x16x32_bf16 v[46:49], v[158:161], v[182:185], v[46:49]
	v_mfma_f32_16x16x32_bf16 v[38:41], v[150:153], v[190:193], v[38:41]
	v_mfma_f32_16x16x32_bf16 v[30:33], v[158:161], v[190:193], v[30:33]
	v_mfma_f32_16x16x32_bf16 v[22:25], v[150:153], v[204:207], v[22:25]
	v_mfma_f32_16x16x32_bf16 v[14:17], v[158:161], v[204:207], v[14:17]
	v_mfma_f32_16x16x32_bf16 v[6:9], v[150:153], v[212:215], v[6:9]
	v_mfma_f32_16x16x32_bf16 v[2:5], v[158:161], v[212:215], v[2:5]
	s_setprio 0
	s_barrier
	s_add_i32 s62, 0, 0x18000
	s_add_i32 s63, 0, 0x1c000
	v_add_u32_e32 v142, s62, v194
	v_add_u32_e32 v158, s63, v194
	ds_read_b128 v[130:133], v142
	ds_read_b128 v[134:137], v142 offset:1024
	ds_read_b128 v[138:141], v142 offset:2048
	ds_read_b128 v[142:145], v142 offset:3072
	ds_read_b128 v[146:149], v158
	ds_read_b128 v[150:153], v158 offset:1024
	ds_read_b128 v[154:157], v158 offset:2048
	ds_read_b128 v[158:161], v158 offset:3072
	s_add_u32 s44, s44, 0x80000
	s_addc_u32 s45, s45, 0
	s_mov_b32 m0, s3
	v_lshl_add_u64 v[224:225], s[44:45], 0, v[166:167]
	ds_read_b128 v[162:165], v198 offset:32768
	ds_read_b128 v[182:185], v198 offset:33792
	ds_read_b128 v[186:189], v198 offset:34816
	ds_read_b128 v[190:193], v198 offset:35840
	ds_read_b128 v[200:203], v198 offset:36864
	ds_read_b128 v[204:207], v198 offset:37888
	ds_read_b128 v[208:211], v198 offset:38912
	ds_read_b128 v[212:215], v198 offset:39936
	global_load_lds_dwordx4 v[224:225], off
	v_lshl_add_u64 v[224:225], s[44:45], 0, v[170:171]
	s_mov_b32 m0, s46
	s_nop 0
	global_load_lds_dwordx4 v[224:225], off
	s_mov_b32 m0, s1
	s_nop 0
	global_load_lds_dwordx4 v[220:221], off
	s_mov_b32 m0, s2
	s_nop 0
	global_load_lds_dwordx4 v[222:223], off
	s_waitcnt vmcnt(10)
	s_waitcnt lgkmcnt(0)
	s_barrier
; #define PG8_STAGE(bufoff, gbase, voff) do { _Pragma("unroll") for (int _i = 0; _i < 2; ++_i) \
;         __builtin_amdgcn_global_load_lds((const unsigned*)((const char*)(gbase) + (voff)[_i]), (PG8_LAS unsigned*)(lds + (bufoff) + ldsw + _i * 8192), 16, 0, 0); } while (0)
; #define PG8_LDA(dst, b, h) do { _Pragma("unroll") for (int m = 0; m < 4; ++m) _Pragma("unroll") for (int k = 0; k < 2; ++k) dst[m][k] = *(const PG8_LAS bf16x8*)(lds + PG8_SA(b, h) + aoff + m * 2048 + k * 1024); } while (0)
; #define PG8_MMA(ai, bj, At, Bt) do { __builtin_amdgcn_s_setprio(1); _Pragma("unroll") for (int m = 0; m < 4; ++m) _Pragma("unroll") for (int n = 0; n < 2; ++n) _Pragma("unroll") for (int k = 0; k < 2; ++k) \
;         acc[ai][bj][m][n] = __builtin_amdgcn_mfma_f32_16x16x32_bf16(Bt[n][k], At[m][k], acc[ai][bj][m][n], 0, 0, 0); __builtin_amdgcn_s_setprio(0); } while (0)
; #define PG8_WAIT_V(n) asm volatile("s_waitcnt vmcnt(" #n ")" ::: "memory")
; #define PG8_WAIT_L(n) asm volatile("s_waitcnt lgkmcnt(" #n ")" ::: "memory")
; #define PG8_BAR __builtin_amdgcn_s_barrier()
; #define PG8_SCHED __builtin_amdgcn_sched_barrier(0)
; template <class Epi, class Sched, bool ALIGN_EPI = false, bool SP2 = false, bool HALFM = false>
; __device__ __forceinline__ void gemm_phase(PG8_LAS unsigned char* lds, const Gemm g, const Sched& S, const Epi& E) {
;     ...
;             PG8_WAIT_V(8); PG8_WAIT_L(0); PG8_BAR; PG8_MMA(0, 0, At, B0); PG8_MMA(0, 1, At, B1); PG8_BAR; PG8_SCHED;
;             PG8_LDA(At, 1, 1); PG8_STAGE(PG8_SB(1, 0), b3, voffB); PG8_STAGE(PG8_SB(1, 1), b3 + hstep, voffB); PG8_STAGE(PG8_SA(1, 0), a3, voffA);
;             PG8_WAIT_V(8); PG8_WAIT_L(0); PG8_BAR; if constexpr (!HALFM) { PG8_MMA(1, 0, At, B0); PG8_MMA(1, 1, At, B1); } PG8_BAR; PG8_SCHED;
	s_setprio 1
	s_waitcnt lgkmcnt(0)
	v_mfma_f32_16x16x32_bf16 v[126:129], v[130:133], v[162:165], v[126:129]
	v_mfma_f32_16x16x32_bf16 v[122:125], v[138:141], v[162:165], v[122:125]
	v_mfma_f32_16x16x32_bf16 v[114:117], v[130:133], v[186:189], v[114:117]
	v_mfma_f32_16x16x32_bf16 v[106:109], v[138:141], v[186:189], v[106:109]
	v_mfma_f32_16x16x32_bf16 v[98:101], v[130:133], v[200:203], v[98:101]
	v_mfma_f32_16x16x32_bf16 v[90:93], v[138:141], v[200:203], v[90:93]
	v_mfma_f32_16x16x32_bf16 v[82:85], v[130:133], v[208:211], v[82:85]
	v_mfma_f32_16x16x32_bf16 v[74:77], v[138:141], v[208:211], v[74:77]
	v_mfma_f32_16x16x32_bf16 v[126:129], v[134:137], v[182:185], v[126:129]
	v_mfma_f32_16x16x32_bf16 v[122:125], v[142:145], v[182:185], v[122:125]
	v_mfma_f32_16x16x32_bf16 v[114:117], v[134:137], v[190:193], v[114:117]
	v_mfma_f32_16x16x32_bf16 v[106:109], v[142:145], v[190:193], v[106:109]
	v_mfma_f32_16x16x32_bf16 v[98:101], v[134:137], v[204:207], v[98:101]
	v_mfma_f32_16x16x32_bf16 v[90:93], v[142:145], v[204:207], v[90:93]
	v_mfma_f32_16x16x32_bf16 v[82:85], v[134:137], v[212:215], v[82:85]
	v_mfma_f32_16x16x32_bf16 v[74:77], v[142:145], v[212:215], v[74:77]
	v_mfma_f32_16x16x32_bf16 v[118:121], v[146:149], v[162:165], v[118:121]
	v_mfma_f32_16x16x32_bf16 v[110:113], v[154:157], v[162:165], v[110:113]
	v_mfma_f32_16x16x32_bf16 v[102:105], v[146:149], v[186:189], v[102:105]
	v_mfma_f32_16x16x32_bf16 v[94:97], v[154:157], v[186:189], v[94:97]
	v_mfma_f32_16x16x32_bf16 v[86:89], v[146:149], v[200:203], v[86:89]
	v_mfma_f32_16x16x32_bf16 v[78:81], v[154:157], v[200:203], v[78:81]
	v_mfma_f32_16x16x32_bf16 v[70:73], v[146:149], v[208:211], v[70:73]
	v_mfma_f32_16x16x32_bf16 v[66:69], v[154:157], v[208:211], v[66:69]
	v_mfma_f32_16x16x32_bf16 v[118:121], v[150:153], v[182:185], v[118:121]
	v_mfma_f32_16x16x32_bf16 v[110:113], v[158:161], v[182:185], v[110:113]
	v_mfma_f32_16x16x32_bf16 v[102:105], v[150:153], v[190:193], v[102:105]
	v_mfma_f32_16x16x32_bf16 v[94:97], v[158:161], v[190:193], v[94:97]
	v_mfma_f32_16x16x32_bf16 v[86:89], v[150:153], v[204:207], v[86:89]
	v_mfma_f32_16x16x32_bf16 v[78:81], v[158:161], v[204:207], v[78:81]
	v_mfma_f32_16x16x32_bf16 v[70:73], v[150:153], v[212:215], v[70:73]
	v_mfma_f32_16x16x32_bf16 v[66:69], v[158:161], v[212:215], v[66:69]
	s_setprio 0
	s_barrier
	s_add_i32 s44, s62, s0
	v_lshl_add_u64 v[216:217], v[216:217], 0, s[18:19]
	s_mov_b32 m0, s44
	ds_read_b128 v[162:165], v198 offset:49152
	ds_read_b128 v[182:185], v198 offset:50176
	ds_read_b128 v[186:189], v198 offset:51200
	ds_read_b128 v[190:193], v198 offset:52224
	ds_read_b128 v[200:203], v198 offset:53248
	ds_read_b128 v[204:207], v198 offset:54272
	ds_read_b128 v[208:211], v198 offset:55296
	ds_read_b128 v[212:215], v198 offset:56320
	global_load_lds_dwordx4 v[216:217], off
	s_add_i32 m0, s44, 0x2000
	s_add_u32 s42, s42, 0x80080
	v_lshl_add_u64 v[216:217], v[218:219], 0, s[18:19]
	s_addc_u32 s43, s43, 0
	s_add_i32 s44, s63, s0
	global_load_lds_dwordx4 v[216:217], off
	v_lshl_add_u64 v[216:217], s[42:43], 0, v[168:169]
	s_mov_b32 m0, s44
	s_nop 0
	global_load_lds_dwordx4 v[216:217], off
	v_lshl_add_u64 v[216:217], s[42:43], 0, v[172:173]
	s_add_i32 m0, s44, 0x2000
	s_nop 0
	global_load_lds_dwordx4 v[216:217], off
	s_waitcnt vmcnt(4)
	s_waitcnt lgkmcnt(0)
	s_barrier
	s_setprio 1
	s_waitcnt lgkmcnt(0)
	v_mfma_f32_16x16x32_bf16 v[62:65], v[130:133], v[162:165], v[62:65]
	v_mfma_f32_16x16x32_bf16 v[58:61], v[138:141], v[162:165], v[58:61]
	v_mfma_f32_16x16x32_bf16 v[50:53], v[130:133], v[186:189], v[50:53]
	v_mfma_f32_16x16x32_bf16 v[42:45], v[138:141], v[186:189], v[42:45]
	v_mfma_f32_16x16x32_bf16 v[34:37], v[130:133], v[200:203], v[34:37]
	v_mfma_f32_16x16x32_bf16 v[26:29], v[138:141], v[200:203], v[26:29]
	v_mfma_f32_16x16x32_bf16 v[18:21], v[130:133], v[208:211], v[18:21]
	v_mfma_f32_16x16x32_bf16 v[10:13], v[138:141], v[208:211], v[10:13]
	v_mfma_f32_16x16x32_bf16 v[62:65], v[134:137], v[182:185], v[62:65]
	v_mfma_f32_16x16x32_bf16 v[58:61], v[142:145], v[182:185], v[58:61]
	v_mfma_f32_16x16x32_bf16 v[50:53], v[134:137], v[190:193], v[50:53]
	v_mfma_f32_16x16x32_bf16 v[42:45], v[142:145], v[190:193], v[42:45]
	v_mfma_f32_16x16x32_bf16 v[34:37], v[134:137], v[204:207], v[34:37]
	v_mfma_f32_16x16x32_bf16 v[26:29], v[142:145], v[204:207], v[26:29]
	v_mfma_f32_16x16x32_bf16 v[18:21], v[134:137], v[212:215], v[18:21]
	v_mfma_f32_16x16x32_bf16 v[10:13], v[142:145], v[212:215], v[10:13]
	v_mfma_f32_16x16x32_bf16 v[54:57], v[146:149], v[162:165], v[54:57]
	v_mfma_f32_16x16x32_bf16 v[46:49], v[154:157], v[162:165], v[46:49]
	v_mfma_f32_16x16x32_bf16 v[38:41], v[146:149], v[186:189], v[38:41]
	v_mfma_f32_16x16x32_bf16 v[30:33], v[154:157], v[186:189], v[30:33]
	v_mfma_f32_16x16x32_bf16 v[22:25], v[146:149], v[200:203], v[22:25]
	v_mfma_f32_16x16x32_bf16 v[14:17], v[154:157], v[200:203], v[14:17]
	v_mfma_f32_16x16x32_bf16 v[6:9], v[146:149], v[208:211], v[6:9]
	v_mfma_f32_16x16x32_bf16 v[2:5], v[154:157], v[208:211], v[2:5]
	v_mfma_f32_16x16x32_bf16 v[54:57], v[150:153], v[182:185], v[54:57]
	v_mfma_f32_16x16x32_bf16 v[46:49], v[158:161], v[182:185], v[46:49]
	v_mfma_f32_16x16x32_bf16 v[38:41], v[150:153], v[190:193], v[38:41]
	v_mfma_f32_16x16x32_bf16 v[30:33], v[158:161], v[190:193], v[30:33]
	v_mfma_f32_16x16x32_bf16 v[22:25], v[150:153], v[204:207], v[22:25]
	v_mfma_f32_16x16x32_bf16 v[14:17], v[158:161], v[204:207], v[14:17]
	v_mfma_f32_16x16x32_bf16 v[6:9], v[150:153], v[212:215], v[6:9]
	v_mfma_f32_16x16x32_bf16 v[2:5], v[158:161], v[212:215], v[2:5]
	s_setprio 0
	s_barrier
	s_add_i32 s61, s61, 2
	s_add_u32 s40, s40, 0x100
	s_addc_u32 s41, s41, 0
	s_add_u32 s59, s59, 0x100
	s_addc_u32 s60, s60, 0
	s_cmp_gt_u32 s61, 29
	s_cbranch_scc0 .LBB0_1510
	s_and_b64 vcc, exec, s[20:21]
	s_cbranch_vccz .LBB0_1513
	s_barrier

; #define PG8_STAGE(bufoff, gbase, voff) do { _Pragma("unroll") for (int _i = 0; _i < 2; ++_i) \
;         __builtin_amdgcn_global_load_lds((const unsigned*)((const char*)(gbase) + (voff)[_i]), (PG8_LAS unsigned*)(lds + (bufoff) + ldsw + _i * 8192), 16, 0, 0); } while (0)
; #define PG8_LDA(dst, b, h) do { _Pragma("unroll") for (int m = 0; m < 4; ++m) _Pragma("unroll") for (int k = 0; k < 2; ++k) dst[m][k] = *(const PG8_LAS bf16x8*)(lds + PG8_SA(b, h) + aoff + m * 2048 + k * 1024); } while (0)
; #define PG8_LDB(dst, b, h) do { _Pragma("unroll") for (int n = 0; n < 2; ++n) _Pragma("unroll") for (int k = 0; k < 2; ++k) dst[n][k] = *(const PG8_LAS bf16x8*)(lds + PG8_SB(b, h) + boff + n * 2048 + k * 1024); } while (0)
; #define PG8_MMA(ai, bj, At, Bt) do { __builtin_amdgcn_s_setprio(1); _Pragma("unroll") for (int m = 0; m < 4; ++m) _Pragma("unroll") for (int n = 0; n < 2; ++n) _Pragma("unroll") for (int k = 0; k < 2; ++k) \
;         acc[ai][bj][m][n] = __builtin_amdgcn_mfma_f32_16x16x32_bf16(Bt[n][k], At[m][k], acc[ai][bj][m][n], 0, 0, 0); __builtin_amdgcn_s_setprio(0); } while (0)
; #define PG8_WAIT_V(n) asm volatile("s_waitcnt vmcnt(" #n ")" ::: "memory")
; #define PG8_BAR __builtin_amdgcn_s_barrier()
; template <class Epi, class Sched, bool ALIGN_EPI = false, bool SP2 = false, bool HALFM = false>
; __device__ __forceinline__ void gemm_phase(PG8_LAS unsigned char* lds, const Gemm g, const Sched& S, const Epi& E) {
;     ...
;             const bool last = (t == nt - 2);
;             const char* a1 = cA + (size_t)(t + 1) * kstep;
;             const char* a2 = last ? nA : cA + (size_t)(t + 2) * kstep; const char* b2 = last ? nB : cB + (size_t)(t + 2) * kstep;
;             const char* a3 = a2 + kstep; const char* b3 = b2 + kstep;
;             if (last && has_next) S.a_ready(nxt);
;             if constexpr (SP2) {
;             PG8_LDB(B0, 0, 0); PG8_LDB(B1, 0, 1); PG8_SCHED; PG8_LDA(At, 0, 0); PG8_STAGE(PG8_SA(1, 1), a1 + hstep, voffA);
;             PG8_WAIT_V(8); PG8_WAIT_L(0); PG8_BAR; PG8_MMA(0, 0, At, B0); PG8_MMA(0, 1, At, B1); PG8_BAR; PG8_SCHED;
;             PG8_LDA(At, 0, 1); PG8_STAGE(PG8_SB(0, 0), b2, voffB); PG8_STAGE(PG8_SB(0, 1), b2 + hstep, voffB); PG8_STAGE(PG8_SA(0, 0), a2, voffA);
;             PG8_WAIT_V(8); PG8_WAIT_L(0); PG8_BAR; if constexpr (!HALFM) { PG8_MMA(1, 0, At, B0); PG8_MMA(1, 1, At, B1); } PG8_BAR; PG8_SCHED;
.LBB0_1600:
	ds_read_b128 v[130:133], v178
	ds_read_b128 v[134:137], v178 offset:1024
	ds_read_b128 v[138:141], v178 offset:2048
	ds_read_b128 v[142:145], v178 offset:3072
	ds_read_b128 v[146:149], v179
	ds_read_b128 v[166:169], v179 offset:1024
	ds_read_b128 v[170:173], v179 offset:2048
	ds_read_b128 v[182:185], v179 offset:3072
	s_add_u32 s38, s36, 0xfffe0080
	s_addc_u32 s39, s37, -1
	s_cmp_eq_u32 s54, 4
	s_cselect_b32 s41, s27, s39
	s_cselect_b32 s40, s50, s38
	s_cselect_b32 s39, s25, s53
	s_cselect_b32 s38, s51, s52
	v_lshl_add_u64 v[174:175], s[36:37], 0, v[158:159]
	s_add_i32 m0, s1, 0xc000
	ds_read_b128 v[186:189], v180
	ds_read_b128 v[190:193], v180 offset:1024
	ds_read_b128 v[194:197], v180 offset:2048
	ds_read_b128 v[198:201], v180 offset:3072
	ds_read_b128 v[202:205], v180 offset:4096
	ds_read_b128 v[206:209], v180 offset:5120
	ds_read_b128 v[210:213], v180 offset:6144
	ds_read_b128 v[214:217], v180 offset:7168
	global_load_lds_dwordx4 v[174:175], off
	v_lshl_add_u64 v[174:175], s[36:37], 0, v[160:161]
	s_add_i32 m0, s1, 0xe000
	s_nop 0
	global_load_lds_dwordx4 v[174:175], off
	s_mov_b32 m0, s43
	v_lshl_add_u64 v[174:175], v[220:221], 0, s[14:15]
	global_load_lds_dwordx4 v[174:175], off
	s_mov_b32 m0, s44
	v_lshl_add_u64 v[174:175], v[222:223], 0, s[14:15]
	global_load_lds_dwordx4 v[174:175], off
	s_waitcnt vmcnt(10)
	s_waitcnt lgkmcnt(0)
	s_barrier
	s_setprio 1
	s_waitcnt lgkmcnt(0)
	v_mfma_f32_16x16x32_bf16 v[126:129], v[130:133], v[186:189], v[126:129]
	v_mfma_f32_16x16x32_bf16 v[122:125], v[138:141], v[186:189], v[122:125]
	v_mfma_f32_16x16x32_bf16 v[110:113], v[130:133], v[194:197], v[110:113]
	v_mfma_f32_16x16x32_bf16 v[106:109], v[138:141], v[194:197], v[106:109]
	v_mfma_f32_16x16x32_bf16 v[94:97], v[130:133], v[202:205], v[94:97]
	v_mfma_f32_16x16x32_bf16 v[90:93], v[138:141], v[202:205], v[90:93]
	v_mfma_f32_16x16x32_bf16 v[78:81], v[130:133], v[210:213], v[78:81]
	v_mfma_f32_16x16x32_bf16 v[74:77], v[138:141], v[210:213], v[74:77]
	v_mfma_f32_16x16x32_bf16 v[126:129], v[134:137], v[190:193], v[126:129]
	v_mfma_f32_16x16x32_bf16 v[122:125], v[142:145], v[190:193], v[122:125]
	v_mfma_f32_16x16x32_bf16 v[110:113], v[134:137], v[198:201], v[110:113]
	v_mfma_f32_16x16x32_bf16 v[106:109], v[142:145], v[198:201], v[106:109]
	v_mfma_f32_16x16x32_bf16 v[94:97], v[134:137], v[206:209], v[94:97]
	v_mfma_f32_16x16x32_bf16 v[90:93], v[142:145], v[206:209], v[90:93]
	v_mfma_f32_16x16x32_bf16 v[78:81], v[134:137], v[214:217], v[78:81]
	v_mfma_f32_16x16x32_bf16 v[74:77], v[142:145], v[214:217], v[74:77]
	v_mfma_f32_16x16x32_bf16 v[118:121], v[146:149], v[186:189], v[118:121]
	v_mfma_f32_16x16x32_bf16 v[114:117], v[170:173], v[186:189], v[114:117]
	v_mfma_f32_16x16x32_bf16 v[102:105], v[146:149], v[194:197], v[102:105]
	v_mfma_f32_16x16x32_bf16 v[98:101], v[170:173], v[194:197], v[98:101]
	v_mfma_f32_16x16x32_bf16 v[86:89], v[146:149], v[202:205], v[86:89]
	v_mfma_f32_16x16x32_bf16 v[82:85], v[170:173], v[202:205], v[82:85]
	v_mfma_f32_16x16x32_bf16 v[70:73], v[146:149], v[210:213], v[70:73]
	v_mfma_f32_16x16x32_bf16 v[66:69], v[170:173], v[210:213], v[66:69]
	v_mfma_f32_16x16x32_bf16 v[118:121], v[166:169], v[190:193], v[118:121]
	v_mfma_f32_16x16x32_bf16 v[114:117], v[182:185], v[190:193], v[114:117]
	v_mfma_f32_16x16x32_bf16 v[102:105], v[166:169], v[198:201], v[102:105]
	v_mfma_f32_16x16x32_bf16 v[98:101], v[182:185], v[198:201], v[98:101]
	v_mfma_f32_16x16x32_bf16 v[86:89], v[166:169], v[206:209], v[86:89]
	v_mfma_f32_16x16x32_bf16 v[82:85], v[182:185], v[206:209], v[82:85]
	v_mfma_f32_16x16x32_bf16 v[70:73], v[166:169], v[214:217], v[70:73]
	v_mfma_f32_16x16x32_bf16 v[66:69], v[182:185], v[214:217], v[66:69]
	s_setprio 0
	s_barrier
	s_add_i32 s55, s46, s0
	v_lshl_add_u64 v[174:175], s[38:39], 0, v[152:153]
	s_mov_b32 m0, s55
	ds_read_b128 v[186:189], v180 offset:16384
	ds_read_b128 v[190:193], v180 offset:17408
	ds_read_b128 v[194:197], v180 offset:18432
	ds_read_b128 v[198:201], v180 offset:19456
	ds_read_b128 v[202:205], v180 offset:20480
	ds_read_b128 v[206:209], v180 offset:21504
	ds_read_b128 v[210:213], v180 offset:22528
	ds_read_b128 v[214:217], v180 offset:23552
	global_load_lds_dwordx4 v[174:175], off
	s_add_i32 m0, s55, 0x2000
	s_add_u32 s56, s38, 0x20000
	v_lshl_add_u64 v[218:219], s[38:39], 0, v[156:157]
	s_addc_u32 s57, s39, 0
	s_add_i32 s55, s47, s0
	global_load_lds_dwordx4 v[218:219], off
	v_lshl_add_u64 v[220:221], s[56:57], 0, v[152:153]
	s_mov_b32 m0, s55
	v_lshl_add_u64 v[222:223], s[40:41], 0, v[154:155]
	global_load_lds_dwordx4 v[220:221], off
	v_lshl_add_u64 v[220:221], s[56:57], 0, v[156:157]
	s_add_i32 m0, s55, 0x2000
	s_nop 0
	global_load_lds_dwordx4 v[220:221], off
	v_lshl_add_u64 v[220:221], s[40:41], 0, v[150:151]
	s_waitcnt vmcnt(4)
	s_waitcnt lgkmcnt(0)
	s_barrier
; #define PG8_STAGE(bufoff, gbase, voff) do { _Pragma("unroll") for (int _i = 0; _i < 2; ++_i) \
;         __builtin_amdgcn_global_load_lds((const unsigned*)((const char*)(gbase) + (voff)[_i]), (PG8_LAS unsigned*)(lds + (bufoff) + ldsw + _i * 8192), 16, 0, 0); } while (0)
; #define PG8_LDA(dst, b, h) do { _Pragma("unroll") for (int m = 0; m < 4; ++m) _Pragma("unroll") for (int k = 0; k < 2; ++k) dst[m][k] = *(const PG8_LAS bf16x8*)(lds + PG8_SA(b, h) + aoff + m * 2048 + k * 1024); } while (0)
; #define PG8_LDB(dst, b, h) do { _Pragma("unroll") for (int n = 0; n < 2; ++n) _Pragma("unroll") for (int k = 0; k < 2; ++k) dst[n][k] = *(const PG8_LAS bf16x8*)(lds + PG8_SB(b, h) + boff + n * 2048 + k * 1024); } while (0)
; #define PG8_MMA(ai, bj, At, Bt) do { __builtin_amdgcn_s_setprio(1); _Pragma("unroll") for (int m = 0; m < 4; ++m) _Pragma("unroll") for (int n = 0; n < 2; ++n) _Pragma("unroll") for (int k = 0; k < 2; ++k) \
;         acc[ai][bj][m][n] = __builtin_amdgcn_mfma_f32_16x16x32_bf16(Bt[n][k], At[m][k], acc[ai][bj][m][n], 0, 0, 0); __builtin_amdgcn_s_setprio(0); } while (0)
; #define PG8_WAIT_V(n) asm volatile("s_waitcnt vmcnt(" #n ")" ::: "memory")
; #define PG8_WAIT_L(n) asm volatile("s_waitcnt lgkmcnt(" #n ")" ::: "memory")
; #define PG8_BAR __builtin_amdgcn_s_barrier()
; #define PG8_SCHED __builtin_amdgcn_sched_barrier(0)
; template <class Epi, class Sched, bool ALIGN_EPI = false, bool SP2 = false, bool HALFM = false>
; __device__ __forceinline__ void gemm_phase(PG8_LAS unsigned char* lds, const Gemm g, const Sched& S, const Epi& E) {
;     ...
;             PG8_WAIT_V(8); PG8_WAIT_L(0); PG8_BAR; if constexpr (!HALFM) { PG8_MMA(1, 0, At, B0); PG8_MMA(1, 1, At, B1); } PG8_BAR; PG8_SCHED;
;             PG8_LDB(B0, 1, 0); PG8_LDB(B1, 1, 1); PG8_SCHED; PG8_LDA(At, 1, 0); PG8_STAGE(PG8_SA(0, 1), a2 + hstep, voffA);
;             PG8_WAIT_V(8); PG8_WAIT_L(0); PG8_BAR; PG8_MMA(0, 0, At, B0); PG8_MMA(0, 1, At, B1); PG8_BAR; PG8_SCHED;
	s_setprio 1
	s_waitcnt lgkmcnt(0)
	v_mfma_f32_16x16x32_bf16 v[62:65], v[130:133], v[186:189], v[62:65]
	v_mfma_f32_16x16x32_bf16 v[58:61], v[138:141], v[186:189], v[58:61]
	v_mfma_f32_16x16x32_bf16 v[46:49], v[130:133], v[194:197], v[46:49]
	v_mfma_f32_16x16x32_bf16 v[42:45], v[138:141], v[194:197], v[42:45]
	v_mfma_f32_16x16x32_bf16 v[30:33], v[130:133], v[202:205], v[30:33]
	v_mfma_f32_16x16x32_bf16 v[26:29], v[138:141], v[202:205], v[26:29]
	v_mfma_f32_16x16x32_bf16 v[14:17], v[130:133], v[210:213], v[14:17]
	v_mfma_f32_16x16x32_bf16 v[10:13], v[138:141], v[210:213], v[10:13]
	v_mfma_f32_16x16x32_bf16 v[62:65], v[134:137], v[190:193], v[62:65]
	v_mfma_f32_16x16x32_bf16 v[58:61], v[142:145], v[190:193], v[58:61]
	v_mfma_f32_16x16x32_bf16 v[46:49], v[134:137], v[198:201], v[46:49]
	v_mfma_f32_16x16x32_bf16 v[42:45], v[142:145], v[198:201], v[42:45]
	v_mfma_f32_16x16x32_bf16 v[30:33], v[134:137], v[206:209], v[30:33]
	v_mfma_f32_16x16x32_bf16 v[26:29], v[142:145], v[206:209], v[26:29]
	v_mfma_f32_16x16x32_bf16 v[14:17], v[134:137], v[214:217], v[14:17]
	v_mfma_f32_16x16x32_bf16 v[10:13], v[142:145], v[214:217], v[10:13]
	v_mfma_f32_16x16x32_bf16 v[54:57], v[146:149], v[186:189], v[54:57]
	v_mfma_f32_16x16x32_bf16 v[50:53], v[170:173], v[186:189], v[50:53]
	v_mfma_f32_16x16x32_bf16 v[38:41], v[146:149], v[194:197], v[38:41]
	v_mfma_f32_16x16x32_bf16 v[34:37], v[170:173], v[194:197], v[34:37]
	v_mfma_f32_16x16x32_bf16 v[22:25], v[146:149], v[202:205], v[22:25]
	v_mfma_f32_16x16x32_bf16 v[18:21], v[170:173], v[202:205], v[18:21]
	v_mfma_f32_16x16x32_bf16 v[6:9], v[146:149], v[210:213], v[6:9]
	v_mfma_f32_16x16x32_bf16 v[2:5], v[170:173], v[210:213], v[2:5]
	v_mfma_f32_16x16x32_bf16 v[54:57], v[166:169], v[190:193], v[54:57]
	v_mfma_f32_16x16x32_bf16 v[50:53], v[182:185], v[190:193], v[50:53]
	v_mfma_f32_16x16x32_bf16 v[38:41], v[166:169], v[198:201], v[38:41]
	v_mfma_f32_16x16x32_bf16 v[34:37], v[182:185], v[198:201], v[34:37]
	v_mfma_f32_16x16x32_bf16 v[22:25], v[166:169], v[206:209], v[22:25]
	v_mfma_f32_16x16x32_bf16 v[18:21], v[182:185], v[206:209], v[18:21]
	v_mfma_f32_16x16x32_bf16 v[6:9], v[166:169], v[214:217], v[6:9]
	v_mfma_f32_16x16x32_bf16 v[2:5], v[182:185], v[214:217], v[2:5]
	s_setprio 0
	s_barrier
	s_add_i32 s55, 0, 0x18000
	s_add_i32 s56, 0, 0x1c000
	v_add_u32_e32 v142, s55, v176
	v_add_u32_e32 v181, s56, v176
	ds_read_b128 v[130:133], v142
	ds_read_b128 v[134:137], v142 offset:1024
	ds_read_b128 v[138:141], v142 offset:2048
	ds_read_b128 v[142:145], v142 offset:3072
	ds_read_b128 v[146:149], v181
	ds_read_b128 v[166:169], v181 offset:1024
	ds_read_b128 v[170:173], v181 offset:2048
	ds_read_b128 v[182:185], v181 offset:3072
	s_add_u32 s40, s40, 0x20000
	s_addc_u32 s41, s41, 0
	s_mov_b32 m0, s3
	v_lshl_add_u64 v[224:225], s[40:41], 0, v[150:151]
	ds_read_b128 v[186:189], v180 offset:32768
	ds_read_b128 v[190:193], v180 offset:33792
	ds_read_b128 v[194:197], v180 offset:34816
	ds_read_b128 v[198:201], v180 offset:35840
	ds_read_b128 v[202:205], v180 offset:36864
	ds_read_b128 v[206:209], v180 offset:37888
	ds_read_b128 v[210:213], v180 offset:38912
	ds_read_b128 v[214:217], v180 offset:39936
	global_load_lds_dwordx4 v[224:225], off
	v_lshl_add_u64 v[224:225], s[40:41], 0, v[154:155]
	s_mov_b32 m0, s35
	s_nop 0
	global_load_lds_dwordx4 v[224:225], off
	s_mov_b32 m0, s1
	s_nop 0
	global_load_lds_dwordx4 v[220:221], off
	s_mov_b32 m0, s2
	s_nop 0
	global_load_lds_dwordx4 v[222:223], off
	s_waitcnt vmcnt(10)
	s_waitcnt lgkmcnt(0)
	s_barrier
; #define PG8_STAGE(bufoff, gbase, voff) do { _Pragma("unroll") for (int _i = 0; _i < 2; ++_i) \
;         __builtin_amdgcn_global_load_lds((const unsigned*)((const char*)(gbase) + (voff)[_i]), (PG8_LAS unsigned*)(lds + (bufoff) + ldsw + _i * 8192), 16, 0, 0); } while (0)
; #define PG8_LDA(dst, b, h) do { _Pragma("unroll") for (int m = 0; m < 4; ++m) _Pragma("unroll") for (int k = 0; k < 2; ++k) dst[m][k] = *(const PG8_LAS bf16x8*)(lds + PG8_SA(b, h) + aoff + m * 2048 + k * 1024); } while (0)
; #define PG8_MMA(ai, bj, At, Bt) do { __builtin_amdgcn_s_setprio(1); _Pragma("unroll") for (int m = 0; m < 4; ++m) _Pragma("unroll") for (int n = 0; n < 2; ++n) _Pragma("unroll") for (int k = 0; k < 2; ++k) \
;         acc[ai][bj][m][n] = __builtin_amdgcn_mfma_f32_16x16x32_bf16(Bt[n][k], At[m][k], acc[ai][bj][m][n], 0, 0, 0); __builtin_amdgcn_s_setprio(0); } while (0)
; #define PG8_WAIT_V(n) asm volatile("s_waitcnt vmcnt(" #n ")" ::: "memory")
; #define PG8_WAIT_L(n) asm volatile("s_waitcnt lgkmcnt(" #n ")" ::: "memory")
; #define PG8_BAR __builtin_amdgcn_s_barrier()
; #define PG8_SCHED __builtin_amdgcn_sched_barrier(0)
; template <class Epi, class Sched, bool ALIGN_EPI = false, bool SP2 = false, bool HALFM = false>
; __device__ __forceinline__ void gemm_phase(PG8_LAS unsigned char* lds, const Gemm g, const Sched& S, const Epi& E) {
;     ...
;             PG8_WAIT_V(8); PG8_WAIT_L(0); PG8_BAR; PG8_MMA(0, 0, At, B0); PG8_MMA(0, 1, At, B1); PG8_BAR; PG8_SCHED;
;             PG8_LDA(At, 1, 1); PG8_STAGE(PG8_SB(1, 0), b3, voffB); PG8_STAGE(PG8_SB(1, 1), b3 + hstep, voffB); PG8_STAGE(PG8_SA(1, 0), a3, voffA);
;             PG8_WAIT_V(8); PG8_WAIT_L(0); PG8_BAR; if constexpr (!HALFM) { PG8_MMA(1, 0, At, B0); PG8_MMA(1, 1, At, B1); } PG8_BAR; PG8_SCHED;
	s_setprio 1
	s_waitcnt lgkmcnt(0)
	v_mfma_f32_16x16x32_bf16 v[126:129], v[130:133], v[186:189], v[126:129]
	v_mfma_f32_16x16x32_bf16 v[122:125], v[138:141], v[186:189], v[122:125]
	v_mfma_f32_16x16x32_bf16 v[110:113], v[130:133], v[194:197], v[110:113]
	v_mfma_f32_16x16x32_bf16 v[106:109], v[138:141], v[194:197], v[106:109]
	v_mfma_f32_16x16x32_bf16 v[94:97], v[130:133], v[202:205], v[94:97]
	v_mfma_f32_16x16x32_bf16 v[90:93], v[138:141], v[202:205], v[90:93]
	v_mfma_f32_16x16x32_bf16 v[78:81], v[130:133], v[210:213], v[78:81]
	v_mfma_f32_16x16x32_bf16 v[74:77], v[138:141], v[210:213], v[74:77]
	v_mfma_f32_16x16x32_bf16 v[126:129], v[134:137], v[190:193], v[126:129]
	v_mfma_f32_16x16x32_bf16 v[122:125], v[142:145], v[190:193], v[122:125]
	v_mfma_f32_16x16x32_bf16 v[110:113], v[134:137], v[198:201], v[110:113]
	v_mfma_f32_16x16x32_bf16 v[106:109], v[142:145], v[198:201], v[106:109]
	v_mfma_f32_16x16x32_bf16 v[94:97], v[134:137], v[206:209], v[94:97]
	v_mfma_f32_16x16x32_bf16 v[90:93], v[142:145], v[206:209], v[90:93]
	v_mfma_f32_16x16x32_bf16 v[78:81], v[134:137], v[214:217], v[78:81]
	v_mfma_f32_16x16x32_bf16 v[74:77], v[142:145], v[214:217], v[74:77]
	v_mfma_f32_16x16x32_bf16 v[118:121], v[146:149], v[186:189], v[118:121]
	v_mfma_f32_16x16x32_bf16 v[114:117], v[170:173], v[186:189], v[114:117]
	v_mfma_f32_16x16x32_bf16 v[102:105], v[146:149], v[194:197], v[102:105]
	v_mfma_f32_16x16x32_bf16 v[98:101], v[170:173], v[194:197], v[98:101]
	v_mfma_f32_16x16x32_bf16 v[86:89], v[146:149], v[202:205], v[86:89]
	v_mfma_f32_16x16x32_bf16 v[82:85], v[170:173], v[202:205], v[82:85]
	v_mfma_f32_16x16x32_bf16 v[70:73], v[146:149], v[210:213], v[70:73]
	v_mfma_f32_16x16x32_bf16 v[66:69], v[170:173], v[210:213], v[66:69]
	v_mfma_f32_16x16x32_bf16 v[118:121], v[166:169], v[190:193], v[118:121]
	v_mfma_f32_16x16x32_bf16 v[114:117], v[182:185], v[190:193], v[114:117]
	v_mfma_f32_16x16x32_bf16 v[102:105], v[166:169], v[198:201], v[102:105]
	v_mfma_f32_16x16x32_bf16 v[98:101], v[182:185], v[198:201], v[98:101]
	v_mfma_f32_16x16x32_bf16 v[86:89], v[166:169], v[206:209], v[86:89]
	v_mfma_f32_16x16x32_bf16 v[82:85], v[182:185], v[206:209], v[82:85]
	v_mfma_f32_16x16x32_bf16 v[70:73], v[166:169], v[214:217], v[70:73]
	v_mfma_f32_16x16x32_bf16 v[66:69], v[182:185], v[214:217], v[66:69]
	s_setprio 0
	s_barrier
	s_add_i32 s40, s55, s0
	v_lshl_add_u64 v[174:175], v[174:175], 0, s[14:15]
	s_mov_b32 m0, s40
	ds_read_b128 v[186:189], v180 offset:49152
	ds_read_b128 v[190:193], v180 offset:50176
	ds_read_b128 v[194:197], v180 offset:51200
	ds_read_b128 v[198:201], v180 offset:52224
	ds_read_b128 v[202:205], v180 offset:53248
	ds_read_b128 v[206:209], v180 offset:54272
	ds_read_b128 v[210:213], v180 offset:55296
	ds_read_b128 v[214:217], v180 offset:56320
	global_load_lds_dwordx4 v[174:175], off
	s_add_i32 m0, s40, 0x2000
	s_add_u32 s38, s38, 0x20080
	v_lshl_add_u64 v[174:175], v[218:219], 0, s[14:15]
	s_addc_u32 s39, s39, 0
	s_add_i32 s40, s56, s0
	global_load_lds_dwordx4 v[174:175], off
	v_lshl_add_u64 v[174:175], s[38:39], 0, v[152:153]
	s_mov_b32 m0, s40
	s_nop 0
	global_load_lds_dwordx4 v[174:175], off
	v_lshl_add_u64 v[174:175], s[38:39], 0, v[156:157]
	s_add_i32 m0, s40, 0x2000
	s_nop 0
	global_load_lds_dwordx4 v[174:175], off
	s_waitcnt vmcnt(4)
	s_waitcnt lgkmcnt(0)
	s_barrier
	s_setprio 1
	s_waitcnt lgkmcnt(0)
	v_mfma_f32_16x16x32_bf16 v[62:65], v[130:133], v[186:189], v[62:65]
	v_mfma_f32_16x16x32_bf16 v[58:61], v[138:141], v[186:189], v[58:61]
	v_mfma_f32_16x16x32_bf16 v[46:49], v[130:133], v[194:197], v[46:49]
	v_mfma_f32_16x16x32_bf16 v[42:45], v[138:141], v[194:197], v[42:45]
	v_mfma_f32_16x16x32_bf16 v[30:33], v[130:133], v[202:205], v[30:33]
	v_mfma_f32_16x16x32_bf16 v[26:29], v[138:141], v[202:205], v[26:29]
	v_mfma_f32_16x16x32_bf16 v[14:17], v[130:133], v[210:213], v[14:17]
	v_mfma_f32_16x16x32_bf16 v[10:13], v[138:141], v[210:213], v[10:13]
	v_mfma_f32_16x16x32_bf16 v[62:65], v[134:137], v[190:193], v[62:65]
	v_mfma_f32_16x16x32_bf16 v[58:61], v[142:145], v[190:193], v[58:61]
	v_mfma_f32_16x16x32_bf16 v[46:49], v[134:137], v[198:201], v[46:49]
	v_mfma_f32_16x16x32_bf16 v[42:45], v[142:145], v[198:201], v[42:45]
	v_mfma_f32_16x16x32_bf16 v[30:33], v[134:137], v[206:209], v[30:33]
	v_mfma_f32_16x16x32_bf16 v[26:29], v[142:145], v[206:209], v[26:29]
	v_mfma_f32_16x16x32_bf16 v[14:17], v[134:137], v[214:217], v[14:17]
	v_mfma_f32_16x16x32_bf16 v[10:13], v[142:145], v[214:217], v[10:13]
	v_mfma_f32_16x16x32_bf16 v[54:57], v[146:149], v[186:189], v[54:57]
	v_mfma_f32_16x16x32_bf16 v[50:53], v[170:173], v[186:189], v[50:53]
	v_mfma_f32_16x16x32_bf16 v[38:41], v[146:149], v[194:197], v[38:41]
	v_mfma_f32_16x16x32_bf16 v[34:37], v[170:173], v[194:197], v[34:37]
	v_mfma_f32_16x16x32_bf16 v[22:25], v[146:149], v[202:205], v[22:25]
	v_mfma_f32_16x16x32_bf16 v[18:21], v[170:173], v[202:205], v[18:21]
	v_mfma_f32_16x16x32_bf16 v[6:9], v[146:149], v[210:213], v[6:9]
	v_mfma_f32_16x16x32_bf16 v[2:5], v[170:173], v[210:213], v[2:5]
	v_mfma_f32_16x16x32_bf16 v[54:57], v[166:169], v[190:193], v[54:57]
	v_mfma_f32_16x16x32_bf16 v[50:53], v[182:185], v[190:193], v[50:53]
	v_mfma_f32_16x16x32_bf16 v[38:41], v[166:169], v[198:201], v[38:41]
	v_mfma_f32_16x16x32_bf16 v[34:37], v[182:185], v[198:201], v[34:37]
	v_mfma_f32_16x16x32_bf16 v[22:25], v[166:169], v[206:209], v[22:25]
	v_mfma_f32_16x16x32_bf16 v[18:21], v[182:185], v[206:209], v[18:21]
	v_mfma_f32_16x16x32_bf16 v[6:9], v[166:169], v[214:217], v[6:9]
	v_mfma_f32_16x16x32_bf16 v[2:5], v[182:185], v[214:217], v[2:5]
	s_setprio 0
	s_barrier
	s_add_i32 s54, s54, 2
	s_add_u32 s36, s36, 0x100
	s_addc_u32 s37, s37, 0
	s_add_u32 s52, s52, 0x100
	s_addc_u32 s53, s53, 0
	s_cmp_gt_u32 s54, 5
	s_cbranch_scc0 .LBB0_1600
	s_and_b64 vcc, exec, s[20:21]
	s_cbranch_vccz .LBB0_1603
	s_barrier

; #define PG8_STAGE(bufoff, gbase, voff) do { _Pragma("unroll") for (int _i = 0; _i < 2; ++_i) \
;         __builtin_amdgcn_global_load_lds((const unsigned*)((const char*)(gbase) + (voff)[_i]), (PG8_LAS unsigned*)(lds + (bufoff) + ldsw + _i * 8192), 16, 0, 0); } while (0)
; #define PG8_LDA(dst, b, h) do { _Pragma("unroll") for (int m = 0; m < 4; ++m) _Pragma("unroll") for (int k = 0; k < 2; ++k) dst[m][k] = *(const PG8_LAS bf16x8*)(lds + PG8_SA(b, h) + aoff + m * 2048 + k * 1024); } while (0)
; #define PG8_LDB(dst, b, h) do { _Pragma("unroll") for (int n = 0; n < 2; ++n) _Pragma("unroll") for (int k = 0; k < 2; ++k) dst[n][k] = *(const PG8_LAS bf16x8*)(lds + PG8_SB(b, h) + boff + n * 2048 + k * 1024); } while (0)
; #define PG8_MMA(ai, bj, At, Bt) do { __builtin_amdgcn_s_setprio(1); _Pragma("unroll") for (int m = 0; m < 4; ++m) _Pragma("unroll") for (int n = 0; n < 2; ++n) _Pragma("unroll") for (int k = 0; k < 2; ++k) \
;         acc[ai][bj][m][n] = __builtin_amdgcn_mfma_f32_16x16x32_bf16(Bt[n][k], At[m][k], acc[ai][bj][m][n], 0, 0, 0); __builtin_amdgcn_s_setprio(0); } while (0)
; #define PG8_WAIT_V(n) asm volatile("s_waitcnt vmcnt(" #n ")" ::: "memory")
; #define PG8_BAR __builtin_amdgcn_s_barrier()
; template <class Epi, class Sched, bool ALIGN_EPI = false, bool SP2 = false, bool HALFM = false>
; __device__ __forceinline__ void gemm_phase(PG8_LAS unsigned char* lds, const Gemm g, const Sched& S, const Epi& E) {
;     ...
;             const bool last = (t == nt - 2);
;             const char* a1 = cA + (size_t)(t + 1) * kstep;
;             const char* a2 = last ? nA : cA + (size_t)(t + 2) * kstep; const char* b2 = last ? nB : cB + (size_t)(t + 2) * kstep;
;             const char* a3 = a2 + kstep; const char* b3 = b2 + kstep;
;             if (last && has_next) S.a_ready(nxt);
;             if constexpr (SP2) {
;             PG8_LDB(B0, 0, 0); PG8_LDB(B1, 0, 1); PG8_SCHED; PG8_LDA(At, 0, 0); PG8_STAGE(PG8_SA(1, 1), a1 + hstep, voffA);
;             PG8_WAIT_V(8); PG8_WAIT_L(0); PG8_BAR; PG8_MMA(0, 0, At, B0); PG8_MMA(0, 1, At, B1); PG8_BAR; PG8_SCHED;
;             PG8_LDA(At, 0, 1); PG8_STAGE(PG8_SB(0, 0), b2, voffB); PG8_STAGE(PG8_SB(0, 1), b2 + hstep, voffB); PG8_STAGE(PG8_SA(0, 0), a2, voffA);
;             PG8_WAIT_V(8); PG8_WAIT_L(0); PG8_BAR; if constexpr (!HALFM) { PG8_MMA(1, 0, At, B0); PG8_MMA(1, 1, At, B1); } PG8_BAR; PG8_SCHED;
.LBB0_1692:
	ds_read_b128 v[114:117], v246
	ds_read_b128 v[118:121], v246 offset:1024
	ds_read_b128 v[130:133], v246 offset:2048
	ds_read_b128 v[134:137], v246 offset:3072
	ds_read_b128 v[138:141], v247
	ds_read_b128 v[142:145], v247 offset:1024
	ds_read_b128 v[146:149], v247 offset:2048
	ds_read_b128 v[158:161], v247 offset:3072
	s_add_u32 s38, s36, 0xfffc0080
	s_addc_u32 s39, s37, -1
	s_cmp_eq_u32 s53, 12
	s_cselect_b32 s41, s25, s39
	s_cselect_b32 s40, s31, s38
	s_cselect_b32 s39, s23, s52
	s_cselect_b32 s38, s50, s51
	v_lshl_add_u64 v[206:207], s[36:37], 0, v[202:203]
	s_add_i32 m0, s1, 0xc000
	ds_read_b128 v[162:165], v248
	ds_read_b128 v[166:169], v248 offset:1024
	ds_read_b128 v[170:173], v248 offset:2048
	ds_read_b128 v[174:177], v248 offset:3072
	ds_read_b128 v[178:181], v248 offset:4096
	ds_read_b128 v[182:185], v248 offset:5120
	ds_read_b128 v[186:189], v248 offset:6144
	ds_read_b128 v[190:193], v248 offset:7168
	global_load_lds_dwordx4 v[206:207], off
	v_lshl_add_u64 v[206:207], s[36:37], 0, v[204:205]
	s_add_i32 m0, s1, 0xe000
	s_nop 0
	global_load_lds_dwordx4 v[206:207], off
	s_mov_b32 m0, s43
	v_lshl_add_u64 v[206:207], v[210:211], 0, s[10:11]
	global_load_lds_dwordx4 v[206:207], off
	s_mov_b32 m0, s44
	v_lshl_add_u64 v[206:207], v[212:213], 0, s[10:11]
	global_load_lds_dwordx4 v[206:207], off
	s_waitcnt vmcnt(10)
	s_waitcnt lgkmcnt(0)
	s_barrier
	s_setprio 1
	s_waitcnt lgkmcnt(0)
	v_mfma_f32_16x16x32_bf16 v[154:157], v[114:117], v[162:165], v[154:157]
	v_mfma_f32_16x16x32_bf16 v[150:153], v[130:133], v[162:165], v[150:153]
	v_mfma_f32_16x16x32_bf16 v[110:113], v[114:117], v[170:173], v[110:113]
	v_mfma_f32_16x16x32_bf16 v[106:109], v[130:133], v[170:173], v[106:109]
	v_mfma_f32_16x16x32_bf16 v[94:97], v[114:117], v[178:181], v[94:97]
	v_mfma_f32_16x16x32_bf16 v[90:93], v[130:133], v[178:181], v[90:93]
	v_mfma_f32_16x16x32_bf16 v[78:81], v[114:117], v[186:189], v[78:81]
	v_mfma_f32_16x16x32_bf16 v[74:77], v[130:133], v[186:189], v[74:77]
	v_mfma_f32_16x16x32_bf16 v[154:157], v[118:121], v[166:169], v[154:157]
	v_mfma_f32_16x16x32_bf16 v[150:153], v[134:137], v[166:169], v[150:153]
	v_mfma_f32_16x16x32_bf16 v[110:113], v[118:121], v[174:177], v[110:113]
	v_mfma_f32_16x16x32_bf16 v[106:109], v[134:137], v[174:177], v[106:109]
	v_mfma_f32_16x16x32_bf16 v[94:97], v[118:121], v[182:185], v[94:97]
	v_mfma_f32_16x16x32_bf16 v[90:93], v[134:137], v[182:185], v[90:93]
	v_mfma_f32_16x16x32_bf16 v[78:81], v[118:121], v[190:193], v[78:81]
	v_mfma_f32_16x16x32_bf16 v[74:77], v[134:137], v[190:193], v[74:77]
	v_mfma_f32_16x16x32_bf16 v[126:129], v[138:141], v[162:165], v[126:129]
	v_mfma_f32_16x16x32_bf16 v[122:125], v[146:149], v[162:165], v[122:125]
	v_mfma_f32_16x16x32_bf16 v[102:105], v[138:141], v[170:173], v[102:105]
	v_mfma_f32_16x16x32_bf16 v[98:101], v[146:149], v[170:173], v[98:101]
	v_mfma_f32_16x16x32_bf16 v[86:89], v[138:141], v[178:181], v[86:89]
	v_mfma_f32_16x16x32_bf16 v[82:85], v[146:149], v[178:181], v[82:85]
	v_mfma_f32_16x16x32_bf16 v[70:73], v[138:141], v[186:189], v[70:73]
	v_mfma_f32_16x16x32_bf16 v[66:69], v[146:149], v[186:189], v[66:69]
	v_mfma_f32_16x16x32_bf16 v[126:129], v[142:145], v[166:169], v[126:129]
	v_mfma_f32_16x16x32_bf16 v[122:125], v[158:161], v[166:169], v[122:125]
	v_mfma_f32_16x16x32_bf16 v[102:105], v[142:145], v[174:177], v[102:105]
	v_mfma_f32_16x16x32_bf16 v[98:101], v[158:161], v[174:177], v[98:101]
	v_mfma_f32_16x16x32_bf16 v[86:89], v[142:145], v[182:185], v[86:89]
	v_mfma_f32_16x16x32_bf16 v[82:85], v[158:161], v[182:185], v[82:85]
	v_mfma_f32_16x16x32_bf16 v[70:73], v[142:145], v[190:193], v[70:73]
	v_mfma_f32_16x16x32_bf16 v[66:69], v[158:161], v[190:193], v[66:69]
	s_setprio 0
	s_barrier
	s_add_i32 s54, s46, s0
	v_lshl_add_u64 v[206:207], s[38:39], 0, v[196:197]
	s_mov_b32 m0, s54
	ds_read_b128 v[162:165], v248 offset:16384
	ds_read_b128 v[166:169], v248 offset:17408
	ds_read_b128 v[170:173], v248 offset:18432
	ds_read_b128 v[174:177], v248 offset:19456
	ds_read_b128 v[178:181], v248 offset:20480
	ds_read_b128 v[182:185], v248 offset:21504
	ds_read_b128 v[186:189], v248 offset:22528
	ds_read_b128 v[190:193], v248 offset:23552
	global_load_lds_dwordx4 v[206:207], off
	s_add_i32 m0, s54, 0x2000
	s_add_u32 s54, s38, 0x40000
	v_lshl_add_u64 v[208:209], s[38:39], 0, v[200:201]
	s_addc_u32 s55, s39, 0
	s_add_i32 s56, s47, s0
	global_load_lds_dwordx4 v[208:209], off
	v_lshl_add_u64 v[210:211], s[54:55], 0, v[196:197]
	s_mov_b32 m0, s56
	v_lshl_add_u64 v[212:213], s[40:41], 0, v[198:199]
	global_load_lds_dwordx4 v[210:211], off
	v_lshl_add_u64 v[210:211], s[54:55], 0, v[200:201]
	s_add_i32 m0, s56, 0x2000
	s_nop 0
	global_load_lds_dwordx4 v[210:211], off
	v_lshl_add_u64 v[210:211], s[40:41], 0, v[194:195]
	s_waitcnt vmcnt(4)
	s_waitcnt lgkmcnt(0)
	s_barrier
; #define PG8_STAGE(bufoff, gbase, voff) do { _Pragma("unroll") for (int _i = 0; _i < 2; ++_i) \
;         __builtin_amdgcn_global_load_lds((const unsigned*)((const char*)(gbase) + (voff)[_i]), (PG8_LAS unsigned*)(lds + (bufoff) + ldsw + _i * 8192), 16, 0, 0); } while (0)
; #define PG8_LDA(dst, b, h) do { _Pragma("unroll") for (int m = 0; m < 4; ++m) _Pragma("unroll") for (int k = 0; k < 2; ++k) dst[m][k] = *(const PG8_LAS bf16x8*)(lds + PG8_SA(b, h) + aoff + m * 2048 + k * 1024); } while (0)
; #define PG8_LDB(dst, b, h) do { _Pragma("unroll") for (int n = 0; n < 2; ++n) _Pragma("unroll") for (int k = 0; k < 2; ++k) dst[n][k] = *(const PG8_LAS bf16x8*)(lds + PG8_SB(b, h) + boff + n * 2048 + k * 1024); } while (0)
; #define PG8_MMA(ai, bj, At, Bt) do { __builtin_amdgcn_s_setprio(1); _Pragma("unroll") for (int m = 0; m < 4; ++m) _Pragma("unroll") for (int n = 0; n < 2; ++n) _Pragma("unroll") for (int k = 0; k < 2; ++k) \
;         acc[ai][bj][m][n] = __builtin_amdgcn_mfma_f32_16x16x32_bf16(Bt[n][k], At[m][k], acc[ai][bj][m][n], 0, 0, 0); __builtin_amdgcn_s_setprio(0); } while (0)
; #define PG8_WAIT_V(n) asm volatile("s_waitcnt vmcnt(" #n ")" ::: "memory")
; #define PG8_WAIT_L(n) asm volatile("s_waitcnt lgkmcnt(" #n ")" ::: "memory")
; #define PG8_BAR __builtin_amdgcn_s_barrier()
; #define PG8_SCHED __builtin_amdgcn_sched_barrier(0)
; template <class Epi, class Sched, bool ALIGN_EPI = false, bool SP2 = false, bool HALFM = false>
; __device__ __forceinline__ void gemm_phase(PG8_LAS unsigned char* lds, const Gemm g, const Sched& S, const Epi& E) {
;     ...
;             PG8_WAIT_V(8); PG8_WAIT_L(0); PG8_BAR; if constexpr (!HALFM) { PG8_MMA(1, 0, At, B0); PG8_MMA(1, 1, At, B1); } PG8_BAR; PG8_SCHED;
;             PG8_LDB(B0, 1, 0); PG8_LDB(B1, 1, 1); PG8_SCHED; PG8_LDA(At, 1, 0); PG8_STAGE(PG8_SA(0, 1), a2 + hstep, voffA);
;             PG8_WAIT_V(8); PG8_WAIT_L(0); PG8_BAR; PG8_MMA(0, 0, At, B0); PG8_MMA(0, 1, At, B1); PG8_BAR; PG8_SCHED;
	s_setprio 1
	s_waitcnt lgkmcnt(0)
	v_mfma_f32_16x16x32_bf16 v[62:65], v[114:117], v[162:165], v[62:65]
	v_mfma_f32_16x16x32_bf16 v[58:61], v[130:133], v[162:165], v[58:61]
	v_mfma_f32_16x16x32_bf16 v[46:49], v[114:117], v[170:173], v[46:49]
	v_mfma_f32_16x16x32_bf16 v[42:45], v[130:133], v[170:173], v[42:45]
	v_mfma_f32_16x16x32_bf16 v[30:33], v[114:117], v[178:181], v[30:33]
	v_mfma_f32_16x16x32_bf16 v[26:29], v[130:133], v[178:181], v[26:29]
	v_mfma_f32_16x16x32_bf16 v[14:17], v[114:117], v[186:189], v[14:17]
	v_mfma_f32_16x16x32_bf16 v[10:13], v[130:133], v[186:189], v[10:13]
	v_mfma_f32_16x16x32_bf16 v[62:65], v[118:121], v[166:169], v[62:65]
	v_mfma_f32_16x16x32_bf16 v[58:61], v[134:137], v[166:169], v[58:61]
	v_mfma_f32_16x16x32_bf16 v[46:49], v[118:121], v[174:177], v[46:49]
	v_mfma_f32_16x16x32_bf16 v[42:45], v[134:137], v[174:177], v[42:45]
	v_mfma_f32_16x16x32_bf16 v[30:33], v[118:121], v[182:185], v[30:33]
	v_mfma_f32_16x16x32_bf16 v[26:29], v[134:137], v[182:185], v[26:29]
	v_mfma_f32_16x16x32_bf16 v[14:17], v[118:121], v[190:193], v[14:17]
	v_mfma_f32_16x16x32_bf16 v[10:13], v[134:137], v[190:193], v[10:13]
	v_mfma_f32_16x16x32_bf16 v[54:57], v[138:141], v[162:165], v[54:57]
	v_mfma_f32_16x16x32_bf16 v[50:53], v[146:149], v[162:165], v[50:53]
	v_mfma_f32_16x16x32_bf16 v[38:41], v[138:141], v[170:173], v[38:41]
	v_mfma_f32_16x16x32_bf16 v[34:37], v[146:149], v[170:173], v[34:37]
	v_mfma_f32_16x16x32_bf16 v[22:25], v[138:141], v[178:181], v[22:25]
	v_mfma_f32_16x16x32_bf16 v[18:21], v[146:149], v[178:181], v[18:21]
	v_mfma_f32_16x16x32_bf16 v[6:9], v[138:141], v[186:189], v[6:9]
	v_mfma_f32_16x16x32_bf16 v[2:5], v[146:149], v[186:189], v[2:5]
	v_mfma_f32_16x16x32_bf16 v[54:57], v[142:145], v[166:169], v[54:57]
	v_mfma_f32_16x16x32_bf16 v[50:53], v[158:161], v[166:169], v[50:53]
	v_mfma_f32_16x16x32_bf16 v[38:41], v[142:145], v[174:177], v[38:41]
	v_mfma_f32_16x16x32_bf16 v[34:37], v[158:161], v[174:177], v[34:37]
	v_mfma_f32_16x16x32_bf16 v[22:25], v[142:145], v[182:185], v[22:25]
	v_mfma_f32_16x16x32_bf16 v[18:21], v[158:161], v[182:185], v[18:21]
	v_mfma_f32_16x16x32_bf16 v[6:9], v[142:145], v[190:193], v[6:9]
	v_mfma_f32_16x16x32_bf16 v[2:5], v[158:161], v[190:193], v[2:5]
	s_setprio 0
	s_barrier
	s_add_i32 s54, 0, 0x18000
	s_add_i32 s55, 0, 0x1c000
	v_add_u32_e32 v134, s54, v244
	v_add_u32_e32 v158, s55, v244
	ds_read_b128 v[114:117], v134
	ds_read_b128 v[118:121], v134 offset:1024
	ds_read_b128 v[130:133], v134 offset:2048
	ds_read_b128 v[134:137], v134 offset:3072
	ds_read_b128 v[138:141], v158
	ds_read_b128 v[142:145], v158 offset:1024
	ds_read_b128 v[146:149], v158 offset:2048
	ds_read_b128 v[158:161], v158 offset:3072
	s_add_u32 s40, s40, 0x40000
	s_addc_u32 s41, s41, 0
	s_mov_b32 m0, s3
	v_lshl_add_u64 v[214:215], s[40:41], 0, v[194:195]
	ds_read_b128 v[162:165], v248 offset:32768
	ds_read_b128 v[166:169], v248 offset:33792
	ds_read_b128 v[170:173], v248 offset:34816
	ds_read_b128 v[174:177], v248 offset:35840
	ds_read_b128 v[178:181], v248 offset:36864
	ds_read_b128 v[182:185], v248 offset:37888
	ds_read_b128 v[186:189], v248 offset:38912
	ds_read_b128 v[190:193], v248 offset:39936
	global_load_lds_dwordx4 v[214:215], off
	v_lshl_add_u64 v[214:215], s[40:41], 0, v[198:199]
	s_mov_b32 m0, s35
	s_nop 0
	global_load_lds_dwordx4 v[214:215], off
	s_mov_b32 m0, s1
	s_nop 0
	global_load_lds_dwordx4 v[210:211], off
	s_mov_b32 m0, s2
	s_nop 0
	global_load_lds_dwordx4 v[212:213], off
	s_waitcnt vmcnt(10)
	s_waitcnt lgkmcnt(0)
	s_barrier
; #define PG8_STAGE(bufoff, gbase, voff) do { _Pragma("unroll") for (int _i = 0; _i < 2; ++_i) \
;         __builtin_amdgcn_global_load_lds((const unsigned*)((const char*)(gbase) + (voff)[_i]), (PG8_LAS unsigned*)(lds + (bufoff) + ldsw + _i * 8192), 16, 0, 0); } while (0)
; #define PG8_LDA(dst, b, h) do { _Pragma("unroll") for (int m = 0; m < 4; ++m) _Pragma("unroll") for (int k = 0; k < 2; ++k) dst[m][k] = *(const PG8_LAS bf16x8*)(lds + PG8_SA(b, h) + aoff + m * 2048 + k * 1024); } while (0)
; #define PG8_MMA(ai, bj, At, Bt) do { __builtin_amdgcn_s_setprio(1); _Pragma("unroll") for (int m = 0; m < 4; ++m) _Pragma("unroll") for (int n = 0; n < 2; ++n) _Pragma("unroll") for (int k = 0; k < 2; ++k) \
;         acc[ai][bj][m][n] = __builtin_amdgcn_mfma_f32_16x16x32_bf16(Bt[n][k], At[m][k], acc[ai][bj][m][n], 0, 0, 0); __builtin_amdgcn_s_setprio(0); } while (0)
; #define PG8_WAIT_V(n) asm volatile("s_waitcnt vmcnt(" #n ")" ::: "memory")
; #define PG8_WAIT_L(n) asm volatile("s_waitcnt lgkmcnt(" #n ")" ::: "memory")
; #define PG8_BAR __builtin_amdgcn_s_barrier()
; #define PG8_SCHED __builtin_amdgcn_sched_barrier(0)
; template <class Epi, class Sched, bool ALIGN_EPI = false, bool SP2 = false, bool HALFM = false>
; __device__ __forceinline__ void gemm_phase(PG8_LAS unsigned char* lds, const Gemm g, const Sched& S, const Epi& E) {
;     ...
;             PG8_WAIT_V(8); PG8_WAIT_L(0); PG8_BAR; PG8_MMA(0, 0, At, B0); PG8_MMA(0, 1, At, B1); PG8_BAR; PG8_SCHED;
;             PG8_LDA(At, 1, 1); PG8_STAGE(PG8_SB(1, 0), b3, voffB); PG8_STAGE(PG8_SB(1, 1), b3 + hstep, voffB); PG8_STAGE(PG8_SA(1, 0), a3, voffA);
;             PG8_WAIT_V(8); PG8_WAIT_L(0); PG8_BAR; if constexpr (!HALFM) { PG8_MMA(1, 0, At, B0); PG8_MMA(1, 1, At, B1); } PG8_BAR; PG8_SCHED;
	s_setprio 1
	s_waitcnt lgkmcnt(0)
	v_mfma_f32_16x16x32_bf16 v[154:157], v[114:117], v[162:165], v[154:157]
	v_mfma_f32_16x16x32_bf16 v[150:153], v[130:133], v[162:165], v[150:153]
	v_mfma_f32_16x16x32_bf16 v[110:113], v[114:117], v[170:173], v[110:113]
	v_mfma_f32_16x16x32_bf16 v[106:109], v[130:133], v[170:173], v[106:109]
	v_mfma_f32_16x16x32_bf16 v[94:97], v[114:117], v[178:181], v[94:97]
	v_mfma_f32_16x16x32_bf16 v[90:93], v[130:133], v[178:181], v[90:93]
	v_mfma_f32_16x16x32_bf16 v[78:81], v[114:117], v[186:189], v[78:81]
	v_mfma_f32_16x16x32_bf16 v[74:77], v[130:133], v[186:189], v[74:77]
	v_mfma_f32_16x16x32_bf16 v[154:157], v[118:121], v[166:169], v[154:157]
	v_mfma_f32_16x16x32_bf16 v[150:153], v[134:137], v[166:169], v[150:153]
	v_mfma_f32_16x16x32_bf16 v[110:113], v[118:121], v[174:177], v[110:113]
	v_mfma_f32_16x16x32_bf16 v[106:109], v[134:137], v[174:177], v[106:109]
	v_mfma_f32_16x16x32_bf16 v[94:97], v[118:121], v[182:185], v[94:97]
	v_mfma_f32_16x16x32_bf16 v[90:93], v[134:137], v[182:185], v[90:93]
	v_mfma_f32_16x16x32_bf16 v[78:81], v[118:121], v[190:193], v[78:81]
	v_mfma_f32_16x16x32_bf16 v[74:77], v[134:137], v[190:193], v[74:77]
	v_mfma_f32_16x16x32_bf16 v[126:129], v[138:141], v[162:165], v[126:129]
	v_mfma_f32_16x16x32_bf16 v[122:125], v[146:149], v[162:165], v[122:125]
	v_mfma_f32_16x16x32_bf16 v[102:105], v[138:141], v[170:173], v[102:105]
	v_mfma_f32_16x16x32_bf16 v[98:101], v[146:149], v[170:173], v[98:101]
	v_mfma_f32_16x16x32_bf16 v[86:89], v[138:141], v[178:181], v[86:89]
	v_mfma_f32_16x16x32_bf16 v[82:85], v[146:149], v[178:181], v[82:85]
	v_mfma_f32_16x16x32_bf16 v[70:73], v[138:141], v[186:189], v[70:73]
	v_mfma_f32_16x16x32_bf16 v[66:69], v[146:149], v[186:189], v[66:69]
	v_mfma_f32_16x16x32_bf16 v[126:129], v[142:145], v[166:169], v[126:129]
	v_mfma_f32_16x16x32_bf16 v[122:125], v[158:161], v[166:169], v[122:125]
	v_mfma_f32_16x16x32_bf16 v[102:105], v[142:145], v[174:177], v[102:105]
	v_mfma_f32_16x16x32_bf16 v[98:101], v[158:161], v[174:177], v[98:101]
	v_mfma_f32_16x16x32_bf16 v[86:89], v[142:145], v[182:185], v[86:89]
	v_mfma_f32_16x16x32_bf16 v[82:85], v[158:161], v[182:185], v[82:85]
	v_mfma_f32_16x16x32_bf16 v[70:73], v[142:145], v[190:193], v[70:73]
	v_mfma_f32_16x16x32_bf16 v[66:69], v[158:161], v[190:193], v[66:69]
	s_setprio 0
	s_barrier
	s_add_i32 s40, s54, s0
	v_lshl_add_u64 v[206:207], v[206:207], 0, s[10:11]
	s_mov_b32 m0, s40
	ds_read_b128 v[162:165], v248 offset:49152
	ds_read_b128 v[166:169], v248 offset:50176
	ds_read_b128 v[170:173], v248 offset:51200
	ds_read_b128 v[174:177], v248 offset:52224
	ds_read_b128 v[178:181], v248 offset:53248
	ds_read_b128 v[182:185], v248 offset:54272
	ds_read_b128 v[186:189], v248 offset:55296
	ds_read_b128 v[190:193], v248 offset:56320
	global_load_lds_dwordx4 v[206:207], off
	s_add_i32 m0, s40, 0x2000
	s_add_u32 s38, s38, 0x40080
	v_lshl_add_u64 v[206:207], v[208:209], 0, s[10:11]
	s_addc_u32 s39, s39, 0
	s_add_i32 s40, s55, s0
	global_load_lds_dwordx4 v[206:207], off
	v_lshl_add_u64 v[206:207], s[38:39], 0, v[196:197]
	s_mov_b32 m0, s40
	s_nop 0
	global_load_lds_dwordx4 v[206:207], off
	v_lshl_add_u64 v[206:207], s[38:39], 0, v[200:201]
	s_add_i32 m0, s40, 0x2000
	s_nop 0
	global_load_lds_dwordx4 v[206:207], off
	s_waitcnt vmcnt(4)
	s_waitcnt lgkmcnt(0)
	s_barrier
	s_setprio 1
	s_waitcnt lgkmcnt(0)
	v_mfma_f32_16x16x32_bf16 v[62:65], v[114:117], v[162:165], v[62:65]
	v_mfma_f32_16x16x32_bf16 v[58:61], v[130:133], v[162:165], v[58:61]
	v_mfma_f32_16x16x32_bf16 v[46:49], v[114:117], v[170:173], v[46:49]
	v_mfma_f32_16x16x32_bf16 v[42:45], v[130:133], v[170:173], v[42:45]
	v_mfma_f32_16x16x32_bf16 v[30:33], v[114:117], v[178:181], v[30:33]
	v_mfma_f32_16x16x32_bf16 v[26:29], v[130:133], v[178:181], v[26:29]
	v_mfma_f32_16x16x32_bf16 v[14:17], v[114:117], v[186:189], v[14:17]
	v_mfma_f32_16x16x32_bf16 v[10:13], v[130:133], v[186:189], v[10:13]
	v_mfma_f32_16x16x32_bf16 v[62:65], v[118:121], v[166:169], v[62:65]
	v_mfma_f32_16x16x32_bf16 v[58:61], v[134:137], v[166:169], v[58:61]
	v_mfma_f32_16x16x32_bf16 v[46:49], v[118:121], v[174:177], v[46:49]
	v_mfma_f32_16x16x32_bf16 v[42:45], v[134:137], v[174:177], v[42:45]
	v_mfma_f32_16x16x32_bf16 v[30:33], v[118:121], v[182:185], v[30:33]
	v_mfma_f32_16x16x32_bf16 v[26:29], v[134:137], v[182:185], v[26:29]
	v_mfma_f32_16x16x32_bf16 v[14:17], v[118:121], v[190:193], v[14:17]
	v_mfma_f32_16x16x32_bf16 v[10:13], v[134:137], v[190:193], v[10:13]
	v_mfma_f32_16x16x32_bf16 v[54:57], v[138:141], v[162:165], v[54:57]
	v_mfma_f32_16x16x32_bf16 v[50:53], v[146:149], v[162:165], v[50:53]
	v_mfma_f32_16x16x32_bf16 v[38:41], v[138:141], v[170:173], v[38:41]
	v_mfma_f32_16x16x32_bf16 v[34:37], v[146:149], v[170:173], v[34:37]
	v_mfma_f32_16x16x32_bf16 v[22:25], v[138:141], v[178:181], v[22:25]
	v_mfma_f32_16x16x32_bf16 v[18:21], v[146:149], v[178:181], v[18:21]
	v_mfma_f32_16x16x32_bf16 v[6:9], v[138:141], v[186:189], v[6:9]
	v_mfma_f32_16x16x32_bf16 v[2:5], v[146:149], v[186:189], v[2:5]
	v_mfma_f32_16x16x32_bf16 v[54:57], v[142:145], v[166:169], v[54:57]
	v_mfma_f32_16x16x32_bf16 v[50:53], v[158:161], v[166:169], v[50:53]
	v_mfma_f32_16x16x32_bf16 v[38:41], v[142:145], v[174:177], v[38:41]
	v_mfma_f32_16x16x32_bf16 v[34:37], v[158:161], v[174:177], v[34:37]
	v_mfma_f32_16x16x32_bf16 v[22:25], v[142:145], v[182:185], v[22:25]
	v_mfma_f32_16x16x32_bf16 v[18:21], v[158:161], v[182:185], v[18:21]
	v_mfma_f32_16x16x32_bf16 v[6:9], v[142:145], v[190:193], v[6:9]
	v_mfma_f32_16x16x32_bf16 v[2:5], v[158:161], v[190:193], v[2:5]
	s_setprio 0
	s_barrier
	s_add_i32 s53, s53, 2
	s_add_u32 s36, s36, 0x100
	s_addc_u32 s37, s37, 0
	s_add_u32 s51, s51, 0x100
	s_addc_u32 s52, s52, 0
	s_cmp_gt_u32 s53, 13
	s_cbranch_scc0 .LBB0_1692
	s_and_b64 vcc, exec, s[14:15]
	s_cbranch_vccz .LBB0_1695
	s_barrier

; #define PG8_STAGE(bufoff, gbase, voff) do { _Pragma("unroll") for (int _i = 0; _i < 2; ++_i) \
;         __builtin_amdgcn_global_load_lds((const unsigned*)((const char*)(gbase) + (voff)[_i]), (PG8_LAS unsigned*)(lds + (bufoff) + ldsw + _i * 8192), 16, 0, 0); } while (0)
; #define PG8_LDA(dst, b, h) do { _Pragma("unroll") for (int m = 0; m < 4; ++m) _Pragma("unroll") for (int k = 0; k < 2; ++k) dst[m][k] = *(const PG8_LAS bf16x8*)(lds + PG8_SA(b, h) + aoff + m * 2048 + k * 1024); } while (0)
; #define PG8_LDB(dst, b, h) do { _Pragma("unroll") for (int n = 0; n < 2; ++n) _Pragma("unroll") for (int k = 0; k < 2; ++k) dst[n][k] = *(const PG8_LAS bf16x8*)(lds + PG8_SB(b, h) + boff + n * 2048 + k * 1024); } while (0)
; #define PG8_MMA(ai, bj, At, Bt) do { __builtin_amdgcn_s_setprio(1); _Pragma("unroll") for (int m = 0; m < 4; ++m) _Pragma("unroll") for (int n = 0; n < 2; ++n) _Pragma("unroll") for (int k = 0; k < 2; ++k) \
;         acc[ai][bj][m][n] = __builtin_amdgcn_mfma_f32_16x16x32_bf16(Bt[n][k], At[m][k], acc[ai][bj][m][n], 0, 0, 0); __builtin_amdgcn_s_setprio(0); } while (0)
; #define PG8_WAIT_V(n) asm volatile("s_waitcnt vmcnt(" #n ")" ::: "memory")
; #define PG8_BAR __builtin_amdgcn_s_barrier()
; template <class Epi, class Sched, bool ALIGN_EPI = false, bool SP2 = false, bool HALFM = false>
; __device__ __forceinline__ void gemm_phase(PG8_LAS unsigned char* lds, const Gemm g, const Sched& S, const Epi& E) {
;     ...
;             const bool last = (t == nt - 2);
;             const char* a1 = cA + (size_t)(t + 1) * kstep;
;             const char* a2 = last ? nA : cA + (size_t)(t + 2) * kstep; const char* b2 = last ? nB : cB + (size_t)(t + 2) * kstep;
;             const char* a3 = a2 + kstep; const char* b3 = b2 + kstep;
;             if (last && has_next) S.a_ready(nxt);
;             if constexpr (SP2) {
;             PG8_LDB(B0, 0, 0); PG8_LDB(B1, 0, 1); PG8_SCHED; PG8_LDA(At, 0, 0); PG8_STAGE(PG8_SA(1, 1), a1 + hstep, voffA);
;             PG8_WAIT_V(8); PG8_WAIT_L(0); PG8_BAR; PG8_MMA(0, 0, At, B0); PG8_MMA(0, 1, At, B1); PG8_BAR; PG8_SCHED;
;             PG8_LDA(At, 0, 1); PG8_STAGE(PG8_SB(0, 0), b2, voffB); PG8_STAGE(PG8_SB(0, 1), b2 + hstep, voffB); PG8_STAGE(PG8_SA(0, 0), a2, voffA);
;             PG8_WAIT_V(8); PG8_WAIT_L(0); PG8_BAR; if constexpr (!HALFM) { PG8_MMA(1, 0, At, B0); PG8_MMA(1, 1, At, B1); } PG8_BAR; PG8_SCHED;
.LBB0_1805:
	ds_read_b128 v[154:157], v150
	ds_read_b128 v[158:161], v150 offset:1024
	ds_read_b128 v[162:165], v150 offset:2048
	ds_read_b128 v[166:169], v150 offset:3072
	ds_read_b128 v[170:173], v151
	ds_read_b128 v[174:177], v151 offset:1024
	ds_read_b128 v[178:181], v151 offset:2048
	ds_read_b128 v[182:185], v151 offset:3072
	s_add_u32 s38, s36, 0xfffc0080
	s_addc_u32 s39, s37, -1
	s_cmp_eq_u32 s57, 12
	s_cselect_b32 s41, s27, s39
	s_cselect_b32 s40, s53, s38
	s_cselect_b32 s39, s25, s56
	s_cselect_b32 s38, s54, s55
	v_lshl_add_u64 v[146:147], s[36:37], 0, v[138:139]
	s_add_i32 m0, s2, 0xc000
	ds_read_b128 v[186:189], v152
	ds_read_b128 v[190:193], v152 offset:1024
	ds_read_b128 v[194:197], v152 offset:2048
	ds_read_b128 v[198:201], v152 offset:3072
	ds_read_b128 v[202:205], v152 offset:4096
	ds_read_b128 v[206:209], v152 offset:5120
	ds_read_b128 v[210:213], v152 offset:6144
	ds_read_b128 v[214:217], v152 offset:7168
	global_load_lds_dwordx4 v[146:147], off
	v_lshl_add_u64 v[146:147], s[36:37], 0, v[140:141]
	s_add_i32 m0, s2, 0xe000
	s_nop 0
	global_load_lds_dwordx4 v[146:147], off
	s_mov_b32 m0, s44
	v_lshl_add_u64 v[146:147], v[220:221], 0, s[14:15]
	global_load_lds_dwordx4 v[146:147], off
	s_mov_b32 m0, s45
	v_lshl_add_u64 v[146:147], v[222:223], 0, s[14:15]
	global_load_lds_dwordx4 v[146:147], off
	s_waitcnt vmcnt(10)
	s_waitcnt lgkmcnt(0)
	s_barrier
	s_setprio 1
	s_waitcnt lgkmcnt(0)
	v_mfma_f32_16x16x32_bf16 v[118:121], v[154:157], v[186:189], v[118:121]
	v_mfma_f32_16x16x32_bf16 v[114:117], v[162:165], v[186:189], v[114:117]
	v_mfma_f32_16x16x32_bf16 v[110:113], v[154:157], v[194:197], v[110:113]
	v_mfma_f32_16x16x32_bf16 v[106:109], v[162:165], v[194:197], v[106:109]
	v_mfma_f32_16x16x32_bf16 v[94:97], v[154:157], v[202:205], v[94:97]
	v_mfma_f32_16x16x32_bf16 v[90:93], v[162:165], v[202:205], v[90:93]
	v_mfma_f32_16x16x32_bf16 v[78:81], v[154:157], v[210:213], v[78:81]
	v_mfma_f32_16x16x32_bf16 v[74:77], v[162:165], v[210:213], v[74:77]
	v_mfma_f32_16x16x32_bf16 v[118:121], v[158:161], v[190:193], v[118:121]
	v_mfma_f32_16x16x32_bf16 v[114:117], v[166:169], v[190:193], v[114:117]
	v_mfma_f32_16x16x32_bf16 v[110:113], v[158:161], v[198:201], v[110:113]
	v_mfma_f32_16x16x32_bf16 v[106:109], v[166:169], v[198:201], v[106:109]
	v_mfma_f32_16x16x32_bf16 v[94:97], v[158:161], v[206:209], v[94:97]
	v_mfma_f32_16x16x32_bf16 v[90:93], v[166:169], v[206:209], v[90:93]
	v_mfma_f32_16x16x32_bf16 v[78:81], v[158:161], v[214:217], v[78:81]
	v_mfma_f32_16x16x32_bf16 v[74:77], v[166:169], v[214:217], v[74:77]
	v_mfma_f32_16x16x32_bf16 v[126:129], v[170:173], v[186:189], v[126:129]
	v_mfma_f32_16x16x32_bf16 v[122:125], v[178:181], v[186:189], v[122:125]
	v_mfma_f32_16x16x32_bf16 v[102:105], v[170:173], v[194:197], v[102:105]
	v_mfma_f32_16x16x32_bf16 v[98:101], v[178:181], v[194:197], v[98:101]
	v_mfma_f32_16x16x32_bf16 v[86:89], v[170:173], v[202:205], v[86:89]
	v_mfma_f32_16x16x32_bf16 v[82:85], v[178:181], v[202:205], v[82:85]
	v_mfma_f32_16x16x32_bf16 v[70:73], v[170:173], v[210:213], v[70:73]
	v_mfma_f32_16x16x32_bf16 v[66:69], v[178:181], v[210:213], v[66:69]
	v_mfma_f32_16x16x32_bf16 v[126:129], v[174:177], v[190:193], v[126:129]
	v_mfma_f32_16x16x32_bf16 v[122:125], v[182:185], v[190:193], v[122:125]
	v_mfma_f32_16x16x32_bf16 v[102:105], v[174:177], v[198:201], v[102:105]
	v_mfma_f32_16x16x32_bf16 v[98:101], v[182:185], v[198:201], v[98:101]
	v_mfma_f32_16x16x32_bf16 v[86:89], v[174:177], v[206:209], v[86:89]
	v_mfma_f32_16x16x32_bf16 v[82:85], v[182:185], v[206:209], v[82:85]
	v_mfma_f32_16x16x32_bf16 v[70:73], v[174:177], v[214:217], v[70:73]
	v_mfma_f32_16x16x32_bf16 v[66:69], v[182:185], v[214:217], v[66:69]
	s_setprio 0
	s_barrier
	s_add_i32 s58, s49, s0
	v_lshl_add_u64 v[146:147], s[38:39], 0, v[134:135]
	s_mov_b32 m0, s58
	ds_read_b128 v[186:189], v152 offset:16384
	ds_read_b128 v[190:193], v152 offset:17408
	ds_read_b128 v[194:197], v152 offset:18432
	ds_read_b128 v[198:201], v152 offset:19456
	ds_read_b128 v[202:205], v152 offset:20480
	ds_read_b128 v[206:209], v152 offset:21504
	ds_read_b128 v[210:213], v152 offset:22528
	ds_read_b128 v[214:217], v152 offset:23552
	global_load_lds_dwordx4 v[146:147], off
	s_add_i32 m0, s58, 0x2000
	s_add_u32 s58, s38, 0x40000
	v_lshl_add_u64 v[218:219], s[38:39], 0, v[130:131]
	s_addc_u32 s59, s39, 0
	s_add_i32 s60, s50, s0
	global_load_lds_dwordx4 v[218:219], off
	v_lshl_add_u64 v[220:221], s[58:59], 0, v[134:135]
	s_mov_b32 m0, s60
	v_lshl_add_u64 v[222:223], s[40:41], 0, v[132:133]
	global_load_lds_dwordx4 v[220:221], off
	v_lshl_add_u64 v[220:221], s[58:59], 0, v[130:131]
	s_add_i32 m0, s60, 0x2000
	s_nop 0
	global_load_lds_dwordx4 v[220:221], off
	v_lshl_add_u64 v[220:221], s[40:41], 0, v[136:137]
	s_waitcnt vmcnt(4)
	s_waitcnt lgkmcnt(0)
	s_barrier
; #define PG8_STAGE(bufoff, gbase, voff) do { _Pragma("unroll") for (int _i = 0; _i < 2; ++_i) \
;         __builtin_amdgcn_global_load_lds((const unsigned*)((const char*)(gbase) + (voff)[_i]), (PG8_LAS unsigned*)(lds + (bufoff) + ldsw + _i * 8192), 16, 0, 0); } while (0)
; #define PG8_LDA(dst, b, h) do { _Pragma("unroll") for (int m = 0; m < 4; ++m) _Pragma("unroll") for (int k = 0; k < 2; ++k) dst[m][k] = *(const PG8_LAS bf16x8*)(lds + PG8_SA(b, h) + aoff + m * 2048 + k * 1024); } while (0)
; #define PG8_LDB(dst, b, h) do { _Pragma("unroll") for (int n = 0; n < 2; ++n) _Pragma("unroll") for (int k = 0; k < 2; ++k) dst[n][k] = *(const PG8_LAS bf16x8*)(lds + PG8_SB(b, h) + boff + n * 2048 + k * 1024); } while (0)
; #define PG8_MMA(ai, bj, At, Bt) do { __builtin_amdgcn_s_setprio(1); _Pragma("unroll") for (int m = 0; m < 4; ++m) _Pragma("unroll") for (int n = 0; n < 2; ++n) _Pragma("unroll") for (int k = 0; k < 2; ++k) \
;         acc[ai][bj][m][n] = __builtin_amdgcn_mfma_f32_16x16x32_bf16(Bt[n][k], At[m][k], acc[ai][bj][m][n], 0, 0, 0); __builtin_amdgcn_s_setprio(0); } while (0)
; #define PG8_WAIT_V(n) asm volatile("s_waitcnt vmcnt(" #n ")" ::: "memory")
; #define PG8_WAIT_L(n) asm volatile("s_waitcnt lgkmcnt(" #n ")" ::: "memory")
; #define PG8_BAR __builtin_amdgcn_s_barrier()
; #define PG8_SCHED __builtin_amdgcn_sched_barrier(0)
; template <class Epi, class Sched, bool ALIGN_EPI = false, bool SP2 = false, bool HALFM = false>
; __device__ __forceinline__ void gemm_phase(PG8_LAS unsigned char* lds, const Gemm g, const Sched& S, const Epi& E) {
;     ...
;             PG8_WAIT_V(8); PG8_WAIT_L(0); PG8_BAR; if constexpr (!HALFM) { PG8_MMA(1, 0, At, B0); PG8_MMA(1, 1, At, B1); } PG8_BAR; PG8_SCHED;
;             PG8_LDB(B0, 1, 0); PG8_LDB(B1, 1, 1); PG8_SCHED; PG8_LDA(At, 1, 0); PG8_STAGE(PG8_SA(0, 1), a2 + hstep, voffA);
;             PG8_WAIT_V(8); PG8_WAIT_L(0); PG8_BAR; PG8_MMA(0, 0, At, B0); PG8_MMA(0, 1, At, B1); PG8_BAR; PG8_SCHED;
	s_setprio 1
	s_waitcnt lgkmcnt(0)
	v_mfma_f32_16x16x32_bf16 v[62:65], v[154:157], v[186:189], v[62:65]
	v_mfma_f32_16x16x32_bf16 v[58:61], v[162:165], v[186:189], v[58:61]
	v_mfma_f32_16x16x32_bf16 v[46:49], v[154:157], v[194:197], v[46:49]
	v_mfma_f32_16x16x32_bf16 v[42:45], v[162:165], v[194:197], v[42:45]
	v_mfma_f32_16x16x32_bf16 v[30:33], v[154:157], v[202:205], v[30:33]
	v_mfma_f32_16x16x32_bf16 v[26:29], v[162:165], v[202:205], v[26:29]
	v_mfma_f32_16x16x32_bf16 v[14:17], v[154:157], v[210:213], v[14:17]
	v_mfma_f32_16x16x32_bf16 v[10:13], v[162:165], v[210:213], v[10:13]
	v_mfma_f32_16x16x32_bf16 v[62:65], v[158:161], v[190:193], v[62:65]
	v_mfma_f32_16x16x32_bf16 v[58:61], v[166:169], v[190:193], v[58:61]
	v_mfma_f32_16x16x32_bf16 v[46:49], v[158:161], v[198:201], v[46:49]
	v_mfma_f32_16x16x32_bf16 v[42:45], v[166:169], v[198:201], v[42:45]
	v_mfma_f32_16x16x32_bf16 v[30:33], v[158:161], v[206:209], v[30:33]
	v_mfma_f32_16x16x32_bf16 v[26:29], v[166:169], v[206:209], v[26:29]
	v_mfma_f32_16x16x32_bf16 v[14:17], v[158:161], v[214:217], v[14:17]
	v_mfma_f32_16x16x32_bf16 v[10:13], v[166:169], v[214:217], v[10:13]
	v_mfma_f32_16x16x32_bf16 v[54:57], v[170:173], v[186:189], v[54:57]
	v_mfma_f32_16x16x32_bf16 v[50:53], v[178:181], v[186:189], v[50:53]
	v_mfma_f32_16x16x32_bf16 v[38:41], v[170:173], v[194:197], v[38:41]
	v_mfma_f32_16x16x32_bf16 v[34:37], v[178:181], v[194:197], v[34:37]
	v_mfma_f32_16x16x32_bf16 v[22:25], v[170:173], v[202:205], v[22:25]
	v_mfma_f32_16x16x32_bf16 v[18:21], v[178:181], v[202:205], v[18:21]
	v_mfma_f32_16x16x32_bf16 v[6:9], v[170:173], v[210:213], v[6:9]
	v_mfma_f32_16x16x32_bf16 v[2:5], v[178:181], v[210:213], v[2:5]
	v_mfma_f32_16x16x32_bf16 v[54:57], v[174:177], v[190:193], v[54:57]
	v_mfma_f32_16x16x32_bf16 v[50:53], v[182:185], v[190:193], v[50:53]
	v_mfma_f32_16x16x32_bf16 v[38:41], v[174:177], v[198:201], v[38:41]
	v_mfma_f32_16x16x32_bf16 v[34:37], v[182:185], v[198:201], v[34:37]
	v_mfma_f32_16x16x32_bf16 v[22:25], v[174:177], v[206:209], v[22:25]
	v_mfma_f32_16x16x32_bf16 v[18:21], v[182:185], v[206:209], v[18:21]
	v_mfma_f32_16x16x32_bf16 v[6:9], v[174:177], v[214:217], v[6:9]
	v_mfma_f32_16x16x32_bf16 v[2:5], v[182:185], v[214:217], v[2:5]
	s_setprio 0
	s_barrier
	s_add_i32 s58, 0, 0x18000
	s_add_i32 s59, 0, 0x1c000
	v_add_u32_e32 v166, s58, v148
	v_add_u32_e32 v182, s59, v148
	ds_read_b128 v[154:157], v166
	ds_read_b128 v[158:161], v166 offset:1024
	ds_read_b128 v[162:165], v166 offset:2048
	ds_read_b128 v[166:169], v166 offset:3072
	ds_read_b128 v[170:173], v182
	ds_read_b128 v[174:177], v182 offset:1024
	ds_read_b128 v[178:181], v182 offset:2048
	ds_read_b128 v[182:185], v182 offset:3072
	s_add_u32 s40, s40, 0x40000
	s_addc_u32 s41, s41, 0
	s_mov_b32 m0, s35
	v_lshl_add_u64 v[224:225], s[40:41], 0, v[136:137]
	ds_read_b128 v[186:189], v152 offset:32768
	ds_read_b128 v[190:193], v152 offset:33792
	ds_read_b128 v[194:197], v152 offset:34816
	ds_read_b128 v[198:201], v152 offset:35840
	ds_read_b128 v[202:205], v152 offset:36864
	ds_read_b128 v[206:209], v152 offset:37888
	ds_read_b128 v[210:213], v152 offset:38912
	ds_read_b128 v[214:217], v152 offset:39936
	global_load_lds_dwordx4 v[224:225], off
	v_lshl_add_u64 v[224:225], s[40:41], 0, v[132:133]
	s_mov_b32 m0, s42
	s_nop 0
	global_load_lds_dwordx4 v[224:225], off
	s_mov_b32 m0, s2
	s_nop 0
	global_load_lds_dwordx4 v[220:221], off
	s_mov_b32 m0, s3
	s_nop 0
	global_load_lds_dwordx4 v[222:223], off
	s_waitcnt vmcnt(10)
	s_waitcnt lgkmcnt(0)
	s_barrier
; #define PG8_STAGE(bufoff, gbase, voff) do { _Pragma("unroll") for (int _i = 0; _i < 2; ++_i) \
;         __builtin_amdgcn_global_load_lds((const unsigned*)((const char*)(gbase) + (voff)[_i]), (PG8_LAS unsigned*)(lds + (bufoff) + ldsw + _i * 8192), 16, 0, 0); } while (0)
; #define PG8_LDA(dst, b, h) do { _Pragma("unroll") for (int m = 0; m < 4; ++m) _Pragma("unroll") for (int k = 0; k < 2; ++k) dst[m][k] = *(const PG8_LAS bf16x8*)(lds + PG8_SA(b, h) + aoff + m * 2048 + k * 1024); } while (0)
; #define PG8_MMA(ai, bj, At, Bt) do { __builtin_amdgcn_s_setprio(1); _Pragma("unroll") for (int m = 0; m < 4; ++m) _Pragma("unroll") for (int n = 0; n < 2; ++n) _Pragma("unroll") for (int k = 0; k < 2; ++k) \
;         acc[ai][bj][m][n] = __builtin_amdgcn_mfma_f32_16x16x32_bf16(Bt[n][k], At[m][k], acc[ai][bj][m][n], 0, 0, 0); __builtin_amdgcn_s_setprio(0); } while (0)
; #define PG8_WAIT_V(n) asm volatile("s_waitcnt vmcnt(" #n ")" ::: "memory")
; #define PG8_WAIT_L(n) asm volatile("s_waitcnt lgkmcnt(" #n ")" ::: "memory")
; #define PG8_BAR __builtin_amdgcn_s_barrier()
; #define PG8_SCHED __builtin_amdgcn_sched_barrier(0)
; template <class Epi, class Sched, bool ALIGN_EPI = false, bool SP2 = false, bool HALFM = false>
; __device__ __forceinline__ void gemm_phase(PG8_LAS unsigned char* lds, const Gemm g, const Sched& S, const Epi& E) {
;     ...
;             PG8_WAIT_V(8); PG8_WAIT_L(0); PG8_BAR; PG8_MMA(0, 0, At, B0); PG8_MMA(0, 1, At, B1); PG8_BAR; PG8_SCHED;
;             PG8_LDA(At, 1, 1); PG8_STAGE(PG8_SB(1, 0), b3, voffB); PG8_STAGE(PG8_SB(1, 1), b3 + hstep, voffB); PG8_STAGE(PG8_SA(1, 0), a3, voffA);
;             PG8_WAIT_V(8); PG8_WAIT_L(0); PG8_BAR; if constexpr (!HALFM) { PG8_MMA(1, 0, At, B0); PG8_MMA(1, 1, At, B1); } PG8_BAR; PG8_SCHED;
	s_setprio 1
	s_waitcnt lgkmcnt(0)
	v_mfma_f32_16x16x32_bf16 v[118:121], v[154:157], v[186:189], v[118:121]
	v_mfma_f32_16x16x32_bf16 v[114:117], v[162:165], v[186:189], v[114:117]
	v_mfma_f32_16x16x32_bf16 v[110:113], v[154:157], v[194:197], v[110:113]
	v_mfma_f32_16x16x32_bf16 v[106:109], v[162:165], v[194:197], v[106:109]
	v_mfma_f32_16x16x32_bf16 v[94:97], v[154:157], v[202:205], v[94:97]
	v_mfma_f32_16x16x32_bf16 v[90:93], v[162:165], v[202:205], v[90:93]
	v_mfma_f32_16x16x32_bf16 v[78:81], v[154:157], v[210:213], v[78:81]
	v_mfma_f32_16x16x32_bf16 v[74:77], v[162:165], v[210:213], v[74:77]
	v_mfma_f32_16x16x32_bf16 v[118:121], v[158:161], v[190:193], v[118:121]
	v_mfma_f32_16x16x32_bf16 v[114:117], v[166:169], v[190:193], v[114:117]
	v_mfma_f32_16x16x32_bf16 v[110:113], v[158:161], v[198:201], v[110:113]
	v_mfma_f32_16x16x32_bf16 v[106:109], v[166:169], v[198:201], v[106:109]
	v_mfma_f32_16x16x32_bf16 v[94:97], v[158:161], v[206:209], v[94:97]
	v_mfma_f32_16x16x32_bf16 v[90:93], v[166:169], v[206:209], v[90:93]
	v_mfma_f32_16x16x32_bf16 v[78:81], v[158:161], v[214:217], v[78:81]
	v_mfma_f32_16x16x32_bf16 v[74:77], v[166:169], v[214:217], v[74:77]
	v_mfma_f32_16x16x32_bf16 v[126:129], v[170:173], v[186:189], v[126:129]
	v_mfma_f32_16x16x32_bf16 v[122:125], v[178:181], v[186:189], v[122:125]
	v_mfma_f32_16x16x32_bf16 v[102:105], v[170:173], v[194:197], v[102:105]
	v_mfma_f32_16x16x32_bf16 v[98:101], v[178:181], v[194:197], v[98:101]
	v_mfma_f32_16x16x32_bf16 v[86:89], v[170:173], v[202:205], v[86:89]
	v_mfma_f32_16x16x32_bf16 v[82:85], v[178:181], v[202:205], v[82:85]
	v_mfma_f32_16x16x32_bf16 v[70:73], v[170:173], v[210:213], v[70:73]
	v_mfma_f32_16x16x32_bf16 v[66:69], v[178:181], v[210:213], v[66:69]
	v_mfma_f32_16x16x32_bf16 v[126:129], v[174:177], v[190:193], v[126:129]
	v_mfma_f32_16x16x32_bf16 v[122:125], v[182:185], v[190:193], v[122:125]
	v_mfma_f32_16x16x32_bf16 v[102:105], v[174:177], v[198:201], v[102:105]
	v_mfma_f32_16x16x32_bf16 v[98:101], v[182:185], v[198:201], v[98:101]
	v_mfma_f32_16x16x32_bf16 v[86:89], v[174:177], v[206:209], v[86:89]
	v_mfma_f32_16x16x32_bf16 v[82:85], v[182:185], v[206:209], v[82:85]
	v_mfma_f32_16x16x32_bf16 v[70:73], v[174:177], v[214:217], v[70:73]
	v_mfma_f32_16x16x32_bf16 v[66:69], v[182:185], v[214:217], v[66:69]
	s_setprio 0
	s_barrier
	s_add_i32 s40, s58, s0
	v_lshl_add_u64 v[146:147], v[146:147], 0, s[14:15]
	s_mov_b32 m0, s40
	ds_read_b128 v[186:189], v152 offset:49152
	ds_read_b128 v[190:193], v152 offset:50176
	ds_read_b128 v[194:197], v152 offset:51200
	ds_read_b128 v[198:201], v152 offset:52224
	ds_read_b128 v[202:205], v152 offset:53248
	ds_read_b128 v[206:209], v152 offset:54272
	ds_read_b128 v[210:213], v152 offset:55296
	ds_read_b128 v[214:217], v152 offset:56320
	global_load_lds_dwordx4 v[146:147], off
	s_add_i32 m0, s40, 0x2000
	s_add_u32 s38, s38, 0x40080
	v_lshl_add_u64 v[146:147], v[218:219], 0, s[14:15]
	s_addc_u32 s39, s39, 0
	s_add_i32 s40, s59, s0
	global_load_lds_dwordx4 v[146:147], off
	v_lshl_add_u64 v[146:147], s[38:39], 0, v[134:135]
	s_mov_b32 m0, s40
	s_nop 0
	global_load_lds_dwordx4 v[146:147], off
	v_lshl_add_u64 v[146:147], s[38:39], 0, v[130:131]
	s_add_i32 m0, s40, 0x2000
	s_nop 0
	global_load_lds_dwordx4 v[146:147], off
	s_waitcnt vmcnt(4)
	s_waitcnt lgkmcnt(0)
	s_barrier
	s_setprio 1
	s_waitcnt lgkmcnt(0)
	v_mfma_f32_16x16x32_bf16 v[62:65], v[154:157], v[186:189], v[62:65]
	v_mfma_f32_16x16x32_bf16 v[58:61], v[162:165], v[186:189], v[58:61]
	v_mfma_f32_16x16x32_bf16 v[46:49], v[154:157], v[194:197], v[46:49]
	v_mfma_f32_16x16x32_bf16 v[42:45], v[162:165], v[194:197], v[42:45]
	v_mfma_f32_16x16x32_bf16 v[30:33], v[154:157], v[202:205], v[30:33]
	v_mfma_f32_16x16x32_bf16 v[26:29], v[162:165], v[202:205], v[26:29]
	v_mfma_f32_16x16x32_bf16 v[14:17], v[154:157], v[210:213], v[14:17]
	v_mfma_f32_16x16x32_bf16 v[10:13], v[162:165], v[210:213], v[10:13]
	v_mfma_f32_16x16x32_bf16 v[62:65], v[158:161], v[190:193], v[62:65]
	v_mfma_f32_16x16x32_bf16 v[58:61], v[166:169], v[190:193], v[58:61]
	v_mfma_f32_16x16x32_bf16 v[46:49], v[158:161], v[198:201], v[46:49]
	v_mfma_f32_16x16x32_bf16 v[42:45], v[166:169], v[198:201], v[42:45]
	v_mfma_f32_16x16x32_bf16 v[30:33], v[158:161], v[206:209], v[30:33]
	v_mfma_f32_16x16x32_bf16 v[26:29], v[166:169], v[206:209], v[26:29]
	v_mfma_f32_16x16x32_bf16 v[14:17], v[158:161], v[214:217], v[14:17]
	v_mfma_f32_16x16x32_bf16 v[10:13], v[166:169], v[214:217], v[10:13]
	v_mfma_f32_16x16x32_bf16 v[54:57], v[170:173], v[186:189], v[54:57]
	v_mfma_f32_16x16x32_bf16 v[50:53], v[178:181], v[186:189], v[50:53]
	v_mfma_f32_16x16x32_bf16 v[38:41], v[170:173], v[194:197], v[38:41]
	v_mfma_f32_16x16x32_bf16 v[34:37], v[178:181], v[194:197], v[34:37]
	v_mfma_f32_16x16x32_bf16 v[22:25], v[170:173], v[202:205], v[22:25]
	v_mfma_f32_16x16x32_bf16 v[18:21], v[178:181], v[202:205], v[18:21]
	v_mfma_f32_16x16x32_bf16 v[6:9], v[170:173], v[210:213], v[6:9]
	v_mfma_f32_16x16x32_bf16 v[2:5], v[178:181], v[210:213], v[2:5]
	v_mfma_f32_16x16x32_bf16 v[54:57], v[174:177], v[190:193], v[54:57]
	v_mfma_f32_16x16x32_bf16 v[50:53], v[182:185], v[190:193], v[50:53]
	v_mfma_f32_16x16x32_bf16 v[38:41], v[174:177], v[198:201], v[38:41]
	v_mfma_f32_16x16x32_bf16 v[34:37], v[182:185], v[198:201], v[34:37]
	v_mfma_f32_16x16x32_bf16 v[22:25], v[174:177], v[206:209], v[22:25]
	v_mfma_f32_16x16x32_bf16 v[18:21], v[182:185], v[206:209], v[18:21]
	v_mfma_f32_16x16x32_bf16 v[6:9], v[174:177], v[214:217], v[6:9]
	v_mfma_f32_16x16x32_bf16 v[2:5], v[182:185], v[214:217], v[2:5]
	s_setprio 0
	s_barrier
	s_add_i32 s57, s57, 2
	s_add_u32 s36, s36, 0x100
	s_addc_u32 s37, s37, 0
	s_add_u32 s55, s55, 0x100
	s_addc_u32 s56, s56, 0
	s_cmp_gt_u32 s57, 13
	s_cbranch_scc0 .LBB0_1805
	s_and_b64 vcc, exec, s[22:23]
	s_cbranch_vccz .LBB0_1808
	s_barrier

; #define PG8_STAGE(bufoff, gbase, voff) do { _Pragma("unroll") for (int _i = 0; _i < 2; ++_i) \
;         __builtin_amdgcn_global_load_lds((const unsigned*)((const char*)(gbase) + (voff)[_i]), (PG8_LAS unsigned*)(lds + (bufoff) + ldsw + _i * 8192), 16, 0, 0); } while (0)
; #define PG8_LDA(dst, b, h) do { _Pragma("unroll") for (int m = 0; m < 4; ++m) _Pragma("unroll") for (int k = 0; k < 2; ++k) dst[m][k] = *(const PG8_LAS bf16x8*)(lds + PG8_SA(b, h) + aoff + m * 2048 + k * 1024); } while (0)
; #define PG8_LDB(dst, b, h) do { _Pragma("unroll") for (int n = 0; n < 2; ++n) _Pragma("unroll") for (int k = 0; k < 2; ++k) dst[n][k] = *(const PG8_LAS bf16x8*)(lds + PG8_SB(b, h) + boff + n * 2048 + k * 1024); } while (0)
; #define PG8_MMA(ai, bj, At, Bt) do { __builtin_amdgcn_s_setprio(1); _Pragma("unroll") for (int m = 0; m < 4; ++m) _Pragma("unroll") for (int n = 0; n < 2; ++n) _Pragma("unroll") for (int k = 0; k < 2; ++k) \
;         acc[ai][bj][m][n] = __builtin_amdgcn_mfma_f32_16x16x32_bf16(Bt[n][k], At[m][k], acc[ai][bj][m][n], 0, 0, 0); __builtin_amdgcn_s_setprio(0); } while (0)
; #define PG8_WAIT_V(n) asm volatile("s_waitcnt vmcnt(" #n ")" ::: "memory")
; #define PG8_BAR __builtin_amdgcn_s_barrier()
; template <class Epi, class Sched, bool ALIGN_EPI = false, bool SP2 = false, bool HALFM = false>
; __device__ __forceinline__ void gemm_phase(PG8_LAS unsigned char* lds, const Gemm g, const Sched& S, const Epi& E) {
;     ...
;             const bool last = (t == nt - 2);
;             const char* a1 = cA + (size_t)(t + 1) * kstep;
;             const char* a2 = last ? nA : cA + (size_t)(t + 2) * kstep; const char* b2 = last ? nB : cB + (size_t)(t + 2) * kstep;
;             const char* a3 = a2 + kstep; const char* b3 = b2 + kstep;
;             if (last && has_next) S.a_ready(nxt);
;             if constexpr (SP2) {
;             PG8_LDB(B0, 0, 0); PG8_LDB(B1, 0, 1); PG8_SCHED; PG8_LDA(At, 0, 0); PG8_STAGE(PG8_SA(1, 1), a1 + hstep, voffA);
;             PG8_WAIT_V(8); PG8_WAIT_L(0); PG8_BAR; PG8_MMA(0, 0, At, B0); PG8_MMA(0, 1, At, B1); PG8_BAR; PG8_SCHED;
;             PG8_LDA(At, 0, 1); PG8_STAGE(PG8_SB(0, 0), b2, voffB); PG8_STAGE(PG8_SB(0, 1), b2 + hstep, voffB); PG8_STAGE(PG8_SA(0, 0), a2, voffA);
;             PG8_WAIT_V(8); PG8_WAIT_L(0); PG8_BAR; if constexpr (!HALFM) { PG8_MMA(1, 0, At, B0); PG8_MMA(1, 1, At, B1); } PG8_BAR; PG8_SCHED;
.LBB0_1928:
	ds_read_b128 v[114:117], v246
	ds_read_b128 v[118:121], v246 offset:1024
	ds_read_b128 v[130:133], v246 offset:2048
	ds_read_b128 v[134:137], v246 offset:3072
	ds_read_b128 v[138:141], v247
	ds_read_b128 v[142:145], v247 offset:1024
	ds_read_b128 v[146:149], v247 offset:2048
	ds_read_b128 v[158:161], v247 offset:3072
	s_add_u32 s34, s30, 0x100
	s_addc_u32 s35, s31, 0
	s_cmp_eq_u32 s55, 40
	s_cselect_b32 s39, s15, s35
	s_cselect_b32 s38, s14, s34
	s_cselect_b32 s37, s29, s54
	s_cselect_b32 s36, s28, s53
	v_lshl_add_u64 v[206:207], s[30:31], 0, v[202:203]
	s_add_i32 m0, s1, 0xc000
	ds_read_b128 v[162:165], v248
	ds_read_b128 v[166:169], v248 offset:1024
	ds_read_b128 v[170:173], v248 offset:2048
	ds_read_b128 v[174:177], v248 offset:3072
	ds_read_b128 v[178:181], v248 offset:4096
	ds_read_b128 v[182:185], v248 offset:5120
	ds_read_b128 v[186:189], v248 offset:6144
	ds_read_b128 v[190:193], v248 offset:7168
	global_load_lds_dwordx4 v[206:207], off
	v_lshl_add_u64 v[206:207], s[30:31], 0, v[204:205]
	s_add_i32 m0, s1, 0xe000
	s_nop 0
	global_load_lds_dwordx4 v[206:207], off
	s_mov_b32 m0, s44
	v_lshl_add_u64 v[206:207], v[210:211], 0, s[24:25]
	global_load_lds_dwordx4 v[206:207], off
	s_mov_b32 m0, s45
	v_lshl_add_u64 v[206:207], v[212:213], 0, s[24:25]
	global_load_lds_dwordx4 v[206:207], off
	s_waitcnt vmcnt(10)
	s_waitcnt lgkmcnt(0)
	s_barrier
	s_setprio 1
	s_waitcnt lgkmcnt(0)
	v_mfma_f32_16x16x32_bf16 v[154:157], v[114:117], v[162:165], v[154:157]
	v_mfma_f32_16x16x32_bf16 v[150:153], v[130:133], v[162:165], v[150:153]
	v_mfma_f32_16x16x32_bf16 v[110:113], v[114:117], v[170:173], v[110:113]
	v_mfma_f32_16x16x32_bf16 v[106:109], v[130:133], v[170:173], v[106:109]
	v_mfma_f32_16x16x32_bf16 v[94:97], v[114:117], v[178:181], v[94:97]
	v_mfma_f32_16x16x32_bf16 v[90:93], v[130:133], v[178:181], v[90:93]
	v_mfma_f32_16x16x32_bf16 v[78:81], v[114:117], v[186:189], v[78:81]
	v_mfma_f32_16x16x32_bf16 v[74:77], v[130:133], v[186:189], v[74:77]
	v_mfma_f32_16x16x32_bf16 v[154:157], v[118:121], v[166:169], v[154:157]
	v_mfma_f32_16x16x32_bf16 v[150:153], v[134:137], v[166:169], v[150:153]
	v_mfma_f32_16x16x32_bf16 v[110:113], v[118:121], v[174:177], v[110:113]
	v_mfma_f32_16x16x32_bf16 v[106:109], v[134:137], v[174:177], v[106:109]
	v_mfma_f32_16x16x32_bf16 v[94:97], v[118:121], v[182:185], v[94:97]
	v_mfma_f32_16x16x32_bf16 v[90:93], v[134:137], v[182:185], v[90:93]
	v_mfma_f32_16x16x32_bf16 v[78:81], v[118:121], v[190:193], v[78:81]
	v_mfma_f32_16x16x32_bf16 v[74:77], v[134:137], v[190:193], v[74:77]
	v_mfma_f32_16x16x32_bf16 v[126:129], v[138:141], v[162:165], v[126:129]
	v_mfma_f32_16x16x32_bf16 v[122:125], v[146:149], v[162:165], v[122:125]
	v_mfma_f32_16x16x32_bf16 v[102:105], v[138:141], v[170:173], v[102:105]
	v_mfma_f32_16x16x32_bf16 v[98:101], v[146:149], v[170:173], v[98:101]
	v_mfma_f32_16x16x32_bf16 v[86:89], v[138:141], v[178:181], v[86:89]
	v_mfma_f32_16x16x32_bf16 v[82:85], v[146:149], v[178:181], v[82:85]
	v_mfma_f32_16x16x32_bf16 v[70:73], v[138:141], v[186:189], v[70:73]
	v_mfma_f32_16x16x32_bf16 v[66:69], v[146:149], v[186:189], v[66:69]
	v_mfma_f32_16x16x32_bf16 v[126:129], v[142:145], v[166:169], v[126:129]
	v_mfma_f32_16x16x32_bf16 v[122:125], v[158:161], v[166:169], v[122:125]
	v_mfma_f32_16x16x32_bf16 v[102:105], v[142:145], v[174:177], v[102:105]
	v_mfma_f32_16x16x32_bf16 v[98:101], v[158:161], v[174:177], v[98:101]
	v_mfma_f32_16x16x32_bf16 v[86:89], v[142:145], v[182:185], v[86:89]
	v_mfma_f32_16x16x32_bf16 v[82:85], v[158:161], v[182:185], v[82:85]
	v_mfma_f32_16x16x32_bf16 v[70:73], v[142:145], v[190:193], v[70:73]
	v_mfma_f32_16x16x32_bf16 v[66:69], v[158:161], v[190:193], v[66:69]
	s_setprio 0
	s_barrier
	s_add_i32 s30, s47, s0
	v_lshl_add_u64 v[206:207], s[36:37], 0, v[196:197]
	s_mov_b32 m0, s30
	ds_read_b128 v[162:165], v248 offset:16384
	ds_read_b128 v[166:169], v248 offset:17408
	ds_read_b128 v[170:173], v248 offset:18432
	ds_read_b128 v[174:177], v248 offset:19456
	ds_read_b128 v[178:181], v248 offset:20480
	ds_read_b128 v[182:185], v248 offset:21504
	ds_read_b128 v[186:189], v248 offset:22528
	ds_read_b128 v[190:193], v248 offset:23552
	global_load_lds_dwordx4 v[206:207], off
	s_add_i32 m0, s30, 0x2000
	s_add_u32 s30, s36, 0xb0000
	v_lshl_add_u64 v[208:209], s[36:37], 0, v[200:201]
	s_addc_u32 s31, s37, 0
	s_add_i32 s56, s48, s0
	global_load_lds_dwordx4 v[208:209], off
	v_lshl_add_u64 v[210:211], s[30:31], 0, v[196:197]
	s_mov_b32 m0, s56
	v_lshl_add_u64 v[212:213], s[38:39], 0, v[198:199]
	global_load_lds_dwordx4 v[210:211], off
	v_lshl_add_u64 v[210:211], s[30:31], 0, v[200:201]
	s_add_i32 m0, s56, 0x2000
	s_nop 0
	global_load_lds_dwordx4 v[210:211], off
	v_lshl_add_u64 v[210:211], s[38:39], 0, v[194:195]
	s_waitcnt vmcnt(4)
	s_waitcnt lgkmcnt(0)
	s_barrier
; #define PG8_STAGE(bufoff, gbase, voff) do { _Pragma("unroll") for (int _i = 0; _i < 2; ++_i) \
;         __builtin_amdgcn_global_load_lds((const unsigned*)((const char*)(gbase) + (voff)[_i]), (PG8_LAS unsigned*)(lds + (bufoff) + ldsw + _i * 8192), 16, 0, 0); } while (0)
; #define PG8_LDA(dst, b, h) do { _Pragma("unroll") for (int m = 0; m < 4; ++m) _Pragma("unroll") for (int k = 0; k < 2; ++k) dst[m][k] = *(const PG8_LAS bf16x8*)(lds + PG8_SA(b, h) + aoff + m * 2048 + k * 1024); } while (0)
; #define PG8_LDB(dst, b, h) do { _Pragma("unroll") for (int n = 0; n < 2; ++n) _Pragma("unroll") for (int k = 0; k < 2; ++k) dst[n][k] = *(const PG8_LAS bf16x8*)(lds + PG8_SB(b, h) + boff + n * 2048 + k * 1024); } while (0)
; #define PG8_MMA(ai, bj, At, Bt) do { __builtin_amdgcn_s_setprio(1); _Pragma("unroll") for (int m = 0; m < 4; ++m) _Pragma("unroll") for (int n = 0; n < 2; ++n) _Pragma("unroll") for (int k = 0; k < 2; ++k) \
;         acc[ai][bj][m][n] = __builtin_amdgcn_mfma_f32_16x16x32_bf16(Bt[n][k], At[m][k], acc[ai][bj][m][n], 0, 0, 0); __builtin_amdgcn_s_setprio(0); } while (0)
; #define PG8_WAIT_V(n) asm volatile("s_waitcnt vmcnt(" #n ")" ::: "memory")
; #define PG8_WAIT_L(n) asm volatile("s_waitcnt lgkmcnt(" #n ")" ::: "memory")
; #define PG8_BAR __builtin_amdgcn_s_barrier()
; #define PG8_SCHED __builtin_amdgcn_sched_barrier(0)
; template <class Epi, class Sched, bool ALIGN_EPI = false, bool SP2 = false, bool HALFM = false>
; __device__ __forceinline__ void gemm_phase(PG8_LAS unsigned char* lds, const Gemm g, const Sched& S, const Epi& E) {
;     ...
;             PG8_WAIT_V(8); PG8_WAIT_L(0); PG8_BAR; if constexpr (!HALFM) { PG8_MMA(1, 0, At, B0); PG8_MMA(1, 1, At, B1); } PG8_BAR; PG8_SCHED;
;             PG8_LDB(B0, 1, 0); PG8_LDB(B1, 1, 1); PG8_SCHED; PG8_LDA(At, 1, 0); PG8_STAGE(PG8_SA(0, 1), a2 + hstep, voffA);
;             PG8_WAIT_V(8); PG8_WAIT_L(0); PG8_BAR; PG8_MMA(0, 0, At, B0); PG8_MMA(0, 1, At, B1); PG8_BAR; PG8_SCHED;
	s_setprio 1
	s_waitcnt lgkmcnt(0)
	v_mfma_f32_16x16x32_bf16 v[62:65], v[114:117], v[162:165], v[62:65]
	v_mfma_f32_16x16x32_bf16 v[58:61], v[130:133], v[162:165], v[58:61]
	v_mfma_f32_16x16x32_bf16 v[46:49], v[114:117], v[170:173], v[46:49]
	v_mfma_f32_16x16x32_bf16 v[42:45], v[130:133], v[170:173], v[42:45]
	v_mfma_f32_16x16x32_bf16 v[30:33], v[114:117], v[178:181], v[30:33]
	v_mfma_f32_16x16x32_bf16 v[26:29], v[130:133], v[178:181], v[26:29]
	v_mfma_f32_16x16x32_bf16 v[14:17], v[114:117], v[186:189], v[14:17]
	v_mfma_f32_16x16x32_bf16 v[10:13], v[130:133], v[186:189], v[10:13]
	v_mfma_f32_16x16x32_bf16 v[62:65], v[118:121], v[166:169], v[62:65]
	v_mfma_f32_16x16x32_bf16 v[58:61], v[134:137], v[166:169], v[58:61]
	v_mfma_f32_16x16x32_bf16 v[46:49], v[118:121], v[174:177], v[46:49]
	v_mfma_f32_16x16x32_bf16 v[42:45], v[134:137], v[174:177], v[42:45]
	v_mfma_f32_16x16x32_bf16 v[30:33], v[118:121], v[182:185], v[30:33]
	v_mfma_f32_16x16x32_bf16 v[26:29], v[134:137], v[182:185], v[26:29]
	v_mfma_f32_16x16x32_bf16 v[14:17], v[118:121], v[190:193], v[14:17]
	v_mfma_f32_16x16x32_bf16 v[10:13], v[134:137], v[190:193], v[10:13]
	v_mfma_f32_16x16x32_bf16 v[54:57], v[138:141], v[162:165], v[54:57]
	v_mfma_f32_16x16x32_bf16 v[50:53], v[146:149], v[162:165], v[50:53]
	v_mfma_f32_16x16x32_bf16 v[38:41], v[138:141], v[170:173], v[38:41]
	v_mfma_f32_16x16x32_bf16 v[34:37], v[146:149], v[170:173], v[34:37]
	v_mfma_f32_16x16x32_bf16 v[22:25], v[138:141], v[178:181], v[22:25]
	v_mfma_f32_16x16x32_bf16 v[18:21], v[146:149], v[178:181], v[18:21]
	v_mfma_f32_16x16x32_bf16 v[6:9], v[138:141], v[186:189], v[6:9]
	v_mfma_f32_16x16x32_bf16 v[2:5], v[146:149], v[186:189], v[2:5]
	v_mfma_f32_16x16x32_bf16 v[54:57], v[142:145], v[166:169], v[54:57]
	v_mfma_f32_16x16x32_bf16 v[50:53], v[158:161], v[166:169], v[50:53]
	v_mfma_f32_16x16x32_bf16 v[38:41], v[142:145], v[174:177], v[38:41]
	v_mfma_f32_16x16x32_bf16 v[34:37], v[158:161], v[174:177], v[34:37]
	v_mfma_f32_16x16x32_bf16 v[22:25], v[142:145], v[182:185], v[22:25]
	v_mfma_f32_16x16x32_bf16 v[18:21], v[158:161], v[182:185], v[18:21]
	v_mfma_f32_16x16x32_bf16 v[6:9], v[142:145], v[190:193], v[6:9]
	v_mfma_f32_16x16x32_bf16 v[2:5], v[158:161], v[190:193], v[2:5]
	s_setprio 0
	s_barrier
	s_add_i32 s56, 0, 0x18000
	s_add_i32 s57, 0, 0x1c000
	v_add_u32_e32 v134, s56, v244
	v_add_u32_e32 v158, s57, v244
	ds_read_b128 v[114:117], v134
	ds_read_b128 v[118:121], v134 offset:1024
	ds_read_b128 v[130:133], v134 offset:2048
	ds_read_b128 v[134:137], v134 offset:3072
	ds_read_b128 v[138:141], v158
	ds_read_b128 v[142:145], v158 offset:1024
	ds_read_b128 v[146:149], v158 offset:2048
	ds_read_b128 v[158:161], v158 offset:3072
	s_add_u32 s30, s38, 0xb0000
	s_addc_u32 s31, s39, 0
	s_mov_b32 m0, s3
	v_lshl_add_u64 v[214:215], s[30:31], 0, v[194:195]
	ds_read_b128 v[162:165], v248 offset:32768
	ds_read_b128 v[166:169], v248 offset:33792
	ds_read_b128 v[170:173], v248 offset:34816
	ds_read_b128 v[174:177], v248 offset:35840
	ds_read_b128 v[178:181], v248 offset:36864
	ds_read_b128 v[182:185], v248 offset:37888
	ds_read_b128 v[186:189], v248 offset:38912
	ds_read_b128 v[190:193], v248 offset:39936
	global_load_lds_dwordx4 v[214:215], off
	v_lshl_add_u64 v[214:215], s[30:31], 0, v[198:199]
	s_mov_b32 m0, s40
	s_nop 0
	global_load_lds_dwordx4 v[214:215], off
	s_mov_b32 m0, s1
	s_nop 0
	global_load_lds_dwordx4 v[210:211], off
	s_mov_b32 m0, s2
	s_nop 0
	global_load_lds_dwordx4 v[212:213], off
	s_waitcnt vmcnt(10)
	s_waitcnt lgkmcnt(0)
	s_barrier
; #define PG8_STAGE(bufoff, gbase, voff) do { _Pragma("unroll") for (int _i = 0; _i < 2; ++_i) \
;         __builtin_amdgcn_global_load_lds((const unsigned*)((const char*)(gbase) + (voff)[_i]), (PG8_LAS unsigned*)(lds + (bufoff) + ldsw + _i * 8192), 16, 0, 0); } while (0)
; #define PG8_LDA(dst, b, h) do { _Pragma("unroll") for (int m = 0; m < 4; ++m) _Pragma("unroll") for (int k = 0; k < 2; ++k) dst[m][k] = *(const PG8_LAS bf16x8*)(lds + PG8_SA(b, h) + aoff + m * 2048 + k * 1024); } while (0)
; #define PG8_MMA(ai, bj, At, Bt) do { __builtin_amdgcn_s_setprio(1); _Pragma("unroll") for (int m = 0; m < 4; ++m) _Pragma("unroll") for (int n = 0; n < 2; ++n) _Pragma("unroll") for (int k = 0; k < 2; ++k) \
;         acc[ai][bj][m][n] = __builtin_amdgcn_mfma_f32_16x16x32_bf16(Bt[n][k], At[m][k], acc[ai][bj][m][n], 0, 0, 0); __builtin_amdgcn_s_setprio(0); } while (0)
; #define PG8_WAIT_V(n) asm volatile("s_waitcnt vmcnt(" #n ")" ::: "memory")
; #define PG8_WAIT_L(n) asm volatile("s_waitcnt lgkmcnt(" #n ")" ::: "memory")
; #define PG8_BAR __builtin_amdgcn_s_barrier()
; #define PG8_SCHED __builtin_amdgcn_sched_barrier(0)
; template <class Epi, class Sched, bool ALIGN_EPI = false, bool SP2 = false, bool HALFM = false>
; __device__ __forceinline__ void gemm_phase(PG8_LAS unsigned char* lds, const Gemm g, const Sched& S, const Epi& E) {
;     ...
;             PG8_WAIT_V(8); PG8_WAIT_L(0); PG8_BAR; PG8_MMA(0, 0, At, B0); PG8_MMA(0, 1, At, B1); PG8_BAR; PG8_SCHED;
;             PG8_LDA(At, 1, 1); PG8_STAGE(PG8_SB(1, 0), b3, voffB); PG8_STAGE(PG8_SB(1, 1), b3 + hstep, voffB); PG8_STAGE(PG8_SA(1, 0), a3, voffA);
;             PG8_WAIT_V(8); PG8_WAIT_L(0); PG8_BAR; if constexpr (!HALFM) { PG8_MMA(1, 0, At, B0); PG8_MMA(1, 1, At, B1); } PG8_BAR; PG8_SCHED;
	s_setprio 1
	s_waitcnt lgkmcnt(0)
	v_mfma_f32_16x16x32_bf16 v[154:157], v[114:117], v[162:165], v[154:157]
	v_mfma_f32_16x16x32_bf16 v[150:153], v[130:133], v[162:165], v[150:153]
	v_mfma_f32_16x16x32_bf16 v[110:113], v[114:117], v[170:173], v[110:113]
	v_mfma_f32_16x16x32_bf16 v[106:109], v[130:133], v[170:173], v[106:109]
	v_mfma_f32_16x16x32_bf16 v[94:97], v[114:117], v[178:181], v[94:97]
	v_mfma_f32_16x16x32_bf16 v[90:93], v[130:133], v[178:181], v[90:93]
	v_mfma_f32_16x16x32_bf16 v[78:81], v[114:117], v[186:189], v[78:81]
	v_mfma_f32_16x16x32_bf16 v[74:77], v[130:133], v[186:189], v[74:77]
	v_mfma_f32_16x16x32_bf16 v[154:157], v[118:121], v[166:169], v[154:157]
	v_mfma_f32_16x16x32_bf16 v[150:153], v[134:137], v[166:169], v[150:153]
	v_mfma_f32_16x16x32_bf16 v[110:113], v[118:121], v[174:177], v[110:113]
	v_mfma_f32_16x16x32_bf16 v[106:109], v[134:137], v[174:177], v[106:109]
	v_mfma_f32_16x16x32_bf16 v[94:97], v[118:121], v[182:185], v[94:97]
	v_mfma_f32_16x16x32_bf16 v[90:93], v[134:137], v[182:185], v[90:93]
	v_mfma_f32_16x16x32_bf16 v[78:81], v[118:121], v[190:193], v[78:81]
	v_mfma_f32_16x16x32_bf16 v[74:77], v[134:137], v[190:193], v[74:77]
	v_mfma_f32_16x16x32_bf16 v[126:129], v[138:141], v[162:165], v[126:129]
	v_mfma_f32_16x16x32_bf16 v[122:125], v[146:149], v[162:165], v[122:125]
	v_mfma_f32_16x16x32_bf16 v[102:105], v[138:141], v[170:173], v[102:105]
	v_mfma_f32_16x16x32_bf16 v[98:101], v[146:149], v[170:173], v[98:101]
	v_mfma_f32_16x16x32_bf16 v[86:89], v[138:141], v[178:181], v[86:89]
	v_mfma_f32_16x16x32_bf16 v[82:85], v[146:149], v[178:181], v[82:85]
	v_mfma_f32_16x16x32_bf16 v[70:73], v[138:141], v[186:189], v[70:73]
	v_mfma_f32_16x16x32_bf16 v[66:69], v[146:149], v[186:189], v[66:69]
	v_mfma_f32_16x16x32_bf16 v[126:129], v[142:145], v[166:169], v[126:129]
	v_mfma_f32_16x16x32_bf16 v[122:125], v[158:161], v[166:169], v[122:125]
	v_mfma_f32_16x16x32_bf16 v[102:105], v[142:145], v[174:177], v[102:105]
	v_mfma_f32_16x16x32_bf16 v[98:101], v[158:161], v[174:177], v[98:101]
	v_mfma_f32_16x16x32_bf16 v[86:89], v[142:145], v[182:185], v[86:89]
	v_mfma_f32_16x16x32_bf16 v[82:85], v[158:161], v[182:185], v[82:85]
	v_mfma_f32_16x16x32_bf16 v[70:73], v[142:145], v[190:193], v[70:73]
	v_mfma_f32_16x16x32_bf16 v[66:69], v[158:161], v[190:193], v[66:69]
	s_setprio 0
	s_barrier
	s_add_i32 s30, s56, s0
	v_lshl_add_u64 v[206:207], v[206:207], 0, s[24:25]
	s_mov_b32 m0, s30
	ds_read_b128 v[162:165], v248 offset:49152
	ds_read_b128 v[166:169], v248 offset:50176
	ds_read_b128 v[170:173], v248 offset:51200
	ds_read_b128 v[174:177], v248 offset:52224
	ds_read_b128 v[178:181], v248 offset:53248
	ds_read_b128 v[182:185], v248 offset:54272
	ds_read_b128 v[186:189], v248 offset:55296
	ds_read_b128 v[190:193], v248 offset:56320
	global_load_lds_dwordx4 v[206:207], off
	s_add_i32 m0, s30, 0x2000
	s_add_u32 s30, s36, 0xb0080
	v_lshl_add_u64 v[206:207], v[208:209], 0, s[24:25]
	s_addc_u32 s31, s37, 0
	s_add_i32 s36, s57, s0
	global_load_lds_dwordx4 v[206:207], off
	v_lshl_add_u64 v[206:207], s[30:31], 0, v[196:197]
	s_mov_b32 m0, s36
	s_nop 0
	global_load_lds_dwordx4 v[206:207], off
	v_lshl_add_u64 v[206:207], s[30:31], 0, v[200:201]
	s_add_i32 m0, s36, 0x2000
	s_nop 0
	global_load_lds_dwordx4 v[206:207], off
	s_waitcnt vmcnt(4)
	s_waitcnt lgkmcnt(0)
	s_barrier
	s_setprio 1
	s_waitcnt lgkmcnt(0)
	v_mfma_f32_16x16x32_bf16 v[62:65], v[114:117], v[162:165], v[62:65]
	v_mfma_f32_16x16x32_bf16 v[58:61], v[130:133], v[162:165], v[58:61]
	v_mfma_f32_16x16x32_bf16 v[46:49], v[114:117], v[170:173], v[46:49]
	v_mfma_f32_16x16x32_bf16 v[42:45], v[130:133], v[170:173], v[42:45]
	v_mfma_f32_16x16x32_bf16 v[30:33], v[114:117], v[178:181], v[30:33]
	v_mfma_f32_16x16x32_bf16 v[26:29], v[130:133], v[178:181], v[26:29]
	v_mfma_f32_16x16x32_bf16 v[14:17], v[114:117], v[186:189], v[14:17]
	v_mfma_f32_16x16x32_bf16 v[10:13], v[130:133], v[186:189], v[10:13]
	v_mfma_f32_16x16x32_bf16 v[62:65], v[118:121], v[166:169], v[62:65]
	v_mfma_f32_16x16x32_bf16 v[58:61], v[134:137], v[166:169], v[58:61]
	v_mfma_f32_16x16x32_bf16 v[46:49], v[118:121], v[174:177], v[46:49]
	v_mfma_f32_16x16x32_bf16 v[42:45], v[134:137], v[174:177], v[42:45]
	v_mfma_f32_16x16x32_bf16 v[30:33], v[118:121], v[182:185], v[30:33]
	v_mfma_f32_16x16x32_bf16 v[26:29], v[134:137], v[182:185], v[26:29]
	v_mfma_f32_16x16x32_bf16 v[14:17], v[118:121], v[190:193], v[14:17]
	v_mfma_f32_16x16x32_bf16 v[10:13], v[134:137], v[190:193], v[10:13]
	v_mfma_f32_16x16x32_bf16 v[54:57], v[138:141], v[162:165], v[54:57]
	v_mfma_f32_16x16x32_bf16 v[50:53], v[146:149], v[162:165], v[50:53]
	v_mfma_f32_16x16x32_bf16 v[38:41], v[138:141], v[170:173], v[38:41]
	v_mfma_f32_16x16x32_bf16 v[34:37], v[146:149], v[170:173], v[34:37]
	v_mfma_f32_16x16x32_bf16 v[22:25], v[138:141], v[178:181], v[22:25]
	v_mfma_f32_16x16x32_bf16 v[18:21], v[146:149], v[178:181], v[18:21]
	v_mfma_f32_16x16x32_bf16 v[6:9], v[138:141], v[186:189], v[6:9]
	v_mfma_f32_16x16x32_bf16 v[2:5], v[146:149], v[186:189], v[2:5]
	v_mfma_f32_16x16x32_bf16 v[54:57], v[142:145], v[166:169], v[54:57]
	v_mfma_f32_16x16x32_bf16 v[50:53], v[158:161], v[166:169], v[50:53]
	v_mfma_f32_16x16x32_bf16 v[38:41], v[142:145], v[174:177], v[38:41]
	v_mfma_f32_16x16x32_bf16 v[34:37], v[158:161], v[174:177], v[34:37]
	v_mfma_f32_16x16x32_bf16 v[22:25], v[142:145], v[182:185], v[22:25]
	v_mfma_f32_16x16x32_bf16 v[18:21], v[158:161], v[182:185], v[18:21]
	v_mfma_f32_16x16x32_bf16 v[6:9], v[142:145], v[190:193], v[6:9]
	v_mfma_f32_16x16x32_bf16 v[2:5], v[158:161], v[190:193], v[2:5]
	s_setprio 0
	s_barrier
	s_add_i32 s55, s55, 2
	s_add_u32 s53, s53, 0x100
	s_addc_u32 s54, s54, 0
	s_cmp_gt_u32 s55, 41
	s_mov_b64 s[30:31], s[34:35]
	s_cbranch_scc0 .LBB0_1928
	s_and_b64 vcc, exec, s[26:27]
	s_cbranch_vccz .LBB0_1931
	s_barrier

; #define PG8_STAGE(bufoff, gbase, voff) do { _Pragma("unroll") for (int _i = 0; _i < 2; ++_i) \
;         __builtin_amdgcn_global_load_lds((const unsigned*)((const char*)(gbase) + (voff)[_i]), (PG8_LAS unsigned*)(lds + (bufoff) + ldsw + _i * 8192), 16, 0, 0); } while (0)
; #define PG8_LDA(dst, b, h) do { _Pragma("unroll") for (int m = 0; m < 4; ++m) _Pragma("unroll") for (int k = 0; k < 2; ++k) dst[m][k] = *(const PG8_LAS bf16x8*)(lds + PG8_SA(b, h) + aoff + m * 2048 + k * 1024); } while (0)
; #define PG8_LDB(dst, b, h) do { _Pragma("unroll") for (int n = 0; n < 2; ++n) _Pragma("unroll") for (int k = 0; k < 2; ++k) dst[n][k] = *(const PG8_LAS bf16x8*)(lds + PG8_SB(b, h) + boff + n * 2048 + k * 1024); } while (0)
; #define PG8_MMA(ai, bj, At, Bt) do { __builtin_amdgcn_s_setprio(1); _Pragma("unroll") for (int m = 0; m < 4; ++m) _Pragma("unroll") for (int n = 0; n < 2; ++n) _Pragma("unroll") for (int k = 0; k < 2; ++k) \
;         acc[ai][bj][m][n] = __builtin_amdgcn_mfma_f32_16x16x32_bf16(Bt[n][k], At[m][k], acc[ai][bj][m][n], 0, 0, 0); __builtin_amdgcn_s_setprio(0); } while (0)
; #define PG8_WAIT_V(n) asm volatile("s_waitcnt vmcnt(" #n ")" ::: "memory")
; #define PG8_BAR __builtin_amdgcn_s_barrier()
; template <class Epi, class Sched, bool ALIGN_EPI = false, bool SP2 = false, bool HALFM = false>
; __device__ __forceinline__ void gemm_phase(PG8_LAS unsigned char* lds, const Gemm g, const Sched& S, const Epi& E) {
;     ...
;             const bool last = (t == nt - 2);
;             const char* a1 = cA + (size_t)(t + 1) * kstep;
;             const char* a2 = last ? nA : cA + (size_t)(t + 2) * kstep; const char* b2 = last ? nB : cB + (size_t)(t + 2) * kstep;
;             const char* a3 = a2 + kstep; const char* b3 = b2 + kstep;
;             if (last && has_next) S.a_ready(nxt);
;             if constexpr (SP2) {
;             PG8_LDB(B0, 0, 0); PG8_LDB(B1, 0, 1); PG8_SCHED; PG8_LDA(At, 0, 0); PG8_STAGE(PG8_SA(1, 1), a1 + hstep, voffA);
;             PG8_WAIT_V(8); PG8_WAIT_L(0); PG8_BAR; PG8_MMA(0, 0, At, B0); PG8_MMA(0, 1, At, B1); PG8_BAR; PG8_SCHED;
;             PG8_LDA(At, 0, 1); PG8_STAGE(PG8_SB(0, 0), b2, voffB); PG8_STAGE(PG8_SB(0, 1), b2 + hstep, voffB); PG8_STAGE(PG8_SA(0, 0), a2, voffA);
;             PG8_WAIT_V(8); PG8_WAIT_L(0); PG8_BAR; if constexpr (!HALFM) { PG8_MMA(1, 0, At, B0); PG8_MMA(1, 1, At, B1); } PG8_BAR; PG8_SCHED;
.LBB0_2049:
	ds_read_b128 v[126:129], v212
	ds_read_b128 v[130:133], v212 offset:1024
	ds_read_b128 v[138:141], v212 offset:2048
	ds_read_b128 v[142:145], v212 offset:3072
	ds_read_b128 v[146:149], v213
	ds_read_b128 v[150:153], v213 offset:1024
	ds_read_b128 v[154:157], v213 offset:2048
	ds_read_b128 v[158:161], v213 offset:3072
	s_add_u32 s38, s36, 0xfffc0080
	s_addc_u32 s39, s37, -1
	s_cmp_eq_u32 s56, 12
	s_cselect_b32 s41, s27, s39
	s_cselect_b32 s40, s52, s38
	s_cselect_b32 s39, s25, s55
	s_cselect_b32 s38, s53, s54
	v_lshl_add_u64 v[216:217], s[36:37], 0, v[186:187]
	s_add_i32 m0, s1, 0xc000
	ds_read_b128 v[162:165], v214
	ds_read_b128 v[166:169], v214 offset:1024
	ds_read_b128 v[170:173], v214 offset:2048
	ds_read_b128 v[174:177], v214 offset:3072
	ds_read_b128 v[194:197], v214 offset:4096
	ds_read_b128 v[198:201], v214 offset:5120
	ds_read_b128 v[202:205], v214 offset:6144
	ds_read_b128 v[206:209], v214 offset:7168
	global_load_lds_dwordx4 v[216:217], off
	v_lshl_add_u64 v[216:217], s[36:37], 0, v[188:189]
	s_add_i32 m0, s1, 0xe000
	s_nop 0
	global_load_lds_dwordx4 v[216:217], off
	s_mov_b32 m0, s43
	v_lshl_add_u64 v[216:217], v[220:221], 0, s[10:11]
	global_load_lds_dwordx4 v[216:217], off
	s_mov_b32 m0, s46
	v_lshl_add_u64 v[216:217], v[222:223], 0, s[10:11]
	global_load_lds_dwordx4 v[216:217], off
	s_waitcnt vmcnt(10)
	s_waitcnt lgkmcnt(0)
	s_barrier
	s_setprio 1
	s_waitcnt lgkmcnt(0)
	v_mfma_f32_16x16x32_bf16 v[134:137], v[126:129], v[162:165], v[134:137]
	v_mfma_f32_16x16x32_bf16 v[122:125], v[138:141], v[162:165], v[122:125]
	v_mfma_f32_16x16x32_bf16 v[110:113], v[126:129], v[170:173], v[110:113]
	v_mfma_f32_16x16x32_bf16 v[106:109], v[138:141], v[170:173], v[106:109]
	v_mfma_f32_16x16x32_bf16 v[94:97], v[126:129], v[194:197], v[94:97]
	v_mfma_f32_16x16x32_bf16 v[90:93], v[138:141], v[194:197], v[90:93]
	v_mfma_f32_16x16x32_bf16 v[78:81], v[126:129], v[202:205], v[78:81]
	v_mfma_f32_16x16x32_bf16 v[74:77], v[138:141], v[202:205], v[74:77]
	v_mfma_f32_16x16x32_bf16 v[134:137], v[130:133], v[166:169], v[134:137]
	v_mfma_f32_16x16x32_bf16 v[122:125], v[142:145], v[166:169], v[122:125]
	v_mfma_f32_16x16x32_bf16 v[110:113], v[130:133], v[174:177], v[110:113]
	v_mfma_f32_16x16x32_bf16 v[106:109], v[142:145], v[174:177], v[106:109]
	v_mfma_f32_16x16x32_bf16 v[94:97], v[130:133], v[198:201], v[94:97]
	v_mfma_f32_16x16x32_bf16 v[90:93], v[142:145], v[198:201], v[90:93]
	v_mfma_f32_16x16x32_bf16 v[78:81], v[130:133], v[206:209], v[78:81]
	v_mfma_f32_16x16x32_bf16 v[74:77], v[142:145], v[206:209], v[74:77]
	v_mfma_f32_16x16x32_bf16 v[118:121], v[146:149], v[162:165], v[118:121]
	v_mfma_f32_16x16x32_bf16 v[114:117], v[154:157], v[162:165], v[114:117]
	v_mfma_f32_16x16x32_bf16 v[102:105], v[146:149], v[170:173], v[102:105]
	v_mfma_f32_16x16x32_bf16 v[98:101], v[154:157], v[170:173], v[98:101]
	v_mfma_f32_16x16x32_bf16 v[86:89], v[146:149], v[194:197], v[86:89]
	v_mfma_f32_16x16x32_bf16 v[82:85], v[154:157], v[194:197], v[82:85]
	v_mfma_f32_16x16x32_bf16 v[70:73], v[146:149], v[202:205], v[70:73]
	v_mfma_f32_16x16x32_bf16 v[66:69], v[154:157], v[202:205], v[66:69]
	v_mfma_f32_16x16x32_bf16 v[118:121], v[150:153], v[166:169], v[118:121]
	v_mfma_f32_16x16x32_bf16 v[114:117], v[158:161], v[166:169], v[114:117]
	v_mfma_f32_16x16x32_bf16 v[102:105], v[150:153], v[174:177], v[102:105]
	v_mfma_f32_16x16x32_bf16 v[98:101], v[158:161], v[174:177], v[98:101]
	v_mfma_f32_16x16x32_bf16 v[86:89], v[150:153], v[198:201], v[86:89]
	v_mfma_f32_16x16x32_bf16 v[82:85], v[158:161], v[198:201], v[82:85]
	v_mfma_f32_16x16x32_bf16 v[70:73], v[150:153], v[206:209], v[70:73]
	v_mfma_f32_16x16x32_bf16 v[66:69], v[158:161], v[206:209], v[66:69]
	s_setprio 0
	s_barrier
	s_add_i32 s57, s48, s0
	v_lshl_add_u64 v[216:217], s[38:39], 0, v[180:181]
	s_mov_b32 m0, s57
	ds_read_b128 v[162:165], v214 offset:16384
	ds_read_b128 v[166:169], v214 offset:17408
	ds_read_b128 v[170:173], v214 offset:18432
	ds_read_b128 v[174:177], v214 offset:19456
	ds_read_b128 v[194:197], v214 offset:20480
	ds_read_b128 v[198:201], v214 offset:21504
	ds_read_b128 v[202:205], v214 offset:22528
	ds_read_b128 v[206:209], v214 offset:23552
	global_load_lds_dwordx4 v[216:217], off
	s_add_i32 m0, s57, 0x2000
	s_add_u32 s58, s38, 0x40000
	v_lshl_add_u64 v[218:219], s[38:39], 0, v[184:185]
	s_addc_u32 s59, s39, 0
	s_add_i32 s57, s49, s0
	global_load_lds_dwordx4 v[218:219], off
	v_lshl_add_u64 v[220:221], s[58:59], 0, v[180:181]
	s_mov_b32 m0, s57
	v_lshl_add_u64 v[222:223], s[40:41], 0, v[182:183]
	global_load_lds_dwordx4 v[220:221], off
	v_lshl_add_u64 v[220:221], s[58:59], 0, v[184:185]
	s_add_i32 m0, s57, 0x2000
	s_nop 0
	global_load_lds_dwordx4 v[220:221], off
	v_lshl_add_u64 v[220:221], s[40:41], 0, v[178:179]
	s_waitcnt vmcnt(4)
	s_waitcnt lgkmcnt(0)
	s_barrier
; #define PG8_STAGE(bufoff, gbase, voff) do { _Pragma("unroll") for (int _i = 0; _i < 2; ++_i) \
;         __builtin_amdgcn_global_load_lds((const unsigned*)((const char*)(gbase) + (voff)[_i]), (PG8_LAS unsigned*)(lds + (bufoff) + ldsw + _i * 8192), 16, 0, 0); } while (0)
; #define PG8_LDA(dst, b, h) do { _Pragma("unroll") for (int m = 0; m < 4; ++m) _Pragma("unroll") for (int k = 0; k < 2; ++k) dst[m][k] = *(const PG8_LAS bf16x8*)(lds + PG8_SA(b, h) + aoff + m * 2048 + k * 1024); } while (0)
; #define PG8_LDB(dst, b, h) do { _Pragma("unroll") for (int n = 0; n < 2; ++n) _Pragma("unroll") for (int k = 0; k < 2; ++k) dst[n][k] = *(const PG8_LAS bf16x8*)(lds + PG8_SB(b, h) + boff + n * 2048 + k * 1024); } while (0)
; #define PG8_MMA(ai, bj, At, Bt) do { __builtin_amdgcn_s_setprio(1); _Pragma("unroll") for (int m = 0; m < 4; ++m) _Pragma("unroll") for (int n = 0; n < 2; ++n) _Pragma("unroll") for (int k = 0; k < 2; ++k) \
;         acc[ai][bj][m][n] = __builtin_amdgcn_mfma_f32_16x16x32_bf16(Bt[n][k], At[m][k], acc[ai][bj][m][n], 0, 0, 0); __builtin_amdgcn_s_setprio(0); } while (0)
; #define PG8_WAIT_V(n) asm volatile("s_waitcnt vmcnt(" #n ")" ::: "memory")
; #define PG8_WAIT_L(n) asm volatile("s_waitcnt lgkmcnt(" #n ")" ::: "memory")
; #define PG8_BAR __builtin_amdgcn_s_barrier()
; #define PG8_SCHED __builtin_amdgcn_sched_barrier(0)
; template <class Epi, class Sched, bool ALIGN_EPI = false, bool SP2 = false, bool HALFM = false>
; __device__ __forceinline__ void gemm_phase(PG8_LAS unsigned char* lds, const Gemm g, const Sched& S, const Epi& E) {
;     ...
;             PG8_WAIT_V(8); PG8_WAIT_L(0); PG8_BAR; if constexpr (!HALFM) { PG8_MMA(1, 0, At, B0); PG8_MMA(1, 1, At, B1); } PG8_BAR; PG8_SCHED;
;             PG8_LDB(B0, 1, 0); PG8_LDB(B1, 1, 1); PG8_SCHED; PG8_LDA(At, 1, 0); PG8_STAGE(PG8_SA(0, 1), a2 + hstep, voffA);
;             PG8_WAIT_V(8); PG8_WAIT_L(0); PG8_BAR; PG8_MMA(0, 0, At, B0); PG8_MMA(0, 1, At, B1); PG8_BAR; PG8_SCHED;
	s_setprio 1
	s_waitcnt lgkmcnt(0)
	v_mfma_f32_16x16x32_bf16 v[62:65], v[126:129], v[162:165], v[62:65]
	v_mfma_f32_16x16x32_bf16 v[58:61], v[138:141], v[162:165], v[58:61]
	v_mfma_f32_16x16x32_bf16 v[46:49], v[126:129], v[170:173], v[46:49]
	v_mfma_f32_16x16x32_bf16 v[42:45], v[138:141], v[170:173], v[42:45]
	v_mfma_f32_16x16x32_bf16 v[30:33], v[126:129], v[194:197], v[30:33]
	v_mfma_f32_16x16x32_bf16 v[26:29], v[138:141], v[194:197], v[26:29]
	v_mfma_f32_16x16x32_bf16 v[14:17], v[126:129], v[202:205], v[14:17]
	v_mfma_f32_16x16x32_bf16 v[10:13], v[138:141], v[202:205], v[10:13]
	v_mfma_f32_16x16x32_bf16 v[62:65], v[130:133], v[166:169], v[62:65]
	v_mfma_f32_16x16x32_bf16 v[58:61], v[142:145], v[166:169], v[58:61]
	v_mfma_f32_16x16x32_bf16 v[46:49], v[130:133], v[174:177], v[46:49]
	v_mfma_f32_16x16x32_bf16 v[42:45], v[142:145], v[174:177], v[42:45]
	v_mfma_f32_16x16x32_bf16 v[30:33], v[130:133], v[198:201], v[30:33]
	v_mfma_f32_16x16x32_bf16 v[26:29], v[142:145], v[198:201], v[26:29]
	v_mfma_f32_16x16x32_bf16 v[14:17], v[130:133], v[206:209], v[14:17]
	v_mfma_f32_16x16x32_bf16 v[10:13], v[142:145], v[206:209], v[10:13]
	v_mfma_f32_16x16x32_bf16 v[54:57], v[146:149], v[162:165], v[54:57]
	v_mfma_f32_16x16x32_bf16 v[50:53], v[154:157], v[162:165], v[50:53]
	v_mfma_f32_16x16x32_bf16 v[38:41], v[146:149], v[170:173], v[38:41]
	v_mfma_f32_16x16x32_bf16 v[34:37], v[154:157], v[170:173], v[34:37]
	v_mfma_f32_16x16x32_bf16 v[22:25], v[146:149], v[194:197], v[22:25]
	v_mfma_f32_16x16x32_bf16 v[18:21], v[154:157], v[194:197], v[18:21]
	v_mfma_f32_16x16x32_bf16 v[6:9], v[146:149], v[202:205], v[6:9]
	v_mfma_f32_16x16x32_bf16 v[2:5], v[154:157], v[202:205], v[2:5]
	v_mfma_f32_16x16x32_bf16 v[54:57], v[150:153], v[166:169], v[54:57]
	v_mfma_f32_16x16x32_bf16 v[50:53], v[158:161], v[166:169], v[50:53]
	v_mfma_f32_16x16x32_bf16 v[38:41], v[150:153], v[174:177], v[38:41]
	v_mfma_f32_16x16x32_bf16 v[34:37], v[158:161], v[174:177], v[34:37]
	v_mfma_f32_16x16x32_bf16 v[22:25], v[150:153], v[198:201], v[22:25]
	v_mfma_f32_16x16x32_bf16 v[18:21], v[158:161], v[198:201], v[18:21]
	v_mfma_f32_16x16x32_bf16 v[6:9], v[150:153], v[206:209], v[6:9]
	v_mfma_f32_16x16x32_bf16 v[2:5], v[158:161], v[206:209], v[2:5]
	s_setprio 0
	s_barrier
	s_add_i32 s57, 0, 0x18000
	s_add_i32 s58, 0, 0x1c000
	v_add_u32_e32 v142, s57, v210
	v_add_u32_e32 v158, s58, v210
	ds_read_b128 v[126:129], v142
	ds_read_b128 v[130:133], v142 offset:1024
	ds_read_b128 v[138:141], v142 offset:2048
	ds_read_b128 v[142:145], v142 offset:3072
	ds_read_b128 v[146:149], v158
	ds_read_b128 v[150:153], v158 offset:1024
	ds_read_b128 v[154:157], v158 offset:2048
	ds_read_b128 v[158:161], v158 offset:3072
	s_add_u32 s40, s40, 0x40000
	s_addc_u32 s41, s41, 0
	s_mov_b32 m0, s3
	v_lshl_add_u64 v[224:225], s[40:41], 0, v[178:179]
	ds_read_b128 v[162:165], v214 offset:32768
	ds_read_b128 v[166:169], v214 offset:33792
	ds_read_b128 v[170:173], v214 offset:34816
	ds_read_b128 v[174:177], v214 offset:35840
	ds_read_b128 v[194:197], v214 offset:36864
	ds_read_b128 v[198:201], v214 offset:37888
	ds_read_b128 v[202:205], v214 offset:38912
	ds_read_b128 v[206:209], v214 offset:39936
	global_load_lds_dwordx4 v[224:225], off
	v_lshl_add_u64 v[224:225], s[40:41], 0, v[182:183]
	s_mov_b32 m0, s35
	s_nop 0
	global_load_lds_dwordx4 v[224:225], off
	s_mov_b32 m0, s1
	s_nop 0
	global_load_lds_dwordx4 v[220:221], off
	s_mov_b32 m0, s2
	s_nop 0
	global_load_lds_dwordx4 v[222:223], off
	s_waitcnt vmcnt(10)
	s_waitcnt lgkmcnt(0)
	s_barrier
; #define PG8_STAGE(bufoff, gbase, voff) do { _Pragma("unroll") for (int _i = 0; _i < 2; ++_i) \
;         __builtin_amdgcn_global_load_lds((const unsigned*)((const char*)(gbase) + (voff)[_i]), (PG8_LAS unsigned*)(lds + (bufoff) + ldsw + _i * 8192), 16, 0, 0); } while (0)
; #define PG8_LDA(dst, b, h) do { _Pragma("unroll") for (int m = 0; m < 4; ++m) _Pragma("unroll") for (int k = 0; k < 2; ++k) dst[m][k] = *(const PG8_LAS bf16x8*)(lds + PG8_SA(b, h) + aoff + m * 2048 + k * 1024); } while (0)
; #define PG8_MMA(ai, bj, At, Bt) do { __builtin_amdgcn_s_setprio(1); _Pragma("unroll") for (int m = 0; m < 4; ++m) _Pragma("unroll") for (int n = 0; n < 2; ++n) _Pragma("unroll") for (int k = 0; k < 2; ++k) \
;         acc[ai][bj][m][n] = __builtin_amdgcn_mfma_f32_16x16x32_bf16(Bt[n][k], At[m][k], acc[ai][bj][m][n], 0, 0, 0); __builtin_amdgcn_s_setprio(0); } while (0)
; #define PG8_WAIT_V(n) asm volatile("s_waitcnt vmcnt(" #n ")" ::: "memory")
; #define PG8_WAIT_L(n) asm volatile("s_waitcnt lgkmcnt(" #n ")" ::: "memory")
; #define PG8_BAR __builtin_amdgcn_s_barrier()
; #define PG8_SCHED __builtin_amdgcn_sched_barrier(0)
; template <class Epi, class Sched, bool ALIGN_EPI = false, bool SP2 = false, bool HALFM = false>
; __device__ __forceinline__ void gemm_phase(PG8_LAS unsigned char* lds, const Gemm g, const Sched& S, const Epi& E) {
;     ...
;             PG8_WAIT_V(8); PG8_WAIT_L(0); PG8_BAR; PG8_MMA(0, 0, At, B0); PG8_MMA(0, 1, At, B1); PG8_BAR; PG8_SCHED;
;             PG8_LDA(At, 1, 1); PG8_STAGE(PG8_SB(1, 0), b3, voffB); PG8_STAGE(PG8_SB(1, 1), b3 + hstep, voffB); PG8_STAGE(PG8_SA(1, 0), a3, voffA);
;             PG8_WAIT_V(8); PG8_WAIT_L(0); PG8_BAR; if constexpr (!HALFM) { PG8_MMA(1, 0, At, B0); PG8_MMA(1, 1, At, B1); } PG8_BAR; PG8_SCHED;
	s_setprio 1
	s_waitcnt lgkmcnt(0)
	v_mfma_f32_16x16x32_bf16 v[134:137], v[126:129], v[162:165], v[134:137]
	v_mfma_f32_16x16x32_bf16 v[122:125], v[138:141], v[162:165], v[122:125]
	v_mfma_f32_16x16x32_bf16 v[110:113], v[126:129], v[170:173], v[110:113]
	v_mfma_f32_16x16x32_bf16 v[106:109], v[138:141], v[170:173], v[106:109]
	v_mfma_f32_16x16x32_bf16 v[94:97], v[126:129], v[194:197], v[94:97]
	v_mfma_f32_16x16x32_bf16 v[90:93], v[138:141], v[194:197], v[90:93]
	v_mfma_f32_16x16x32_bf16 v[78:81], v[126:129], v[202:205], v[78:81]
	v_mfma_f32_16x16x32_bf16 v[74:77], v[138:141], v[202:205], v[74:77]
	v_mfma_f32_16x16x32_bf16 v[134:137], v[130:133], v[166:169], v[134:137]
	v_mfma_f32_16x16x32_bf16 v[122:125], v[142:145], v[166:169], v[122:125]
	v_mfma_f32_16x16x32_bf16 v[110:113], v[130:133], v[174:177], v[110:113]
	v_mfma_f32_16x16x32_bf16 v[106:109], v[142:145], v[174:177], v[106:109]
	v_mfma_f32_16x16x32_bf16 v[94:97], v[130:133], v[198:201], v[94:97]
	v_mfma_f32_16x16x32_bf16 v[90:93], v[142:145], v[198:201], v[90:93]
	v_mfma_f32_16x16x32_bf16 v[78:81], v[130:133], v[206:209], v[78:81]
	v_mfma_f32_16x16x32_bf16 v[74:77], v[142:145], v[206:209], v[74:77]
	v_mfma_f32_16x16x32_bf16 v[118:121], v[146:149], v[162:165], v[118:121]
	v_mfma_f32_16x16x32_bf16 v[114:117], v[154:157], v[162:165], v[114:117]
	v_mfma_f32_16x16x32_bf16 v[102:105], v[146:149], v[170:173], v[102:105]
	v_mfma_f32_16x16x32_bf16 v[98:101], v[154:157], v[170:173], v[98:101]
	v_mfma_f32_16x16x32_bf16 v[86:89], v[146:149], v[194:197], v[86:89]
	v_mfma_f32_16x16x32_bf16 v[82:85], v[154:157], v[194:197], v[82:85]
	v_mfma_f32_16x16x32_bf16 v[70:73], v[146:149], v[202:205], v[70:73]
	v_mfma_f32_16x16x32_bf16 v[66:69], v[154:157], v[202:205], v[66:69]
	v_mfma_f32_16x16x32_bf16 v[118:121], v[150:153], v[166:169], v[118:121]
	v_mfma_f32_16x16x32_bf16 v[114:117], v[158:161], v[166:169], v[114:117]
	v_mfma_f32_16x16x32_bf16 v[102:105], v[150:153], v[174:177], v[102:105]
	v_mfma_f32_16x16x32_bf16 v[98:101], v[158:161], v[174:177], v[98:101]
	v_mfma_f32_16x16x32_bf16 v[86:89], v[150:153], v[198:201], v[86:89]
	v_mfma_f32_16x16x32_bf16 v[82:85], v[158:161], v[198:201], v[82:85]
	v_mfma_f32_16x16x32_bf16 v[70:73], v[150:153], v[206:209], v[70:73]
	v_mfma_f32_16x16x32_bf16 v[66:69], v[158:161], v[206:209], v[66:69]
	s_setprio 0
	s_barrier
	s_add_i32 s40, s57, s0
	v_lshl_add_u64 v[216:217], v[216:217], 0, s[10:11]
	s_mov_b32 m0, s40
	ds_read_b128 v[162:165], v214 offset:49152
	ds_read_b128 v[166:169], v214 offset:50176
	ds_read_b128 v[170:173], v214 offset:51200
	ds_read_b128 v[174:177], v214 offset:52224
	ds_read_b128 v[194:197], v214 offset:53248
	ds_read_b128 v[198:201], v214 offset:54272
	ds_read_b128 v[202:205], v214 offset:55296
	ds_read_b128 v[206:209], v214 offset:56320
	global_load_lds_dwordx4 v[216:217], off
	s_add_i32 m0, s40, 0x2000
	s_add_u32 s38, s38, 0x40080
	v_lshl_add_u64 v[216:217], v[218:219], 0, s[10:11]
	s_addc_u32 s39, s39, 0
	s_add_i32 s40, s58, s0
	global_load_lds_dwordx4 v[216:217], off
	v_lshl_add_u64 v[216:217], s[38:39], 0, v[180:181]
	s_mov_b32 m0, s40
	s_nop 0
	global_load_lds_dwordx4 v[216:217], off
	v_lshl_add_u64 v[216:217], s[38:39], 0, v[184:185]
	s_add_i32 m0, s40, 0x2000
	s_nop 0
	global_load_lds_dwordx4 v[216:217], off
	s_waitcnt vmcnt(4)
	s_waitcnt lgkmcnt(0)
	s_barrier
	s_setprio 1
	s_waitcnt lgkmcnt(0)
	v_mfma_f32_16x16x32_bf16 v[62:65], v[126:129], v[162:165], v[62:65]
	v_mfma_f32_16x16x32_bf16 v[58:61], v[138:141], v[162:165], v[58:61]
	v_mfma_f32_16x16x32_bf16 v[46:49], v[126:129], v[170:173], v[46:49]
	v_mfma_f32_16x16x32_bf16 v[42:45], v[138:141], v[170:173], v[42:45]
	v_mfma_f32_16x16x32_bf16 v[30:33], v[126:129], v[194:197], v[30:33]
	v_mfma_f32_16x16x32_bf16 v[26:29], v[138:141], v[194:197], v[26:29]
	v_mfma_f32_16x16x32_bf16 v[14:17], v[126:129], v[202:205], v[14:17]
	v_mfma_f32_16x16x32_bf16 v[10:13], v[138:141], v[202:205], v[10:13]
	v_mfma_f32_16x16x32_bf16 v[62:65], v[130:133], v[166:169], v[62:65]
	v_mfma_f32_16x16x32_bf16 v[58:61], v[142:145], v[166:169], v[58:61]
	v_mfma_f32_16x16x32_bf16 v[46:49], v[130:133], v[174:177], v[46:49]
	v_mfma_f32_16x16x32_bf16 v[42:45], v[142:145], v[174:177], v[42:45]
	v_mfma_f32_16x16x32_bf16 v[30:33], v[130:133], v[198:201], v[30:33]
	v_mfma_f32_16x16x32_bf16 v[26:29], v[142:145], v[198:201], v[26:29]
	v_mfma_f32_16x16x32_bf16 v[14:17], v[130:133], v[206:209], v[14:17]
	v_mfma_f32_16x16x32_bf16 v[10:13], v[142:145], v[206:209], v[10:13]
	v_mfma_f32_16x16x32_bf16 v[54:57], v[146:149], v[162:165], v[54:57]
	v_mfma_f32_16x16x32_bf16 v[50:53], v[154:157], v[162:165], v[50:53]
	v_mfma_f32_16x16x32_bf16 v[38:41], v[146:149], v[170:173], v[38:41]
	v_mfma_f32_16x16x32_bf16 v[34:37], v[154:157], v[170:173], v[34:37]
	v_mfma_f32_16x16x32_bf16 v[22:25], v[146:149], v[194:197], v[22:25]
	v_mfma_f32_16x16x32_bf16 v[18:21], v[154:157], v[194:197], v[18:21]
	v_mfma_f32_16x16x32_bf16 v[6:9], v[146:149], v[202:205], v[6:9]
	v_mfma_f32_16x16x32_bf16 v[2:5], v[154:157], v[202:205], v[2:5]
	v_mfma_f32_16x16x32_bf16 v[54:57], v[150:153], v[166:169], v[54:57]
	v_mfma_f32_16x16x32_bf16 v[50:53], v[158:161], v[166:169], v[50:53]
	v_mfma_f32_16x16x32_bf16 v[38:41], v[150:153], v[174:177], v[38:41]
	v_mfma_f32_16x16x32_bf16 v[34:37], v[158:161], v[174:177], v[34:37]
	v_mfma_f32_16x16x32_bf16 v[22:25], v[150:153], v[198:201], v[22:25]
	v_mfma_f32_16x16x32_bf16 v[18:21], v[158:161], v[198:201], v[18:21]
	v_mfma_f32_16x16x32_bf16 v[6:9], v[150:153], v[206:209], v[6:9]
	v_mfma_f32_16x16x32_bf16 v[2:5], v[158:161], v[206:209], v[2:5]
	s_setprio 0
	s_barrier
	s_add_i32 s56, s56, 2
	s_add_u32 s36, s36, 0x100
	s_addc_u32 s37, s37, 0
	s_add_u32 s54, s54, 0x100
	s_addc_u32 s55, s55, 0
	s_cmp_gt_u32 s56, 13
	s_cbranch_scc0 .LBB0_2049
	s_and_b64 vcc, exec, s[12:13]
	s_cbranch_vccz .LBB0_2052
	s_barrier
